# hand-written EpiGate epilogue (packed math, xc loads up front, whole-unit test for the general expm1 path)
# speedup vs baseline: 1.0030x; 1.0030x over previous
; #define PG8_STAGE(bufoff, gbase, voff) do { _Pragma("unroll") for (int _i = 0; _i < 2; ++_i) \
;         __builtin_amdgcn_global_load_lds((const __attribute__((address_space(1))) unsigned*)((const char*)(gbase) + (voff)[_i]), (LAS unsigned*)(lds + (bufoff) + ldsw + _i * 8192), 16, 0, 0); } while (0)
; #define PG8_LDA(dst, b, h) do { _Pragma("unroll") for (int m = 0; m < 4; ++m) _Pragma("unroll") for (int k = 0; k < 2; ++k) dst[m][k] = *(const LAS bf16x8*)(lds + PG8_SA(b, h) + aoff + m * 2048 + k * 1024); } while (0)
; #define PG8_LDB(dst, b, h) do { _Pragma("unroll") for (int n = 0; n < 2; ++n) _Pragma("unroll") for (int k = 0; k < 2; ++k) dst[n][k] = *(const LAS bf16x8*)(lds + PG8_SB(b, h) + boff + n * 2048 + k * 1024); } while (0)
; #define PG8_MMA(ai, bj, At, Bt) do { __builtin_amdgcn_s_setprio(1); _Pragma("unroll") for (int m = 0; m < 4; ++m) _Pragma("unroll") for (int n = 0; n < 2; ++n) _Pragma("unroll") for (int k = 0; k < 2; ++k) \
;         acc[ai][bj][m][n] = __builtin_amdgcn_mfma_f32_16x16x32_bf16(Bt[n][k], At[m][k], acc[ai][bj][m][n], 0, 0, 0); __builtin_amdgcn_s_setprio(0); } while (0)
; #define PG8_WAIT_L(n) asm volatile("s_waitcnt lgkmcnt(" #n ")" ::: "memory")
; template <class Epi>
; __device__ __forceinline__ void gemm_phase(LAS unsigned char* lds, const Gemm g, const StaticOrder& S_in, const Epi& E, int sw) {
;     ...
;         const bool has_next = S.next(ui + 1, nxt);
;         const char* nA = has_next ? PG8_ABASE(nxt) : cA; const char* nB = has_next ? PG8_BBASE(nxt) : cB;
;         for (int t = 0; t < nt; t += 2) {
;             const bool last = (t == nt - 2);
;             const char* a1 = cA + (size_t)(t + 1) * kstep;
;             const char* a2 = last ? nA : cA + (size_t)(t + 2) * kstep; const char* b2 = last ? nB : cB + (size_t)(t + 2) * kstep;
;             const char* a3 = a2 + kstep; const char* b3 = b2 + kstep;
;             PG8_LDB(B0, 0, 0); PG8_SCHED; PG8_LDA(At, 0, 0); PG8_STAGE(PG8_SA(1, 1), a1 + hstepA, voffA);
;             PG8_WAIT_L(8); PG8_BAR; PG8_WAIT_L(0); PG8_MMA(0, 0, At, B0); PG8_BAR; PG8_SCHED;
;             PG8_LDB(B1, 0, 1); PG8_STAGE(PG8_SB(0, 0), b2, voffB);
;             PG8_BAR; PG8_WAIT_L(0); PG8_MMA(0, 1, At, B1); PG8_BAR;
;             PG8_LDA(At, 0, 1); PG8_STAGE(PG8_SA(0, 0), a2, voffA);
;             PG8_BAR; PG8_WAIT_L(0); PG8_MMA(1, 0, At, B0); PG8_BAR; PG8_SCHED;
.Lgate_ord_keep:
.LBB0_428:
	s_ashr_i32 s18, s12, 1
	s_ashr_i32 s17, s16, 31
	s_ashr_i32 s19, s18, 31
	s_lshl_b64 s[18:19], s[18:19], 9
	s_lshl_b64 s[20:21], s[16:17], 20
	s_add_u32 s13, s39, s20
	s_addc_u32 s17, s40, s21
	s_add_u32 s18, s13, s18
	s_addc_u32 s19, s17, s19
	s_and_b64 s[20:21], s[4:5], exec
	s_cselect_b32 s35, s19, s27
	s_cselect_b32 s34, s18, s26
	s_ashr_i32 s13, s12, 31
	s_lshl_b64 s[20:21], s[12:13], 17
	s_add_u32 s20, s41, s20
	s_addc_u32 s21, s42, s21
	s_and_b64 s[30:31], s[4:5], exec
	s_cselect_b32 s31, s21, s29
	s_cselect_b32 s30, s20, s28
	s_add_i32 s17, 0, 0x10000
	v_add_u32_e32 v175, s17, v171
	ds_read_b128 v[18:21], v175
	ds_read_b128 v[22:25], v175 offset:1024
	ds_read_b128 v[26:29], v175 offset:2048
	ds_read_b128 v[30:33], v175 offset:3072
	s_add_u32 s48, s26, 0x80080
	s_addc_u32 s49, s27, 0
	s_add_i32 s50, s23, 0xc000
	v_lshl_add_u64 v[66:67], s[48:49], 0, v[130:131]
	s_mov_b32 m0, s50
	s_add_i32 s13, s23, 0xe000
	ds_read_b128 v[34:37], v174
	ds_read_b128 v[38:41], v174 offset:1024
	ds_read_b128 v[42:45], v174 offset:2048
	ds_read_b128 v[46:49], v174 offset:3072
	ds_read_b128 v[50:53], v174 offset:4096
	ds_read_b128 v[54:57], v174 offset:5120
	ds_read_b128 v[58:61], v174 offset:6144
	ds_read_b128 v[62:65], v174 offset:7168
	global_load_lds_dwordx4 v[66:67], off
	v_lshl_add_u64 v[66:67], s[48:49], 0, v[132:133]
	s_mov_b32 m0, s13
	s_nop 0
	global_load_lds_dwordx4 v[66:67], off
	s_waitcnt lgkmcnt(8)
	s_barrier
	s_waitcnt lgkmcnt(0)
	s_setprio 1
	s_waitcnt lgkmcnt(0)
	v_mfma_f32_16x16x32_bf16 v[66:69], v[18:21], v[34:37], v[10:13]
	v_mfma_f32_16x16x32_bf16 v[70:73], v[26:29], v[34:37], v[14:17]
	v_mfma_f32_16x16x32_bf16 v[74:77], v[18:21], v[42:45], v[10:13]
	v_mfma_f32_16x16x32_bf16 v[78:81], v[26:29], v[42:45], v[14:17]
	v_mfma_f32_16x16x32_bf16 v[82:85], v[18:21], v[50:53], v[10:13]
	v_mfma_f32_16x16x32_bf16 v[86:89], v[26:29], v[50:53], v[14:17]
	v_mfma_f32_16x16x32_bf16 v[90:93], v[18:21], v[58:61], v[10:13]
	v_mfma_f32_16x16x32_bf16 v[94:97], v[26:29], v[58:61], v[14:17]
	v_mfma_f32_16x16x32_bf16 v[66:69], v[22:25], v[38:41], v[66:69]
	v_mfma_f32_16x16x32_bf16 v[70:73], v[30:33], v[38:41], v[70:73]
	v_mfma_f32_16x16x32_bf16 v[74:77], v[22:25], v[46:49], v[74:77]
	v_mfma_f32_16x16x32_bf16 v[78:81], v[30:33], v[46:49], v[78:81]
	v_mfma_f32_16x16x32_bf16 v[82:85], v[22:25], v[54:57], v[82:85]
	v_mfma_f32_16x16x32_bf16 v[86:89], v[30:33], v[54:57], v[86:89]
	v_mfma_f32_16x16x32_bf16 v[90:93], v[22:25], v[62:65], v[90:93]
	v_mfma_f32_16x16x32_bf16 v[94:97], v[30:33], v[62:65], v[94:97]
	s_setprio 0
	s_barrier
	s_add_i32 s51, 0, 0x14000
	v_lshl_add_u64 v[168:169], s[28:29], 0, v[0:1]
	s_mov_b64 s[52:53], 0x100
	s_add_i32 s49, s17, s38
	v_add_u32_e32 v212, s51, v171
	v_lshl_add_u64 v[114:115], v[168:169], 0, s[52:53]
	s_mov_b32 m0, s49
	v_lshl_add_u64 v[172:173], s[28:29], 0, v[134:135]
	s_add_i32 s17, s49, 0x2000
	ds_read_b128 v[98:101], v212
	ds_read_b128 v[102:105], v212 offset:1024
	ds_read_b128 v[106:109], v212 offset:2048
	ds_read_b128 v[110:113], v212 offset:3072
	global_load_lds_dwordx4 v[114:115], off
	v_lshl_add_u64 v[114:115], v[172:173], 0, s[52:53]
	s_mov_b32 m0, s17
	s_nop 0
	global_load_lds_dwordx4 v[114:115], off
	s_barrier
	s_waitcnt lgkmcnt(0)
	s_setprio 1
	s_waitcnt lgkmcnt(0)
	v_mfma_f32_16x16x32_bf16 v[114:117], v[98:101], v[34:37], v[2:5]
	v_mfma_f32_16x16x32_bf16 v[34:37], v[106:109], v[34:37], v[6:9]
	v_mfma_f32_16x16x32_bf16 v[114:117], v[102:105], v[38:41], v[114:117]
	v_mfma_f32_16x16x32_bf16 v[34:37], v[110:113], v[38:41], v[34:37]
	v_mfma_f32_16x16x32_bf16 v[38:41], v[98:101], v[42:45], v[2:5]
	v_mfma_f32_16x16x32_bf16 v[42:45], v[106:109], v[42:45], v[6:9]
	v_mfma_f32_16x16x32_bf16 v[38:41], v[102:105], v[46:49], v[38:41]
	v_mfma_f32_16x16x32_bf16 v[42:45], v[110:113], v[46:49], v[42:45]
	v_mfma_f32_16x16x32_bf16 v[46:49], v[98:101], v[50:53], v[2:5]
	v_mfma_f32_16x16x32_bf16 v[50:53], v[106:109], v[50:53], v[6:9]
	v_mfma_f32_16x16x32_bf16 v[46:49], v[102:105], v[54:57], v[46:49]
	v_mfma_f32_16x16x32_bf16 v[50:53], v[110:113], v[54:57], v[50:53]
	v_mfma_f32_16x16x32_bf16 v[54:57], v[98:101], v[58:61], v[2:5]
	v_mfma_f32_16x16x32_bf16 v[58:61], v[106:109], v[58:61], v[6:9]
	v_mfma_f32_16x16x32_bf16 v[54:57], v[102:105], v[62:65], v[54:57]
	v_mfma_f32_16x16x32_bf16 v[58:61], v[110:113], v[62:65], v[58:61]
	s_setprio 0
	v_lshl_add_u64 v[208:209], s[26:27], 0, v[130:131]
	s_mov_b32 m0, s23
	v_lshl_add_u64 v[152:153], v[208:209], 0, s[52:53]
	v_lshl_add_u64 v[210:211], s[26:27], 0, v[132:133]
	s_barrier
	ds_read_b128 v[62:65], v174 offset:16384
	ds_read_b128 v[118:121], v174 offset:17408
	ds_read_b128 v[122:125], v174 offset:18432
	ds_read_b128 v[126:129], v174 offset:19456
	ds_read_b128 v[136:139], v174 offset:20480
	ds_read_b128 v[140:143], v174 offset:21504
	ds_read_b128 v[144:147], v174 offset:22528
	ds_read_b128 v[148:151], v174 offset:23552
	global_load_lds_dwordx4 v[152:153], off
	v_lshl_add_u64 v[152:153], v[210:211], 0, s[52:53]
	s_mov_b32 m0, s25
	s_nop 0
	global_load_lds_dwordx4 v[152:153], off
	s_barrier
; #define PG8_STAGE(bufoff, gbase, voff) do { _Pragma("unroll") for (int _i = 0; _i < 2; ++_i) \
;         __builtin_amdgcn_global_load_lds((const __attribute__((address_space(1))) unsigned*)((const char*)(gbase) + (voff)[_i]), (LAS unsigned*)(lds + (bufoff) + ldsw + _i * 8192), 16, 0, 0); } while (0)
; #define PG8_LDA(dst, b, h) do { _Pragma("unroll") for (int m = 0; m < 4; ++m) _Pragma("unroll") for (int k = 0; k < 2; ++k) dst[m][k] = *(const LAS bf16x8*)(lds + PG8_SA(b, h) + aoff + m * 2048 + k * 1024); } while (0)
; #define PG8_LDB(dst, b, h) do { _Pragma("unroll") for (int n = 0; n < 2; ++n) _Pragma("unroll") for (int k = 0; k < 2; ++k) dst[n][k] = *(const LAS bf16x8*)(lds + PG8_SB(b, h) + boff + n * 2048 + k * 1024); } while (0)
; #define PG8_MMA(ai, bj, At, Bt) do { __builtin_amdgcn_s_setprio(1); _Pragma("unroll") for (int m = 0; m < 4; ++m) _Pragma("unroll") for (int n = 0; n < 2; ++n) _Pragma("unroll") for (int k = 0; k < 2; ++k) \
;         acc[ai][bj][m][n] = __builtin_amdgcn_mfma_f32_16x16x32_bf16(Bt[n][k], At[m][k], acc[ai][bj][m][n], 0, 0, 0); __builtin_amdgcn_s_setprio(0); } while (0)
; #define PG8_WAIT_V(n) asm volatile("s_waitcnt vmcnt(" #n ")" ::: "memory")
; #define PG8_WAIT_L(n) asm volatile("s_waitcnt lgkmcnt(" #n ")" ::: "memory")
; #define PG8_BAR __builtin_amdgcn_s_barrier()
; #define PG8_SCHED __builtin_amdgcn_sched_barrier(0)
; template <class Epi>
; __device__ __forceinline__ void gemm_phase(LAS unsigned char* lds, const Gemm g, const StaticOrder& S_in, const Epi& E, int sw) {
;     ...
;             PG8_BAR; PG8_WAIT_L(0); PG8_MMA(1, 0, At, B0); PG8_BAR; PG8_SCHED;
;             PG8_STAGE(PG8_SB(0, 1), b2 + hstepB, voffB);
;             PG8_WAIT_V(6); PG8_BAR; PG8_MMA(1, 1, At, B1); PG8_BAR;
;             PG8_LDB(B0, 1, 0); PG8_SCHED; PG8_LDA(At, 1, 0); PG8_STAGE(PG8_SA(0, 1), a2 + hstepA, voffA);
;             PG8_WAIT_L(8); PG8_BAR; PG8_WAIT_L(0); PG8_MMA(0, 0, At, B0); PG8_BAR; PG8_SCHED;
;             PG8_LDB(B1, 1, 1); PG8_STAGE(PG8_SB(1, 0), b3, voffB);
;             PG8_BAR; PG8_WAIT_L(0); PG8_MMA(0, 1, At, B1); PG8_BAR;
;             PG8_LDA(At, 1, 1); PG8_STAGE(PG8_SA(1, 0), a3, voffA);
;             PG8_BAR; PG8_WAIT_L(0); PG8_MMA(1, 0, At, B0); PG8_BAR; PG8_SCHED;
	s_waitcnt lgkmcnt(0)
	s_setprio 1
	s_waitcnt lgkmcnt(0)
	v_mfma_f32_16x16x32_bf16 v[152:155], v[18:21], v[62:65], v[10:13]
	v_mfma_f32_16x16x32_bf16 v[156:159], v[26:29], v[62:65], v[14:17]
	v_mfma_f32_16x16x32_bf16 v[160:163], v[18:21], v[122:125], v[10:13]
	v_mfma_f32_16x16x32_bf16 v[164:167], v[26:29], v[122:125], v[14:17]
	v_mfma_f32_16x16x32_bf16 v[176:179], v[18:21], v[136:139], v[10:13]
	v_mfma_f32_16x16x32_bf16 v[180:183], v[26:29], v[136:139], v[14:17]
	v_mfma_f32_16x16x32_bf16 v[10:13], v[18:21], v[144:147], v[10:13]
	v_mfma_f32_16x16x32_bf16 v[14:17], v[26:29], v[144:147], v[14:17]
	v_mfma_f32_16x16x32_bf16 v[152:155], v[22:25], v[118:121], v[152:155]
	v_mfma_f32_16x16x32_bf16 v[156:159], v[30:33], v[118:121], v[156:159]
	v_mfma_f32_16x16x32_bf16 v[160:163], v[22:25], v[126:129], v[160:163]
	v_mfma_f32_16x16x32_bf16 v[164:167], v[30:33], v[126:129], v[164:167]
	v_mfma_f32_16x16x32_bf16 v[10:13], v[22:25], v[148:151], v[10:13]
	v_mfma_f32_16x16x32_bf16 v[14:17], v[30:33], v[148:151], v[14:17]
	v_mfma_f32_16x16x32_bf16 v[176:179], v[22:25], v[140:143], v[176:179]
	v_mfma_f32_16x16x32_bf16 v[180:183], v[30:33], v[140:143], v[180:183]
	s_setprio 0
	s_barrier
	s_add_u32 s52, s28, 0x10100
	s_addc_u32 s53, s29, 0
	s_add_i32 s51, s51, s38
	v_lshl_add_u64 v[18:19], s[52:53], 0, v[0:1]
	s_mov_b32 m0, s51
	s_add_i32 s48, s51, 0x2000
	global_load_lds_dwordx4 v[18:19], off
	v_lshl_add_u64 v[18:19], s[52:53], 0, v[134:135]
	s_mov_b32 m0, s48
	s_nop 0
	global_load_lds_dwordx4 v[18:19], off
	s_waitcnt vmcnt(6)
	s_barrier
	s_setprio 1
	v_mfma_f32_16x16x32_bf16 v[18:21], v[98:101], v[62:65], v[2:5]
	v_mfma_f32_16x16x32_bf16 v[22:25], v[106:109], v[62:65], v[6:9]
	v_mfma_f32_16x16x32_bf16 v[18:21], v[102:105], v[118:121], v[18:21]
	v_mfma_f32_16x16x32_bf16 v[22:25], v[110:113], v[118:121], v[22:25]
	v_mfma_f32_16x16x32_bf16 v[26:29], v[98:101], v[122:125], v[2:5]
	v_mfma_f32_16x16x32_bf16 v[30:33], v[106:109], v[122:125], v[6:9]
	v_mfma_f32_16x16x32_bf16 v[62:65], v[98:101], v[136:139], v[2:5]
	v_mfma_f32_16x16x32_bf16 v[118:121], v[106:109], v[136:139], v[6:9]
	v_mfma_f32_16x16x32_bf16 v[2:5], v[98:101], v[144:147], v[2:5]
	v_mfma_f32_16x16x32_bf16 v[6:9], v[106:109], v[144:147], v[6:9]
	v_mfma_f32_16x16x32_bf16 v[26:29], v[102:105], v[126:129], v[26:29]
	v_mfma_f32_16x16x32_bf16 v[30:33], v[110:113], v[126:129], v[30:33]
	v_mfma_f32_16x16x32_bf16 v[62:65], v[102:105], v[140:143], v[62:65]
	v_mfma_f32_16x16x32_bf16 v[118:121], v[110:113], v[140:143], v[118:121]
	v_mfma_f32_16x16x32_bf16 v[2:5], v[102:105], v[148:151], v[2:5]
	v_mfma_f32_16x16x32_bf16 v[6:9], v[110:113], v[148:151], v[6:9]
	s_setprio 0
	s_add_i32 s54, 0, 0x18000
	v_add_u32_e32 v220, s54, v171
	s_barrier
	ds_read_b128 v[98:101], v220
	ds_read_b128 v[102:105], v220 offset:1024
	ds_read_b128 v[106:109], v220 offset:2048
	ds_read_b128 v[110:113], v220 offset:3072
	s_add_u32 s52, s26, 0x80100
	s_addc_u32 s53, s27, 0
	s_mov_b32 m0, s43
	v_lshl_add_u64 v[192:193], s[52:53], 0, v[130:131]
	ds_read_b128 v[122:125], v174 offset:32768
	ds_read_b128 v[126:129], v174 offset:33792
	ds_read_b128 v[136:139], v174 offset:34816
	ds_read_b128 v[140:143], v174 offset:35840
	ds_read_b128 v[144:147], v174 offset:36864
	ds_read_b128 v[148:151], v174 offset:37888
	ds_read_b128 v[184:187], v174 offset:38912
	ds_read_b128 v[188:191], v174 offset:39936
	global_load_lds_dwordx4 v[192:193], off
	v_lshl_add_u64 v[192:193], s[52:53], 0, v[132:133]
	s_mov_b32 m0, s44
	s_nop 0
	global_load_lds_dwordx4 v[192:193], off
	s_waitcnt lgkmcnt(8)
	s_barrier
	s_waitcnt lgkmcnt(0)
	s_setprio 1
	s_waitcnt lgkmcnt(0)
	v_mfma_f32_16x16x32_bf16 v[66:69], v[98:101], v[122:125], v[66:69]
	v_mfma_f32_16x16x32_bf16 v[70:73], v[106:109], v[122:125], v[70:73]
	v_mfma_f32_16x16x32_bf16 v[74:77], v[98:101], v[136:139], v[74:77]
	v_mfma_f32_16x16x32_bf16 v[78:81], v[106:109], v[136:139], v[78:81]
	v_mfma_f32_16x16x32_bf16 v[82:85], v[98:101], v[144:147], v[82:85]
	v_mfma_f32_16x16x32_bf16 v[86:89], v[106:109], v[144:147], v[86:89]
	v_mfma_f32_16x16x32_bf16 v[90:93], v[98:101], v[184:187], v[90:93]
	v_mfma_f32_16x16x32_bf16 v[94:97], v[106:109], v[184:187], v[94:97]
	v_mfma_f32_16x16x32_bf16 v[66:69], v[102:105], v[126:129], v[66:69]
	v_mfma_f32_16x16x32_bf16 v[70:73], v[110:113], v[126:129], v[70:73]
	v_mfma_f32_16x16x32_bf16 v[74:77], v[102:105], v[140:143], v[74:77]
	v_mfma_f32_16x16x32_bf16 v[78:81], v[110:113], v[140:143], v[78:81]
	v_mfma_f32_16x16x32_bf16 v[82:85], v[102:105], v[148:151], v[82:85]
	v_mfma_f32_16x16x32_bf16 v[86:89], v[110:113], v[148:151], v[86:89]
	v_mfma_f32_16x16x32_bf16 v[90:93], v[102:105], v[188:191], v[90:93]
	v_mfma_f32_16x16x32_bf16 v[94:97], v[110:113], v[188:191], v[94:97]
	s_setprio 0
	s_barrier
	s_add_i32 s56, 0, 0x1c000
	s_mov_b64 s[58:59], 0x180
	s_add_i32 s53, s54, s38
	v_add_u32_e32 v232, s56, v171
	v_lshl_add_u64 v[168:169], v[168:169], 0, s[58:59]
	s_mov_b32 m0, s53
	s_add_i32 s52, s53, 0x2000
	ds_read_b128 v[192:195], v232
	ds_read_b128 v[196:199], v232 offset:1024
	ds_read_b128 v[200:203], v232 offset:2048
	ds_read_b128 v[204:207], v232 offset:3072
	global_load_lds_dwordx4 v[168:169], off
	v_lshl_add_u64 v[168:169], v[172:173], 0, s[58:59]
	s_mov_b32 m0, s52
	s_nop 0
	global_load_lds_dwordx4 v[168:169], off
	s_barrier
; #define PG8_STAGE(bufoff, gbase, voff) do { _Pragma("unroll") for (int _i = 0; _i < 2; ++_i) \
;         __builtin_amdgcn_global_load_lds((const __attribute__((address_space(1))) unsigned*)((const char*)(gbase) + (voff)[_i]), (LAS unsigned*)(lds + (bufoff) + ldsw + _i * 8192), 16, 0, 0); } while (0)
; #define PG8_LDA(dst, b, h) do { _Pragma("unroll") for (int m = 0; m < 4; ++m) _Pragma("unroll") for (int k = 0; k < 2; ++k) dst[m][k] = *(const LAS bf16x8*)(lds + PG8_SA(b, h) + aoff + m * 2048 + k * 1024); } while (0)
; #define PG8_LDB(dst, b, h) do { _Pragma("unroll") for (int n = 0; n < 2; ++n) _Pragma("unroll") for (int k = 0; k < 2; ++k) dst[n][k] = *(const LAS bf16x8*)(lds + PG8_SB(b, h) + boff + n * 2048 + k * 1024); } while (0)
; #define PG8_MMA(ai, bj, At, Bt) do { __builtin_amdgcn_s_setprio(1); _Pragma("unroll") for (int m = 0; m < 4; ++m) _Pragma("unroll") for (int n = 0; n < 2; ++n) _Pragma("unroll") for (int k = 0; k < 2; ++k) \
;         acc[ai][bj][m][n] = __builtin_amdgcn_mfma_f32_16x16x32_bf16(Bt[n][k], At[m][k], acc[ai][bj][m][n], 0, 0, 0); __builtin_amdgcn_s_setprio(0); } while (0)
; #define PG8_WAIT_V(n) asm volatile("s_waitcnt vmcnt(" #n ")" ::: "memory")
; #define PG8_WAIT_L(n) asm volatile("s_waitcnt lgkmcnt(" #n ")" ::: "memory")
; #define PG8_BAR __builtin_amdgcn_s_barrier()
; #define PG8_SCHED __builtin_amdgcn_sched_barrier(0)
; template <class Epi>
; __device__ __forceinline__ void gemm_phase(LAS unsigned char* lds, const Gemm g, const StaticOrder& S_in, const Epi& E, int sw) {
;     ...
;             PG8_LDB(B0, 0, 0); PG8_SCHED; PG8_LDA(At, 0, 0); PG8_STAGE(PG8_SA(1, 1), a1 + hstepA, voffA);
;     ...
;             PG8_LDB(B1, 1, 1); PG8_STAGE(PG8_SB(1, 0), b3, voffB);
;             PG8_BAR; PG8_WAIT_L(0); PG8_MMA(0, 1, At, B1); PG8_BAR;
;             PG8_LDA(At, 1, 1); PG8_STAGE(PG8_SA(1, 0), a3, voffA);
;             PG8_BAR; PG8_WAIT_L(0); PG8_MMA(1, 0, At, B0); PG8_BAR; PG8_SCHED;
;             PG8_STAGE(PG8_SB(1, 1), b3 + hstepB, voffB);
;             PG8_WAIT_V(6); PG8_BAR; PG8_MMA(1, 1, At, B1); PG8_BAR;
	s_waitcnt lgkmcnt(0)
	s_setprio 1
	s_waitcnt lgkmcnt(0)
	v_mfma_f32_16x16x32_bf16 v[114:117], v[192:195], v[122:125], v[114:117]
	v_mfma_f32_16x16x32_bf16 v[34:37], v[200:203], v[122:125], v[34:37]
	v_mfma_f32_16x16x32_bf16 v[38:41], v[192:195], v[136:139], v[38:41]
	v_mfma_f32_16x16x32_bf16 v[42:45], v[200:203], v[136:139], v[42:45]
	v_mfma_f32_16x16x32_bf16 v[46:49], v[192:195], v[144:147], v[46:49]
	v_mfma_f32_16x16x32_bf16 v[50:53], v[200:203], v[144:147], v[50:53]
	v_mfma_f32_16x16x32_bf16 v[54:57], v[192:195], v[184:187], v[54:57]
	v_mfma_f32_16x16x32_bf16 v[58:61], v[200:203], v[184:187], v[58:61]
	v_mfma_f32_16x16x32_bf16 v[114:117], v[196:199], v[126:129], v[114:117]
	v_mfma_f32_16x16x32_bf16 v[34:37], v[204:207], v[126:129], v[34:37]
	v_mfma_f32_16x16x32_bf16 v[38:41], v[196:199], v[140:143], v[38:41]
	v_mfma_f32_16x16x32_bf16 v[42:45], v[204:207], v[140:143], v[42:45]
	v_mfma_f32_16x16x32_bf16 v[46:49], v[196:199], v[148:151], v[46:49]
	v_mfma_f32_16x16x32_bf16 v[50:53], v[204:207], v[148:151], v[50:53]
	v_mfma_f32_16x16x32_bf16 v[54:57], v[196:199], v[188:191], v[54:57]
	v_mfma_f32_16x16x32_bf16 v[58:61], v[204:207], v[188:191], v[58:61]
	s_setprio 0
	s_mov_b32 m0, s45
	v_lshl_add_u64 v[168:169], v[208:209], 0, s[58:59]
	s_barrier
	ds_read_b128 v[122:125], v174 offset:49152
	ds_read_b128 v[126:129], v174 offset:50176
	ds_read_b128 v[136:139], v174 offset:51200
	ds_read_b128 v[140:143], v174 offset:52224
	ds_read_b128 v[144:147], v174 offset:53248
	ds_read_b128 v[148:151], v174 offset:54272
	ds_read_b128 v[184:187], v174 offset:55296
	ds_read_b128 v[188:191], v174 offset:56320
	global_load_lds_dwordx4 v[168:169], off
	v_lshl_add_u64 v[168:169], v[210:211], 0, s[58:59]
	s_mov_b32 m0, s46
	s_nop 0
	global_load_lds_dwordx4 v[168:169], off
	s_barrier
	s_waitcnt lgkmcnt(0)
	s_setprio 1
	s_waitcnt lgkmcnt(0)
	v_mfma_f32_16x16x32_bf16 v[152:155], v[98:101], v[122:125], v[152:155]
	v_mfma_f32_16x16x32_bf16 v[156:159], v[106:109], v[122:125], v[156:159]
	v_mfma_f32_16x16x32_bf16 v[160:163], v[98:101], v[136:139], v[160:163]
	v_mfma_f32_16x16x32_bf16 v[164:167], v[106:109], v[136:139], v[164:167]
	v_mfma_f32_16x16x32_bf16 v[10:13], v[98:101], v[184:187], v[10:13]
	v_mfma_f32_16x16x32_bf16 v[14:17], v[106:109], v[184:187], v[14:17]
	v_mfma_f32_16x16x32_bf16 v[152:155], v[102:105], v[126:129], v[152:155]
	v_mfma_f32_16x16x32_bf16 v[156:159], v[110:113], v[126:129], v[156:159]
	v_mfma_f32_16x16x32_bf16 v[160:163], v[102:105], v[140:143], v[160:163]
	v_mfma_f32_16x16x32_bf16 v[164:167], v[110:113], v[140:143], v[164:167]
	v_mfma_f32_16x16x32_bf16 v[176:179], v[98:101], v[144:147], v[176:179]
	v_mfma_f32_16x16x32_bf16 v[180:183], v[106:109], v[144:147], v[180:183]
	v_mfma_f32_16x16x32_bf16 v[10:13], v[102:105], v[188:191], v[10:13]
	v_mfma_f32_16x16x32_bf16 v[14:17], v[110:113], v[188:191], v[14:17]
	v_mfma_f32_16x16x32_bf16 v[176:179], v[102:105], v[148:151], v[176:179]
	v_mfma_f32_16x16x32_bf16 v[180:183], v[110:113], v[148:151], v[180:183]
	s_setprio 0
	s_barrier
	s_add_u32 s54, s28, 0x10180
	s_addc_u32 s55, s29, 0
	s_add_i32 s29, s56, s38
	v_lshl_add_u64 v[98:99], s[54:55], 0, v[0:1]
	s_mov_b32 m0, s29
	s_add_i32 s28, s29, 0x2000
	global_load_lds_dwordx4 v[98:99], off
	v_lshl_add_u64 v[98:99], s[54:55], 0, v[134:135]
	s_mov_b32 m0, s28
	s_nop 0
	global_load_lds_dwordx4 v[98:99], off
	s_waitcnt vmcnt(6)
	s_barrier
	s_setprio 1
	v_mfma_f32_16x16x32_bf16 v[18:21], v[192:195], v[122:125], v[18:21]
	v_mfma_f32_16x16x32_bf16 v[22:25], v[200:203], v[122:125], v[22:25]
	v_mfma_f32_16x16x32_bf16 v[26:29], v[192:195], v[136:139], v[26:29]
	v_mfma_f32_16x16x32_bf16 v[30:33], v[200:203], v[136:139], v[30:33]
	v_mfma_f32_16x16x32_bf16 v[62:65], v[192:195], v[144:147], v[62:65]
	v_mfma_f32_16x16x32_bf16 v[98:101], v[200:203], v[144:147], v[118:121]
	v_mfma_f32_16x16x32_bf16 v[2:5], v[192:195], v[184:187], v[2:5]
	v_mfma_f32_16x16x32_bf16 v[6:9], v[200:203], v[184:187], v[6:9]
	v_mfma_f32_16x16x32_bf16 v[18:21], v[196:199], v[126:129], v[18:21]
	v_mfma_f32_16x16x32_bf16 v[22:25], v[204:207], v[126:129], v[22:25]
	v_mfma_f32_16x16x32_bf16 v[26:29], v[196:199], v[140:143], v[26:29]
	v_mfma_f32_16x16x32_bf16 v[30:33], v[204:207], v[140:143], v[30:33]
	v_mfma_f32_16x16x32_bf16 v[62:65], v[196:199], v[148:151], v[62:65]
	v_mfma_f32_16x16x32_bf16 v[98:101], v[204:207], v[148:151], v[98:101]
	v_mfma_f32_16x16x32_bf16 v[2:5], v[196:199], v[188:191], v[2:5]
	v_mfma_f32_16x16x32_bf16 v[6:9], v[204:207], v[188:191], v[6:9]
	s_setprio 0
	s_barrier
	ds_read_b128 v[102:105], v175
	ds_read_b128 v[106:109], v175 offset:1024
	ds_read_b128 v[110:113], v175 offset:2048
	ds_read_b128 v[118:121], v175 offset:3072
	s_add_u32 s26, s26, 0x80180
	s_addc_u32 s27, s27, 0
	s_mov_b32 m0, s50
	v_lshl_add_u64 v[168:169], s[26:27], 0, v[130:131]
	ds_read_b128 v[122:125], v174
	ds_read_b128 v[126:129], v174 offset:1024
	ds_read_b128 v[136:139], v174 offset:2048
	ds_read_b128 v[140:143], v174 offset:3072
	ds_read_b128 v[144:147], v174 offset:4096
	ds_read_b128 v[148:151], v174 offset:5120
	ds_read_b128 v[184:187], v174 offset:6144
	ds_read_b128 v[188:191], v174 offset:7168
	global_load_lds_dwordx4 v[168:169], off
	v_lshl_add_u64 v[168:169], s[26:27], 0, v[132:133]
	s_mov_b32 m0, s13
	s_nop 0
	global_load_lds_dwordx4 v[168:169], off
	s_waitcnt lgkmcnt(8)
	s_barrier
; #define PG8_STAGE(bufoff, gbase, voff) do { _Pragma("unroll") for (int _i = 0; _i < 2; ++_i) \
;         __builtin_amdgcn_global_load_lds((const __attribute__((address_space(1))) unsigned*)((const char*)(gbase) + (voff)[_i]), (LAS unsigned*)(lds + (bufoff) + ldsw + _i * 8192), 16, 0, 0); } while (0)
; #define PG8_LDA(dst, b, h) do { _Pragma("unroll") for (int m = 0; m < 4; ++m) _Pragma("unroll") for (int k = 0; k < 2; ++k) dst[m][k] = *(const LAS bf16x8*)(lds + PG8_SA(b, h) + aoff + m * 2048 + k * 1024); } while (0)
; #define PG8_LDB(dst, b, h) do { _Pragma("unroll") for (int n = 0; n < 2; ++n) _Pragma("unroll") for (int k = 0; k < 2; ++k) dst[n][k] = *(const LAS bf16x8*)(lds + PG8_SB(b, h) + boff + n * 2048 + k * 1024); } while (0)
; #define PG8_WAIT_V(n) asm volatile("s_waitcnt vmcnt(" #n ")" ::: "memory")
; #define PG8_WAIT_L(n) asm volatile("s_waitcnt lgkmcnt(" #n ")" ::: "memory")
; #define PG8_BAR __builtin_amdgcn_s_barrier()
; #define PG8_SCHED __builtin_amdgcn_sched_barrier(0)
; template <class Epi>
; __device__ __forceinline__ void gemm_phase(LAS unsigned char* lds, const Gemm g, const StaticOrder& S_in, const Epi& E, int sw) {
;     ...
;             PG8_WAIT_L(8); PG8_BAR; PG8_WAIT_L(0); PG8_MMA(0, 0, At, B0); PG8_BAR; PG8_SCHED;
;             PG8_LDB(B1, 0, 1); PG8_STAGE(PG8_SB(0, 0), b2, voffB);
;             PG8_BAR; PG8_WAIT_L(0); PG8_MMA(0, 1, At, B1); PG8_BAR;
;             PG8_LDA(At, 0, 1); PG8_STAGE(PG8_SA(0, 0), a2, voffA);
;             PG8_BAR; PG8_WAIT_L(0); PG8_MMA(1, 0, At, B0); PG8_BAR; PG8_SCHED;
;             PG8_STAGE(PG8_SB(0, 1), b2 + hstepB, voffB);
;             PG8_WAIT_V(6); PG8_BAR; PG8_MMA(1, 1, At, B1); PG8_BAR;
;             PG8_LDB(B0, 1, 0); PG8_SCHED; PG8_LDA(At, 1, 0); PG8_STAGE(PG8_SA(0, 1), a2 + hstepA, voffA);
;             PG8_WAIT_L(8); PG8_BAR; PG8_WAIT_L(0); PG8_MMA(0, 0, At, B0); PG8_BAR; PG8_SCHED;
;             PG8_LDB(B1, 1, 1); PG8_STAGE(PG8_SB(1, 0), b3, voffB);
;             PG8_BAR; PG8_WAIT_L(0); PG8_MMA(0, 1, At, B1); PG8_BAR;
;             PG8_LDA(At, 1, 1); PG8_STAGE(PG8_SA(1, 0), a3, voffA);
;             PG8_BAR; PG8_WAIT_L(0); PG8_MMA(1, 0, At, B0); PG8_BAR; PG8_SCHED;
;             PG8_STAGE(PG8_SB(1, 1), b3 + hstepB, voffB);
;             PG8_WAIT_V(6); PG8_BAR; PG8_MMA(1, 1, At, B1); PG8_BAR;
	s_waitcnt lgkmcnt(0)
	s_setprio 1
	s_waitcnt lgkmcnt(0)
	v_mfma_f32_16x16x32_bf16 v[66:69], v[102:105], v[122:125], v[66:69]
	v_mfma_f32_16x16x32_bf16 v[70:73], v[110:113], v[122:125], v[70:73]
	v_mfma_f32_16x16x32_bf16 v[74:77], v[102:105], v[136:139], v[74:77]
	v_mfma_f32_16x16x32_bf16 v[78:81], v[110:113], v[136:139], v[78:81]
	v_mfma_f32_16x16x32_bf16 v[82:85], v[102:105], v[144:147], v[82:85]
	v_mfma_f32_16x16x32_bf16 v[86:89], v[110:113], v[144:147], v[86:89]
	v_mfma_f32_16x16x32_bf16 v[90:93], v[102:105], v[184:187], v[90:93]
	v_mfma_f32_16x16x32_bf16 v[94:97], v[110:113], v[184:187], v[94:97]
	v_mfma_f32_16x16x32_bf16 v[66:69], v[106:109], v[126:129], v[66:69]
	v_mfma_f32_16x16x32_bf16 v[70:73], v[118:121], v[126:129], v[70:73]
	v_mfma_f32_16x16x32_bf16 v[74:77], v[106:109], v[140:143], v[74:77]
	v_mfma_f32_16x16x32_bf16 v[78:81], v[118:121], v[140:143], v[78:81]
	v_mfma_f32_16x16x32_bf16 v[82:85], v[106:109], v[148:151], v[82:85]
	v_mfma_f32_16x16x32_bf16 v[86:89], v[118:121], v[148:151], v[86:89]
	v_mfma_f32_16x16x32_bf16 v[90:93], v[106:109], v[188:191], v[90:93]
	v_mfma_f32_16x16x32_bf16 v[94:97], v[118:121], v[188:191], v[94:97]
	s_setprio 0
	s_barrier
	s_mov_b32 m0, s49
	v_lshl_add_u64 v[168:169], s[30:31], 0, v[0:1]
	ds_read_b128 v[192:195], v212
	ds_read_b128 v[196:199], v212 offset:1024
	ds_read_b128 v[200:203], v212 offset:2048
	ds_read_b128 v[204:207], v212 offset:3072
	global_load_lds_dwordx4 v[168:169], off
	v_lshl_add_u64 v[172:173], s[30:31], 0, v[134:135]
	s_mov_b32 m0, s17
	s_nop 0
	global_load_lds_dwordx4 v[172:173], off
	s_barrier
	s_waitcnt lgkmcnt(0)
	s_setprio 1
	s_waitcnt lgkmcnt(0)
	v_mfma_f32_16x16x32_bf16 v[50:53], v[200:203], v[144:147], v[50:53]
	v_mfma_f32_16x16x32_bf16 v[38:41], v[192:195], v[136:139], v[38:41]
	v_mfma_f32_16x16x32_bf16 v[42:45], v[200:203], v[136:139], v[42:45]
	v_mfma_f32_16x16x32_bf16 v[136:139], v[204:207], v[148:151], v[50:53]
	v_mfma_f32_16x16x32_bf16 v[50:53], v[192:195], v[184:187], v[54:57]
	v_mfma_f32_16x16x32_bf16 v[34:37], v[200:203], v[122:125], v[34:37]
	v_mfma_f32_16x16x32_bf16 v[38:41], v[196:199], v[140:143], v[38:41]
	v_mfma_f32_16x16x32_bf16 v[42:45], v[204:207], v[140:143], v[42:45]
	v_mfma_f32_16x16x32_bf16 v[46:49], v[192:195], v[144:147], v[46:49]
	v_mfma_f32_16x16x32_bf16 v[140:143], v[196:199], v[188:191], v[50:53]
	v_mfma_f32_16x16x32_bf16 v[50:53], v[200:203], v[184:187], v[58:61]
	v_mfma_f32_16x16x32_bf16 v[114:117], v[192:195], v[122:125], v[114:117]
	v_mfma_f32_16x16x32_bf16 v[34:37], v[204:207], v[126:129], v[34:37]
	v_mfma_f32_16x16x32_bf16 v[46:49], v[196:199], v[148:151], v[46:49]
	v_mfma_f32_16x16x32_bf16 v[144:147], v[204:207], v[188:191], v[50:53]
	v_mfma_f32_16x16x32_bf16 v[208:211], v[196:199], v[126:129], v[114:117]
	s_setprio 0
	s_mov_b32 m0, s23
	v_lshl_add_u64 v[240:241], s[34:35], 0, v[130:131]
	s_barrier
	ds_read_b128 v[50:53], v174 offset:16384
	ds_read_b128 v[54:57], v174 offset:17408
	ds_read_b128 v[58:61], v174 offset:18432
	ds_read_b128 v[114:117], v174 offset:19456
	ds_read_b128 v[122:125], v174 offset:20480
	ds_read_b128 v[126:129], v174 offset:21504
	ds_read_b128 v[148:151], v174 offset:22528
	ds_read_b128 v[184:187], v174 offset:23552
	global_load_lds_dwordx4 v[240:241], off
	v_lshl_add_u64 v[242:243], s[34:35], 0, v[132:133]
	s_mov_b32 m0, s25
	s_nop 0
	global_load_lds_dwordx4 v[242:243], off
	s_barrier
	s_waitcnt lgkmcnt(0)
	s_setprio 1
	s_waitcnt lgkmcnt(0)
	v_mfma_f32_16x16x32_bf16 v[152:155], v[102:105], v[50:53], v[152:155]
	v_mfma_f32_16x16x32_bf16 v[156:159], v[110:113], v[50:53], v[156:159]
	v_mfma_f32_16x16x32_bf16 v[160:163], v[102:105], v[58:61], v[160:163]
	v_mfma_f32_16x16x32_bf16 v[164:167], v[110:113], v[58:61], v[164:167]
	v_mfma_f32_16x16x32_bf16 v[10:13], v[102:105], v[148:151], v[10:13]
	v_mfma_f32_16x16x32_bf16 v[14:17], v[110:113], v[148:151], v[14:17]
	v_mfma_f32_16x16x32_bf16 v[152:155], v[106:109], v[54:57], v[152:155]
	v_mfma_f32_16x16x32_bf16 v[156:159], v[118:121], v[54:57], v[156:159]
	v_mfma_f32_16x16x32_bf16 v[160:163], v[106:109], v[114:117], v[160:163]
	v_mfma_f32_16x16x32_bf16 v[164:167], v[118:121], v[114:117], v[164:167]
	v_mfma_f32_16x16x32_bf16 v[176:179], v[102:105], v[122:125], v[176:179]
	v_mfma_f32_16x16x32_bf16 v[180:183], v[110:113], v[122:125], v[180:183]
	v_mfma_f32_16x16x32_bf16 v[10:13], v[106:109], v[184:187], v[10:13]
	v_mfma_f32_16x16x32_bf16 v[14:17], v[118:121], v[184:187], v[14:17]
	v_mfma_f32_16x16x32_bf16 v[176:179], v[106:109], v[126:129], v[176:179]
	v_mfma_f32_16x16x32_bf16 v[180:183], v[118:121], v[126:129], v[180:183]
	s_setprio 0
	s_barrier
	s_add_u32 s26, s30, 0x10000
	s_addc_u32 s27, s31, 0
	s_mov_b32 m0, s51
	v_lshl_add_u64 v[102:103], s[26:27], 0, v[0:1]
	global_load_lds_dwordx4 v[102:103], off
	v_lshl_add_u64 v[102:103], s[26:27], 0, v[134:135]
	s_mov_b32 m0, s48
	s_nop 0
	global_load_lds_dwordx4 v[102:103], off
	s_waitcnt vmcnt(6)
	s_barrier
	s_setprio 1
	v_mfma_f32_16x16x32_bf16 v[26:29], v[192:195], v[58:61], v[26:29]
	v_mfma_f32_16x16x32_bf16 v[188:191], v[196:199], v[114:117], v[26:29]
	v_mfma_f32_16x16x32_bf16 v[26:29], v[200:203], v[58:61], v[30:33]
	v_mfma_f32_16x16x32_bf16 v[18:21], v[192:195], v[50:53], v[18:21]
	v_mfma_f32_16x16x32_bf16 v[22:25], v[200:203], v[50:53], v[22:25]
	v_mfma_f32_16x16x32_bf16 v[212:215], v[204:207], v[114:117], v[26:29]
	v_mfma_f32_16x16x32_bf16 v[26:29], v[192:195], v[122:125], v[62:65]
	v_mfma_f32_16x16x32_bf16 v[2:5], v[192:195], v[148:151], v[2:5]
	v_mfma_f32_16x16x32_bf16 v[6:9], v[200:203], v[148:151], v[6:9]
	v_mfma_f32_16x16x32_bf16 v[18:21], v[196:199], v[54:57], v[18:21]
	v_mfma_f32_16x16x32_bf16 v[22:25], v[204:207], v[54:57], v[22:25]
	v_mfma_f32_16x16x32_bf16 v[62:65], v[196:199], v[126:129], v[26:29]
	v_mfma_f32_16x16x32_bf16 v[26:29], v[200:203], v[122:125], v[98:101]
	v_mfma_f32_16x16x32_bf16 v[2:5], v[196:199], v[184:187], v[2:5]
	v_mfma_f32_16x16x32_bf16 v[6:9], v[204:207], v[184:187], v[6:9]
	v_mfma_f32_16x16x32_bf16 v[216:219], v[204:207], v[126:129], v[26:29]
	s_setprio 0
	s_barrier
; #define PG8_STAGE(bufoff, gbase, voff) do { _Pragma("unroll") for (int _i = 0; _i < 2; ++_i) \
;         __builtin_amdgcn_global_load_lds((const __attribute__((address_space(1))) unsigned*)((const char*)(gbase) + (voff)[_i]), (LAS unsigned*)(lds + (bufoff) + ldsw + _i * 8192), 16, 0, 0); } while (0)
; #define PG8_LDA(dst, b, h) do { _Pragma("unroll") for (int m = 0; m < 4; ++m) _Pragma("unroll") for (int k = 0; k < 2; ++k) dst[m][k] = *(const LAS bf16x8*)(lds + PG8_SA(b, h) + aoff + m * 2048 + k * 1024); } while (0)
; #define PG8_LDB(dst, b, h) do { _Pragma("unroll") for (int n = 0; n < 2; ++n) _Pragma("unroll") for (int k = 0; k < 2; ++k) dst[n][k] = *(const LAS bf16x8*)(lds + PG8_SB(b, h) + boff + n * 2048 + k * 1024); } while (0)
; #define PG8_MMA(ai, bj, At, Bt) do { __builtin_amdgcn_s_setprio(1); _Pragma("unroll") for (int m = 0; m < 4; ++m) _Pragma("unroll") for (int n = 0; n < 2; ++n) _Pragma("unroll") for (int k = 0; k < 2; ++k) \
;         acc[ai][bj][m][n] = __builtin_amdgcn_mfma_f32_16x16x32_bf16(Bt[n][k], At[m][k], acc[ai][bj][m][n], 0, 0, 0); __builtin_amdgcn_s_setprio(0); } while (0)
; #define PG8_WAIT_V(n) asm volatile("s_waitcnt vmcnt(" #n ")" ::: "memory")
; #define PG8_WAIT_L(n) asm volatile("s_waitcnt lgkmcnt(" #n ")" ::: "memory")
; #define PG8_BAR __builtin_amdgcn_s_barrier()
; #define PG8_SCHED __builtin_amdgcn_sched_barrier(0)
; template <class Epi>
; __device__ __forceinline__ void gemm_phase(LAS unsigned char* lds, const Gemm g, const StaticOrder& S_in, const Epi& E, int sw) {
;     ...
;             PG8_LDB(B0, 1, 0); PG8_SCHED; PG8_LDA(At, 1, 0); PG8_STAGE(PG8_SA(0, 1), a2 + hstepA, voffA);
;             PG8_WAIT_L(8); PG8_BAR; PG8_WAIT_L(0); PG8_MMA(0, 0, At, B0); PG8_BAR; PG8_SCHED;
;             PG8_LDB(B1, 1, 1); PG8_STAGE(PG8_SB(1, 0), b3, voffB);
;             PG8_BAR; PG8_WAIT_L(0); PG8_MMA(0, 1, At, B1); PG8_BAR;
;             PG8_LDA(At, 1, 1); PG8_STAGE(PG8_SA(1, 0), a3, voffA);
;             PG8_BAR; PG8_WAIT_L(0); PG8_MMA(1, 0, At, B0); PG8_BAR; PG8_SCHED;
;             PG8_STAGE(PG8_SB(1, 1), b3 + hstepB, voffB);
;             PG8_WAIT_V(6); PG8_BAR; PG8_MMA(1, 1, At, B1); PG8_BAR;
	s_nop 2
	ds_read_b128 v[26:29], v220
	ds_read_b128 v[30:33], v220 offset:1024
	ds_read_b128 v[148:151], v220 offset:2048
	ds_read_b128 v[184:187], v220 offset:3072
	s_add_u32 s26, s34, 0x80000
	s_addc_u32 s27, s35, 0
	s_mov_b32 m0, s43
	v_lshl_add_u64 v[58:59], s[26:27], 0, v[130:131]
	ds_read_b128 v[50:53], v174 offset:32768
	ds_read_b128 v[54:57], v174 offset:33792
	ds_read_b128 v[98:101], v174 offset:34816
	ds_read_b128 v[102:105], v174 offset:35840
	ds_read_b128 v[110:113], v174 offset:36864
	ds_read_b128 v[192:195], v174 offset:37888
	ds_read_b128 v[196:199], v174 offset:38912
	ds_read_b128 v[200:203], v174 offset:39936
	global_load_lds_dwordx4 v[58:59], off
	v_lshl_add_u64 v[58:59], s[26:27], 0, v[132:133]
	s_mov_b32 m0, s44
	s_nop 0
	global_load_lds_dwordx4 v[58:59], off
	s_waitcnt lgkmcnt(8)
	s_barrier
	s_waitcnt lgkmcnt(0)
	s_setprio 1
	s_waitcnt lgkmcnt(0)
	v_mfma_f32_16x16x32_bf16 v[58:61], v[26:29], v[50:53], v[66:69]
	v_mfma_f32_16x16x32_bf16 v[204:207], v[30:33], v[54:57], v[58:61]
	v_mfma_f32_16x16x32_bf16 v[58:61], v[148:151], v[50:53], v[70:73]
	v_mfma_f32_16x16x32_bf16 v[220:223], v[184:187], v[54:57], v[58:61]
	v_mfma_f32_16x16x32_bf16 v[58:61], v[26:29], v[98:101], v[74:77]
	v_mfma_f32_16x16x32_bf16 v[224:227], v[30:33], v[102:105], v[58:61]
	v_mfma_f32_16x16x32_bf16 v[58:61], v[148:151], v[98:101], v[78:81]
	v_mfma_f32_16x16x32_bf16 v[126:129], v[184:187], v[102:105], v[58:61]
	v_mfma_f32_16x16x32_bf16 v[58:61], v[26:29], v[110:113], v[82:85]
	v_mfma_f32_16x16x32_bf16 v[122:125], v[30:33], v[192:195], v[58:61]
	v_mfma_f32_16x16x32_bf16 v[58:61], v[148:151], v[110:113], v[86:89]
	v_mfma_f32_16x16x32_bf16 v[118:121], v[184:187], v[192:195], v[58:61]
	v_mfma_f32_16x16x32_bf16 v[58:61], v[26:29], v[196:199], v[90:93]
	v_mfma_f32_16x16x32_bf16 v[114:117], v[30:33], v[200:203], v[58:61]
	v_mfma_f32_16x16x32_bf16 v[58:61], v[148:151], v[196:199], v[94:97]
	v_mfma_f32_16x16x32_bf16 v[106:109], v[184:187], v[200:203], v[58:61]
	s_setprio 0
	s_barrier
	s_mov_b32 m0, s53
	s_nop 3
	v_lshl_add_u64 v[58:59], v[168:169], 0, s[86:87]
	ds_read_b128 v[78:81], v232
	ds_read_b128 v[82:85], v232 offset:1024
	ds_read_b128 v[228:231], v232 offset:2048
	ds_read_b128 v[232:235], v232 offset:3072
	global_load_lds_dwordx4 v[58:59], off
	v_lshl_add_u64 v[58:59], v[172:173], 0, s[86:87]
	s_mov_b32 m0, s52
	s_nop 0
	global_load_lds_dwordx4 v[58:59], off
	s_barrier
	s_waitcnt lgkmcnt(0)
	s_setprio 1
	s_waitcnt lgkmcnt(0)
	v_mfma_f32_16x16x32_bf16 v[34:37], v[228:231], v[50:53], v[34:37]
	v_mfma_f32_16x16x32_bf16 v[66:69], v[232:235], v[54:57], v[34:37]
	v_mfma_f32_16x16x32_bf16 v[34:37], v[78:81], v[98:101], v[38:41]
	v_mfma_f32_16x16x32_bf16 v[58:61], v[78:81], v[50:53], v[208:211]
	v_mfma_f32_16x16x32_bf16 v[50:53], v[82:85], v[102:105], v[34:37]
	v_mfma_f32_16x16x32_bf16 v[34:37], v[228:231], v[98:101], v[42:45]
	v_mfma_f32_16x16x32_bf16 v[58:61], v[82:85], v[54:57], v[58:61]
	v_mfma_f32_16x16x32_bf16 v[54:57], v[232:235], v[102:105], v[34:37]
	v_mfma_f32_16x16x32_bf16 v[34:37], v[78:81], v[110:113], v[46:49]
	v_mfma_f32_16x16x32_bf16 v[42:45], v[82:85], v[192:195], v[34:37]
	v_mfma_f32_16x16x32_bf16 v[34:37], v[228:231], v[110:113], v[136:139]
	v_mfma_f32_16x16x32_bf16 v[46:49], v[232:235], v[192:195], v[34:37]
	v_mfma_f32_16x16x32_bf16 v[34:37], v[78:81], v[196:199], v[140:143]
	v_mfma_f32_16x16x32_bf16 v[38:41], v[228:231], v[196:199], v[144:147]
	v_mfma_f32_16x16x32_bf16 v[34:37], v[82:85], v[200:203], v[34:37]
	v_mfma_f32_16x16x32_bf16 v[38:41], v[232:235], v[200:203], v[38:41]
	s_setprio 0
	s_mov_b32 m0, s45
	v_lshl_add_u64 v[70:71], v[240:241], 0, s[86:87]
	s_barrier
	ds_read_b128 v[136:139], v174 offset:49152
	ds_read_b128 v[140:143], v174 offset:50176
	ds_read_b128 v[144:147], v174 offset:51200
	ds_read_b128 v[192:195], v174 offset:52224
	ds_read_b128 v[196:199], v174 offset:53248
	ds_read_b128 v[200:203], v174 offset:54272
	ds_read_b128 v[208:211], v174 offset:55296
	ds_read_b128 v[236:239], v174 offset:56320
	global_load_lds_dwordx4 v[70:71], off
	v_lshl_add_u64 v[70:71], v[242:243], 0, s[86:87]
	s_mov_b32 m0, s46
	s_nop 0
	global_load_lds_dwordx4 v[70:71], off
	s_barrier
	s_waitcnt lgkmcnt(0)
	s_setprio 1
	s_waitcnt lgkmcnt(0)
	v_mfma_f32_16x16x32_bf16 v[70:73], v[26:29], v[136:139], v[152:155]
	v_mfma_f32_16x16x32_bf16 v[110:113], v[30:33], v[140:143], v[70:73]
	v_mfma_f32_16x16x32_bf16 v[70:73], v[148:151], v[136:139], v[156:159]
	v_mfma_f32_16x16x32_bf16 v[102:105], v[184:187], v[140:143], v[70:73]
	v_mfma_f32_16x16x32_bf16 v[70:73], v[26:29], v[144:147], v[160:163]
	v_mfma_f32_16x16x32_bf16 v[98:101], v[30:33], v[192:195], v[70:73]
	v_mfma_f32_16x16x32_bf16 v[70:73], v[148:151], v[144:147], v[164:167]
	v_mfma_f32_16x16x32_bf16 v[94:97], v[184:187], v[192:195], v[70:73]
	v_mfma_f32_16x16x32_bf16 v[70:73], v[26:29], v[196:199], v[176:179]
	v_mfma_f32_16x16x32_bf16 v[10:13], v[26:29], v[208:211], v[10:13]
	v_mfma_f32_16x16x32_bf16 v[90:93], v[30:33], v[200:203], v[70:73]
	v_mfma_f32_16x16x32_bf16 v[70:73], v[148:151], v[196:199], v[180:183]
	v_mfma_f32_16x16x32_bf16 v[74:77], v[30:33], v[236:239], v[10:13]
	v_mfma_f32_16x16x32_bf16 v[10:13], v[148:151], v[208:211], v[14:17]
	v_mfma_f32_16x16x32_bf16 v[86:89], v[184:187], v[200:203], v[70:73]
	v_mfma_f32_16x16x32_bf16 v[70:73], v[184:187], v[236:239], v[10:13]
	s_setprio 0
	s_barrier
	s_add_u32 s26, s30, 0x10080
	s_addc_u32 s27, s31, 0
	s_mov_b32 m0, s29
	s_nop 0
	v_lshl_add_u64 v[10:11], s[26:27], 0, v[0:1]
	global_load_lds_dwordx4 v[10:11], off
	v_lshl_add_u64 v[10:11], s[26:27], 0, v[134:135]
	s_mov_b32 m0, s28
	s_nop 0
	global_load_lds_dwordx4 v[10:11], off
	s_waitcnt vmcnt(6)
	s_barrier
; #define LAS __attribute__((address_space(3)))
; __device__ __forceinline__ unsigned cvt_pk_bf16(float lo, float hi) { unsigned r; asm volatile("v_cvt_pk_bf16_f32 %0, %1, %2" : "=v"(r) : "v"(lo), "v"(hi)); return r; }
; __device__ __forceinline__ int ltid(int sw) { unsigned z = 0u; asm volatile("" : "+s"(sw), "+s"(z)); int t = sw * 64 + (int)__builtin_amdgcn_mbcnt_hi(~0u, __builtin_amdgcn_mbcnt_lo(~0u, z)); asm volatile("" : "+v"(t)); return t; }
; #define PG8_WAIT_V(n) asm volatile("s_waitcnt vmcnt(" #n ")" ::: "memory")
; #define PG8_BAR __builtin_amdgcn_s_barrier()
; template <class Epi>
; __device__ __forceinline__ void gemm_phase(LAS unsigned char* lds, const Gemm g, const StaticOrder& S_in, const Epi& E, int sw) {
;     ...
;             PG8_WAIT_V(6); PG8_BAR; PG8_MMA(1, 1, At, B1); PG8_BAR;
;     __device__ __forceinline__ void operator()(AccMut acc, const Unit& u, int sw) const {
;         const int tid_ = ltid(sw), lane_ = tid_ & 63, wr = sw >> 2, wc = sw & 3, fr = lane_ & 15, fq = lane_ >> 4;
;         const int row0 = u.pm * BM + wr * 64 + fr, c0 = u.pn * 128 + wc * 32 + 8 * fq;
;         u32x4 xnext = *(const u32x4*)(XC + (size_t)row0 * E + c0);
;         { f32x4 ns[2];
; #pragma unroll
;           for (int n = 0; n < 2; ++n) ns[n] = *(const LAS f32x4*)(nsp + c0 + 4 * n);
; #pragma unroll
;           for (int ai = 0; ai < 2; ++ai)
; #pragma unroll
;             for (int m = 0; m < 4; ++m) {
; #pragma unroll
;                 for (int n = 0; n < 2; ++n)
; #pragma unroll
;                     for (int jp = 0; jp < 2; ++jp) {
;                         const f32x2 z = (f32x2){acc[ai][0][m][n][2 * jp], acc[ai][0][m][n][2 * jp + 1]} * (-1.44269504f);
;                         f32x2 e; e.x = __builtin_amdgcn_exp2f(z.x); e.y = __builtin_amdgcn_exp2f(z.y); e = e + 1.0f;
;                         f32x2 r; r.x = __builtin_amdgcn_rcpf(e.x); r.y = __builtin_amdgcn_rcpf(e.y);
;                         r = r * (f32x2){ns[n][2 * jp], ns[n][2 * jp + 1]};
;                         acc[ai][0][m][n][2 * jp] = r.x; acc[ai][0][m][n][2 * jp + 1] = r.y; }
;                 const f32x4 l0 = acc[ai][0][m][0], l1 = acc[ai][0][m][1];
;                 u32x4 w; w.x = cvt_pk_bf16(l0[0], l0[1]); w.y = cvt_pk_bf16(l0[2], l0[3]); w.z = cvt_pk_bf16(l1[0], l1[1]); w.w = cvt_pk_bf16(l1[2], l1[3]);
;                 *(u32x4*)(LA + (size_t)(row0 + ai * HALF + m * 16) * E + c0) = w; } }
	s_setprio 1
	v_mfma_f32_16x16x32_bf16 v[10:13], v[78:81], v[136:139], v[18:21]
	v_mfma_f32_16x16x32_bf16 v[26:29], v[82:85], v[140:143], v[10:13]
	v_mfma_f32_16x16x32_bf16 v[10:13], v[228:231], v[136:139], v[22:25]
	v_mfma_f32_16x16x32_bf16 v[30:33], v[232:235], v[140:143], v[10:13]
	v_mfma_f32_16x16x32_bf16 v[10:13], v[78:81], v[144:147], v[188:191]
	v_mfma_f32_16x16x32_bf16 v[18:21], v[82:85], v[192:195], v[10:13]
	v_mfma_f32_16x16x32_bf16 v[10:13], v[228:231], v[144:147], v[212:215]
	v_mfma_f32_16x16x32_bf16 v[22:25], v[232:235], v[192:195], v[10:13]
	v_mfma_f32_16x16x32_bf16 v[10:13], v[78:81], v[196:199], v[62:65]
	v_mfma_f32_16x16x32_bf16 v[14:17], v[228:231], v[196:199], v[216:219]
	v_mfma_f32_16x16x32_bf16 v[2:5], v[78:81], v[208:211], v[2:5]
	v_mfma_f32_16x16x32_bf16 v[6:9], v[228:231], v[208:211], v[6:9]
	v_mfma_f32_16x16x32_bf16 v[10:13], v[82:85], v[200:203], v[10:13]
	v_mfma_f32_16x16x32_bf16 v[14:17], v[232:235], v[200:203], v[14:17]
	v_mfma_f32_16x16x32_bf16 v[2:5], v[82:85], v[236:239], v[2:5]
	v_mfma_f32_16x16x32_bf16 v[6:9], v[232:235], v[236:239], v[6:9]
	s_setprio 0
	s_barrier
	v_mbcnt_lo_u32_b32 v239, -1, 0
	v_mbcnt_hi_u32_b32 v239, -1, v239
	s_lshl_b32 s13, s24, 8
	s_add_i32 s13, s13, s3
	s_lshl_b32 s17, s22, 7
	s_or_b32 s17, s17, s85
	v_and_b32_e32 v240, 15, v239
	v_lshrrev_b32_e32 v241, 1, v239
	v_and_b32_e32 v241, 24, v241
	v_or_b32_e32 v240, s13, v240
	v_or_b32_e32 v242, s17, v241
	v_lshlrev_b32_e32 v168, 12, v240
	v_lshlrev_b32_e32 v243, 2, v242
	v_lshl_add_u32 v168, v242, 1, v168
	v_add_u32_e32 v243, 0x24400, v243
	global_load_dwordx4 v[136:139], v168, s[6:7]
	ds_read_b128 v[228:231], v243
	ds_read_b128 v[232:235], v243 offset:16
	v_add_u32_e32 v169, 0x10000, v168
	global_load_dwordx4 v[140:143], v169, s[6:7]
	v_add_u32_e32 v172, 0x20000, v168
	global_load_dwordx4 v[144:147], v172, s[6:7]
	v_add_u32_e32 v173, 0x30000, v168
	global_load_dwordx4 v[148:151], v173, s[6:7]
	v_add_u32_e32 v176, 0x80000, v168
	global_load_dwordx4 v[152:155], v176, s[6:7]
	v_add_u32_e32 v177, 0x90000, v168
	global_load_dwordx4 v[156:159], v177, s[6:7]
	v_add_u32_e32 v178, 0xa0000, v168
	global_load_dwordx4 v[160:163], v178, s[6:7]
	v_add_u32_e32 v179, 0xb0000, v168
	global_load_dwordx4 v[164:167], v179, s[6:7]
	s_mov_b32 s26, 0xbe888889
	s_mov_b32 s22, 0xbfaaaaab
	s_mov_b32 s13, 0xbe000000
	v_mov_b32_e32 v236, 0xbf2aaaab
	v_mov_b32_e32 v238, 0
	v_pk_mul_f32 v[180:181], v[204:205], s[74:75] op_sel_hi:[1,0]
	v_pk_mul_f32 v[182:183], v[206:207], s[74:75] op_sel_hi:[1,0]
	v_pk_mul_f32 v[184:185], v[220:221], s[74:75] op_sel_hi:[1,0]
	v_pk_mul_f32 v[186:187], v[222:223], s[74:75] op_sel_hi:[1,0]
	v_exp_f32_e32 v180, v180
	v_exp_f32_e32 v181, v181
	v_exp_f32_e32 v182, v182
	v_exp_f32_e32 v183, v183
	v_exp_f32_e32 v184, v184
	v_exp_f32_e32 v185, v185
	v_exp_f32_e32 v186, v186
	v_exp_f32_e32 v187, v187
	v_pk_add_f32 v[180:181], v[180:181], 1.0 op_sel_hi:[1,0]
	v_pk_add_f32 v[182:183], v[182:183], 1.0 op_sel_hi:[1,0]
	v_pk_add_f32 v[184:185], v[184:185], 1.0 op_sel_hi:[1,0]
	v_pk_add_f32 v[186:187], v[186:187], 1.0 op_sel_hi:[1,0]
	v_rcp_f32_e32 v180, v180
	v_rcp_f32_e32 v181, v181
	v_rcp_f32_e32 v182, v182
	v_rcp_f32_e32 v183, v183
	v_rcp_f32_e32 v184, v184
	v_rcp_f32_e32 v185, v185
	v_rcp_f32_e32 v186, v186
	v_rcp_f32_e32 v187, v187
	s_waitcnt lgkmcnt(0)
	v_pk_mul_f32 v[204:205], v[180:181], v[228:229]
	v_pk_mul_f32 v[206:207], v[182:183], v[230:231]
	v_pk_mul_f32 v[220:221], v[184:185], v[232:233]
	v_pk_mul_f32 v[222:223], v[186:187], v[234:235]
	v_min3_f32 v238, v238, v204, v205
	v_min3_f32 v238, v238, v206, v207
	v_min3_f32 v238, v238, v220, v221
	v_min3_f32 v238, v238, v222, v223
	v_cvt_pk_bf16_f32 v208, v204, v205
	v_cvt_pk_bf16_f32 v209, v206, v207
	v_cvt_pk_bf16_f32 v210, v220, v221
	v_cvt_pk_bf16_f32 v211, v222, v223
	global_store_dwordx4 v168, v[208:211], s[8:9]
	v_pk_mul_f32 v[180:181], v[224:225], s[74:75] op_sel_hi:[1,0]
	v_pk_mul_f32 v[182:183], v[226:227], s[74:75] op_sel_hi:[1,0]
	v_pk_mul_f32 v[184:185], v[126:127], s[74:75] op_sel_hi:[1,0]
	v_pk_mul_f32 v[186:187], v[128:129], s[74:75] op_sel_hi:[1,0]
	v_exp_f32_e32 v180, v180
	v_exp_f32_e32 v181, v181
	v_exp_f32_e32 v182, v182
	v_exp_f32_e32 v183, v183
	v_exp_f32_e32 v184, v184
	v_exp_f32_e32 v185, v185
	v_exp_f32_e32 v186, v186
	v_exp_f32_e32 v187, v187
	v_pk_add_f32 v[180:181], v[180:181], 1.0 op_sel_hi:[1,0]
	v_pk_add_f32 v[182:183], v[182:183], 1.0 op_sel_hi:[1,0]
	v_pk_add_f32 v[184:185], v[184:185], 1.0 op_sel_hi:[1,0]
	v_pk_add_f32 v[186:187], v[186:187], 1.0 op_sel_hi:[1,0]
	v_rcp_f32_e32 v180, v180
	v_rcp_f32_e32 v181, v181
	v_rcp_f32_e32 v182, v182
	v_rcp_f32_e32 v183, v183
	v_rcp_f32_e32 v184, v184
	v_rcp_f32_e32 v185, v185
	v_rcp_f32_e32 v186, v186
	v_rcp_f32_e32 v187, v187
	v_pk_mul_f32 v[224:225], v[180:181], v[228:229]
	v_pk_mul_f32 v[226:227], v[182:183], v[230:231]
	v_pk_mul_f32 v[126:127], v[184:185], v[232:233]
	v_pk_mul_f32 v[128:129], v[186:187], v[234:235]
	v_min3_f32 v238, v238, v224, v225
	v_min3_f32 v238, v238, v226, v227
	v_min3_f32 v238, v238, v126, v127
	v_min3_f32 v238, v238, v128, v129
	v_cvt_pk_bf16_f32 v212, v224, v225
	v_cvt_pk_bf16_f32 v213, v226, v227
	v_cvt_pk_bf16_f32 v214, v126, v127
	v_cvt_pk_bf16_f32 v215, v128, v129
	global_store_dwordx4 v169, v[212:215], s[8:9]
	v_pk_mul_f32 v[180:181], v[122:123], s[74:75] op_sel_hi:[1,0]
	v_pk_mul_f32 v[182:183], v[124:125], s[74:75] op_sel_hi:[1,0]
	v_pk_mul_f32 v[184:185], v[118:119], s[74:75] op_sel_hi:[1,0]
	v_pk_mul_f32 v[186:187], v[120:121], s[74:75] op_sel_hi:[1,0]
	v_exp_f32_e32 v180, v180
	v_exp_f32_e32 v181, v181
	v_exp_f32_e32 v182, v182
	v_exp_f32_e32 v183, v183
	v_exp_f32_e32 v184, v184
; __device__ __forceinline__ unsigned cvt_pk_bf16(float lo, float hi) { unsigned r; asm volatile("v_cvt_pk_bf16_f32 %0, %1, %2" : "=v"(r) : "v"(lo), "v"(hi)); return r; }
;     __device__ __forceinline__ void operator()(AccMut acc, const Unit& u, int sw) const {
;     ...
;           for (int ai = 0; ai < 2; ++ai)
; #pragma unroll
;             for (int m = 0; m < 4; ++m) {
; #pragma unroll
;                 for (int n = 0; n < 2; ++n)
; #pragma unroll
;                     for (int jp = 0; jp < 2; ++jp) {
;                         const f32x2 z = (f32x2){acc[ai][0][m][n][2 * jp], acc[ai][0][m][n][2 * jp + 1]} * (-1.44269504f);
;                         f32x2 e; e.x = __builtin_amdgcn_exp2f(z.x); e.y = __builtin_amdgcn_exp2f(z.y); e = e + 1.0f;
;                         f32x2 r; r.x = __builtin_amdgcn_rcpf(e.x); r.y = __builtin_amdgcn_rcpf(e.y);
;                         r = r * (f32x2){ns[n][2 * jp], ns[n][2 * jp + 1]};
;                         acc[ai][0][m][n][2 * jp] = r.x; acc[ai][0][m][n][2 * jp + 1] = r.y; }
;                 const f32x4 l0 = acc[ai][0][m][0], l1 = acc[ai][0][m][1];
;                 u32x4 w; w.x = cvt_pk_bf16(l0[0], l0[1]); w.y = cvt_pk_bf16(l0[2], l0[3]); w.z = cvt_pk_bf16(l1[0], l1[1]); w.w = cvt_pk_bf16(l1[2], l1[3]);
;                 *(u32x4*)(LA + (size_t)(row0 + ai * HALF + m * 16) * E + c0) = w; } }
	v_exp_f32_e32 v185, v185
	v_exp_f32_e32 v186, v186
	v_exp_f32_e32 v187, v187
	v_pk_add_f32 v[180:181], v[180:181], 1.0 op_sel_hi:[1,0]
	v_pk_add_f32 v[182:183], v[182:183], 1.0 op_sel_hi:[1,0]
	v_pk_add_f32 v[184:185], v[184:185], 1.0 op_sel_hi:[1,0]
	v_pk_add_f32 v[186:187], v[186:187], 1.0 op_sel_hi:[1,0]
	v_rcp_f32_e32 v180, v180
	v_rcp_f32_e32 v181, v181
	v_rcp_f32_e32 v182, v182
	v_rcp_f32_e32 v183, v183
	v_rcp_f32_e32 v184, v184
	v_rcp_f32_e32 v185, v185
	v_rcp_f32_e32 v186, v186
	v_rcp_f32_e32 v187, v187
	v_pk_mul_f32 v[122:123], v[180:181], v[228:229]
	v_pk_mul_f32 v[124:125], v[182:183], v[230:231]
	v_pk_mul_f32 v[118:119], v[184:185], v[232:233]
	v_pk_mul_f32 v[120:121], v[186:187], v[234:235]
	v_min3_f32 v238, v238, v122, v123
	v_min3_f32 v238, v238, v124, v125
	v_min3_f32 v238, v238, v118, v119
	v_min3_f32 v238, v238, v120, v121
	v_cvt_pk_bf16_f32 v208, v122, v123
	v_cvt_pk_bf16_f32 v209, v124, v125
	v_cvt_pk_bf16_f32 v210, v118, v119
	v_cvt_pk_bf16_f32 v211, v120, v121
	global_store_dwordx4 v172, v[208:211], s[8:9]
	v_pk_mul_f32 v[180:181], v[114:115], s[74:75] op_sel_hi:[1,0]
	v_pk_mul_f32 v[182:183], v[116:117], s[74:75] op_sel_hi:[1,0]
	v_pk_mul_f32 v[184:185], v[106:107], s[74:75] op_sel_hi:[1,0]
	v_pk_mul_f32 v[186:187], v[108:109], s[74:75] op_sel_hi:[1,0]
	v_exp_f32_e32 v180, v180
	v_exp_f32_e32 v181, v181
	v_exp_f32_e32 v182, v182
	v_exp_f32_e32 v183, v183
	v_exp_f32_e32 v184, v184
	v_exp_f32_e32 v185, v185
	v_exp_f32_e32 v186, v186
	v_exp_f32_e32 v187, v187
	v_pk_add_f32 v[180:181], v[180:181], 1.0 op_sel_hi:[1,0]
	v_pk_add_f32 v[182:183], v[182:183], 1.0 op_sel_hi:[1,0]
	v_pk_add_f32 v[184:185], v[184:185], 1.0 op_sel_hi:[1,0]
	v_pk_add_f32 v[186:187], v[186:187], 1.0 op_sel_hi:[1,0]
	v_rcp_f32_e32 v180, v180
	v_rcp_f32_e32 v181, v181
	v_rcp_f32_e32 v182, v182
	v_rcp_f32_e32 v183, v183
	v_rcp_f32_e32 v184, v184
	v_rcp_f32_e32 v185, v185
	v_rcp_f32_e32 v186, v186
	v_rcp_f32_e32 v187, v187
	v_pk_mul_f32 v[114:115], v[180:181], v[228:229]
	v_pk_mul_f32 v[116:117], v[182:183], v[230:231]
	v_pk_mul_f32 v[106:107], v[184:185], v[232:233]
	v_pk_mul_f32 v[108:109], v[186:187], v[234:235]
	v_min3_f32 v238, v238, v114, v115
	v_min3_f32 v238, v238, v116, v117
	v_min3_f32 v238, v238, v106, v107
	v_min3_f32 v238, v238, v108, v109
	v_cvt_pk_bf16_f32 v212, v114, v115
	v_cvt_pk_bf16_f32 v213, v116, v117
	v_cvt_pk_bf16_f32 v214, v106, v107
	v_cvt_pk_bf16_f32 v215, v108, v109
	global_store_dwordx4 v173, v[212:215], s[8:9]
	v_pk_mul_f32 v[180:181], v[110:111], s[74:75] op_sel_hi:[1,0]
	v_pk_mul_f32 v[182:183], v[112:113], s[74:75] op_sel_hi:[1,0]
	v_pk_mul_f32 v[184:185], v[102:103], s[74:75] op_sel_hi:[1,0]
	v_pk_mul_f32 v[186:187], v[104:105], s[74:75] op_sel_hi:[1,0]
	v_exp_f32_e32 v180, v180
	v_exp_f32_e32 v181, v181
	v_exp_f32_e32 v182, v182
	v_exp_f32_e32 v183, v183
	v_exp_f32_e32 v184, v184
	v_exp_f32_e32 v185, v185
	v_exp_f32_e32 v186, v186
	v_exp_f32_e32 v187, v187
	v_pk_add_f32 v[180:181], v[180:181], 1.0 op_sel_hi:[1,0]
	v_pk_add_f32 v[182:183], v[182:183], 1.0 op_sel_hi:[1,0]
	v_pk_add_f32 v[184:185], v[184:185], 1.0 op_sel_hi:[1,0]
	v_pk_add_f32 v[186:187], v[186:187], 1.0 op_sel_hi:[1,0]
	v_rcp_f32_e32 v180, v180
	v_rcp_f32_e32 v181, v181
	v_rcp_f32_e32 v182, v182
	v_rcp_f32_e32 v183, v183
	v_rcp_f32_e32 v184, v184
	v_rcp_f32_e32 v185, v185
	v_rcp_f32_e32 v186, v186
	v_rcp_f32_e32 v187, v187
	v_pk_mul_f32 v[110:111], v[180:181], v[228:229]
	v_pk_mul_f32 v[112:113], v[182:183], v[230:231]
	v_pk_mul_f32 v[102:103], v[184:185], v[232:233]
	v_pk_mul_f32 v[104:105], v[186:187], v[234:235]
	v_min3_f32 v238, v238, v110, v111
	v_min3_f32 v238, v238, v112, v113
	v_min3_f32 v238, v238, v102, v103
	v_min3_f32 v238, v238, v104, v105
	v_cvt_pk_bf16_f32 v208, v110, v111
	v_cvt_pk_bf16_f32 v209, v112, v113
	v_cvt_pk_bf16_f32 v210, v102, v103
	v_cvt_pk_bf16_f32 v211, v104, v105
	global_store_dwordx4 v176, v[208:211], s[8:9]
	v_pk_mul_f32 v[180:181], v[98:99], s[74:75] op_sel_hi:[1,0]
	v_pk_mul_f32 v[182:183], v[100:101], s[74:75] op_sel_hi:[1,0]
	v_pk_mul_f32 v[184:185], v[94:95], s[74:75] op_sel_hi:[1,0]
	v_pk_mul_f32 v[186:187], v[96:97], s[74:75] op_sel_hi:[1,0]
	v_exp_f32_e32 v180, v180
	v_exp_f32_e32 v181, v181
	v_exp_f32_e32 v182, v182
	v_exp_f32_e32 v183, v183
	v_exp_f32_e32 v184, v184
	v_exp_f32_e32 v185, v185
	v_exp_f32_e32 v186, v186
	v_exp_f32_e32 v187, v187
	v_pk_add_f32 v[180:181], v[180:181], 1.0 op_sel_hi:[1,0]
	v_pk_add_f32 v[182:183], v[182:183], 1.0 op_sel_hi:[1,0]
	v_pk_add_f32 v[184:185], v[184:185], 1.0 op_sel_hi:[1,0]
	v_pk_add_f32 v[186:187], v[186:187], 1.0 op_sel_hi:[1,0]
	v_rcp_f32_e32 v180, v180
	v_rcp_f32_e32 v181, v181
	v_rcp_f32_e32 v182, v182
	v_rcp_f32_e32 v183, v183
	v_rcp_f32_e32 v184, v184
	v_rcp_f32_e32 v185, v185
	v_rcp_f32_e32 v186, v186
	v_rcp_f32_e32 v187, v187
	v_pk_mul_f32 v[98:99], v[180:181], v[228:229]
	v_pk_mul_f32 v[100:101], v[182:183], v[230:231]
	v_pk_mul_f32 v[94:95], v[184:185], v[232:233]
	v_pk_mul_f32 v[96:97], v[186:187], v[234:235]
	v_min3_f32 v238, v238, v98, v99
	v_min3_f32 v238, v238, v100, v101
	v_min3_f32 v238, v238, v94, v95
	v_min3_f32 v238, v238, v96, v97
	v_cvt_pk_bf16_f32 v212, v98, v99
	v_cvt_pk_bf16_f32 v213, v100, v101
	v_cvt_pk_bf16_f32 v214, v94, v95
	v_cvt_pk_bf16_f32 v215, v96, v97
	global_store_dwordx4 v177, v[212:215], s[8:9]
	v_pk_mul_f32 v[180:181], v[90:91], s[74:75] op_sel_hi:[1,0]
	v_pk_mul_f32 v[182:183], v[92:93], s[74:75] op_sel_hi:[1,0]
	v_pk_mul_f32 v[184:185], v[86:87], s[74:75] op_sel_hi:[1,0]
	v_pk_mul_f32 v[186:187], v[88:89], s[74:75] op_sel_hi:[1,0]
	v_exp_f32_e32 v180, v180
	v_exp_f32_e32 v181, v181
	v_exp_f32_e32 v182, v182
	v_exp_f32_e32 v183, v183
;     __device__ __forceinline__ void operator()(AccMut acc, const Unit& u, int sw) const {
;     ...
;           for (int ai = 0; ai < 2; ++ai)
; #pragma unroll
;             for (int m = 0; m < 4; ++m) {
; #pragma unroll
;                 for (int n = 0; n < 2; ++n)
; #pragma unroll
;                     for (int jp = 0; jp < 2; ++jp) {
;                         const f32x2 z = (f32x2){acc[ai][0][m][n][2 * jp], acc[ai][0][m][n][2 * jp + 1]} * (-1.44269504f);
;                         f32x2 e; e.x = __builtin_amdgcn_exp2f(z.x); e.y = __builtin_amdgcn_exp2f(z.y); e = e + 1.0f;
;                         f32x2 r; r.x = __builtin_amdgcn_rcpf(e.x); r.y = __builtin_amdgcn_rcpf(e.y);
;                         r = r * (f32x2){ns[n][2 * jp], ns[n][2 * jp + 1]};
;                         acc[ai][0][m][n][2 * jp] = r.x; acc[ai][0][m][n][2 * jp + 1] = r.y; }
;                 const f32x4 l0 = acc[ai][0][m][0], l1 = acc[ai][0][m][1];
;                 u32x4 w; w.x = cvt_pk_bf16(l0[0], l0[1]); w.y = cvt_pk_bf16(l0[2], l0[3]); w.z = cvt_pk_bf16(l1[0], l1[1]); w.w = cvt_pk_bf16(l1[2], l1[3]);
;                 *(u32x4*)(LA + (size_t)(row0 + ai * HALF + m * 16) * E + c0) = w; } }
; #pragma unroll
;         for (int ai = 0; ai < 2; ++ai)
; #pragma unroll
;             for (int m = 0; m < 4; ++m) { const size_t off = (size_t)(row0 + ai * HALF + m * 16) * E + c0;
;                 const u32x4 xw = xnext;
;                 if (ai * 4 + m < 7) { const int ai2 = (ai * 4 + m + 1) >> 2, m2 = (ai * 4 + m + 1) & 3; xnext = *(const u32x4*)(XC + (size_t)(row0 + ai2 * HALF + m2 * 16) * E + c0); }
;                 float bt[8];
; #pragma unroll
;                 for (int n = 0; n < 2; ++n)
; #pragma unroll
;                     for (int jp = 0; jp < 2; ++jp) {
;                         const f32x2 z = (f32x2){acc[ai][1][m][n][2 * jp], acc[ai][1][m][n][2 * jp + 1]} * (-1.44269504f);
;                         f32x2 e; e.x = __builtin_amdgcn_exp2f(z.x); e.y = __builtin_amdgcn_exp2f(z.y); e = e + 1.0f;
;                         f32x2 ig; ig.x = __builtin_amdgcn_rcpf(e.x); ig.y = __builtin_amdgcn_rcpf(e.y);
;                         const f32x2 x2 = (f32x2){acc[ai][0][m][n][2 * jp], acc[ai][0][m][n][2 * jp + 1]} * 2.0f;
;                         f32x2 ser = x2 * (1.0f / 120.0f) + (1.0f / 24.0f); ser = ser * x2 + (1.0f / 6.0f); ser = ser * x2 + 0.5f; ser = ser * x2 + 1.0f; ser = ser * (-x2);
	v_exp_f32_e32 v184, v184
	v_exp_f32_e32 v185, v185
	v_exp_f32_e32 v186, v186
	v_exp_f32_e32 v187, v187
	v_pk_add_f32 v[180:181], v[180:181], 1.0 op_sel_hi:[1,0]
	v_pk_add_f32 v[182:183], v[182:183], 1.0 op_sel_hi:[1,0]
	v_pk_add_f32 v[184:185], v[184:185], 1.0 op_sel_hi:[1,0]
	v_pk_add_f32 v[186:187], v[186:187], 1.0 op_sel_hi:[1,0]
	v_rcp_f32_e32 v180, v180
	v_rcp_f32_e32 v181, v181
	v_rcp_f32_e32 v182, v182
	v_rcp_f32_e32 v183, v183
	v_rcp_f32_e32 v184, v184
	v_rcp_f32_e32 v185, v185
	v_rcp_f32_e32 v186, v186
	v_rcp_f32_e32 v187, v187
	v_pk_mul_f32 v[90:91], v[180:181], v[228:229]
	v_pk_mul_f32 v[92:93], v[182:183], v[230:231]
	v_pk_mul_f32 v[86:87], v[184:185], v[232:233]
	v_pk_mul_f32 v[88:89], v[186:187], v[234:235]
	v_min3_f32 v238, v238, v90, v91
	v_min3_f32 v238, v238, v92, v93
	v_min3_f32 v238, v238, v86, v87
	v_min3_f32 v238, v238, v88, v89
	v_cvt_pk_bf16_f32 v208, v90, v91
	v_cvt_pk_bf16_f32 v209, v92, v93
	v_cvt_pk_bf16_f32 v210, v86, v87
	v_cvt_pk_bf16_f32 v211, v88, v89
	global_store_dwordx4 v178, v[208:211], s[8:9]
	v_pk_mul_f32 v[180:181], v[74:75], s[74:75] op_sel_hi:[1,0]
	v_pk_mul_f32 v[182:183], v[76:77], s[74:75] op_sel_hi:[1,0]
	v_pk_mul_f32 v[184:185], v[70:71], s[74:75] op_sel_hi:[1,0]
	v_pk_mul_f32 v[186:187], v[72:73], s[74:75] op_sel_hi:[1,0]
	v_exp_f32_e32 v180, v180
	v_exp_f32_e32 v181, v181
	v_exp_f32_e32 v182, v182
	v_exp_f32_e32 v183, v183
	v_exp_f32_e32 v184, v184
	v_exp_f32_e32 v185, v185
	v_exp_f32_e32 v186, v186
	v_exp_f32_e32 v187, v187
	v_pk_add_f32 v[180:181], v[180:181], 1.0 op_sel_hi:[1,0]
	v_pk_add_f32 v[182:183], v[182:183], 1.0 op_sel_hi:[1,0]
	v_pk_add_f32 v[184:185], v[184:185], 1.0 op_sel_hi:[1,0]
	v_pk_add_f32 v[186:187], v[186:187], 1.0 op_sel_hi:[1,0]
	v_rcp_f32_e32 v180, v180
	v_rcp_f32_e32 v181, v181
	v_rcp_f32_e32 v182, v182
	v_rcp_f32_e32 v183, v183
	v_rcp_f32_e32 v184, v184
	v_rcp_f32_e32 v185, v185
	v_rcp_f32_e32 v186, v186
	v_rcp_f32_e32 v187, v187
	v_pk_mul_f32 v[74:75], v[180:181], v[228:229]
	v_pk_mul_f32 v[76:77], v[182:183], v[230:231]
	v_pk_mul_f32 v[70:71], v[184:185], v[232:233]
	v_pk_mul_f32 v[72:73], v[186:187], v[234:235]
	v_min3_f32 v238, v238, v74, v75
	v_min3_f32 v238, v238, v76, v77
	v_min3_f32 v238, v238, v70, v71
	v_min3_f32 v238, v238, v72, v73
	v_cvt_pk_bf16_f32 v212, v74, v75
	v_cvt_pk_bf16_f32 v213, v76, v77
	v_cvt_pk_bf16_f32 v214, v70, v71
	v_cvt_pk_bf16_f32 v215, v72, v73
	global_store_dwordx4 v179, v[212:215], s[8:9]
	v_cmp_ge_f32_e32 vcc, s13, v238
	s_nop 4
	s_cbranch_vccnz .Lgate_epi_general
	v_pk_mul_f32 v[180:181], v[58:59], s[74:75] op_sel_hi:[1,0]
	v_pk_mul_f32 v[182:183], v[60:61], s[74:75] op_sel_hi:[1,0]
	v_pk_mul_f32 v[184:185], v[66:67], s[74:75] op_sel_hi:[1,0]
	v_pk_mul_f32 v[186:187], v[68:69], s[74:75] op_sel_hi:[1,0]
	v_exp_f32_e32 v180, v180
	v_exp_f32_e32 v181, v181
	v_exp_f32_e32 v182, v182
	v_exp_f32_e32 v183, v183
	v_exp_f32_e32 v184, v184
	v_exp_f32_e32 v185, v185
	v_exp_f32_e32 v186, v186
	v_exp_f32_e32 v187, v187
	v_pk_fma_f32 v[188:189], v[204:205], s[26:27], v[236:237] op_sel_hi:[1,0,0]
	v_pk_fma_f32 v[190:191], v[206:207], s[26:27], v[236:237] op_sel_hi:[1,0,0]
	v_pk_fma_f32 v[192:193], v[220:221], s[26:27], v[236:237] op_sel_hi:[1,0,0]
	v_pk_fma_f32 v[194:195], v[222:223], s[26:27], v[236:237] op_sel_hi:[1,0,0]
	v_pk_add_f32 v[180:181], v[180:181], 1.0 op_sel_hi:[1,0]
	v_pk_add_f32 v[182:183], v[182:183], 1.0 op_sel_hi:[1,0]
	v_pk_add_f32 v[184:185], v[184:185], 1.0 op_sel_hi:[1,0]
	v_pk_add_f32 v[186:187], v[186:187], 1.0 op_sel_hi:[1,0]
	v_rcp_f32_e32 v180, v180
	v_rcp_f32_e32 v181, v181
	v_rcp_f32_e32 v182, v182
	v_rcp_f32_e32 v183, v183
	v_rcp_f32_e32 v184, v184
	v_rcp_f32_e32 v185, v185
	v_rcp_f32_e32 v186, v186
	v_rcp_f32_e32 v187, v187
	v_pk_fma_f32 v[188:189], v[204:205], v[188:189], s[22:23] op_sel_hi:[1,1,0]
	v_pk_fma_f32 v[190:191], v[206:207], v[190:191], s[22:23] op_sel_hi:[1,1,0]
	v_pk_fma_f32 v[192:193], v[220:221], v[192:193], s[22:23] op_sel_hi:[1,1,0]
	v_pk_fma_f32 v[194:195], v[222:223], v[194:195], s[22:23] op_sel_hi:[1,1,0]
	v_pk_fma_f32 v[188:189], v[204:205], v[188:189], -2.0 op_sel_hi:[1,1,0]
	v_pk_fma_f32 v[190:191], v[206:207], v[190:191], -2.0 op_sel_hi:[1,1,0]
	v_pk_fma_f32 v[192:193], v[220:221], v[192:193], -2.0 op_sel_hi:[1,1,0]
	v_pk_fma_f32 v[194:195], v[222:223], v[194:195], -2.0 op_sel_hi:[1,1,0]
	v_pk_fma_f32 v[188:189], v[204:205], v[188:189], -2.0 op_sel_hi:[1,1,0]
	v_pk_fma_f32 v[190:191], v[206:207], v[190:191], -2.0 op_sel_hi:[1,1,0]
	v_pk_fma_f32 v[192:193], v[220:221], v[192:193], -2.0 op_sel_hi:[1,1,0]
	v_pk_fma_f32 v[194:195], v[222:223], v[194:195], -2.0 op_sel_hi:[1,1,0]
	v_pk_mul_f32 v[188:189], v[204:205], v[188:189]
	v_pk_mul_f32 v[190:191], v[206:207], v[190:191]
	v_pk_mul_f32 v[192:193], v[220:221], v[192:193]
	v_pk_mul_f32 v[194:195], v[222:223], v[194:195]
	v_sqrt_f32_e32 v188, v188
	v_sqrt_f32_e32 v189, v189
	v_sqrt_f32_e32 v190, v190
	v_sqrt_f32_e32 v191, v191
	v_sqrt_f32_e32 v192, v192
	v_sqrt_f32_e32 v193, v193
	v_sqrt_f32_e32 v194, v194
	v_sqrt_f32_e32 v195, v195
	s_waitcnt vmcnt(15)
; __device__ __forceinline__ unsigned cvt_pk_bf16(float lo, float hi) { unsigned r; asm volatile("v_cvt_pk_bf16_f32 %0, %1, %2" : "=v"(r) : "v"(lo), "v"(hi)); return r; }
;     __device__ __forceinline__ void operator()(AccMut acc, const Unit& u, int sw) const {
;     ...
;         for (int ai = 0; ai < 2; ++ai)
; #pragma unroll
;             for (int m = 0; m < 4; ++m) { const size_t off = (size_t)(row0 + ai * HALF + m * 16) * E + c0;
;                 const u32x4 xw = xnext;
;                 if (ai * 4 + m < 7) { const int ai2 = (ai * 4 + m + 1) >> 2, m2 = (ai * 4 + m + 1) & 3; xnext = *(const u32x4*)(XC + (size_t)(row0 + ai2 * HALF + m2 * 16) * E + c0); }
;                 float bt[8];
; #pragma unroll
;                 for (int n = 0; n < 2; ++n)
; #pragma unroll
;                     for (int jp = 0; jp < 2; ++jp) {
;                         const f32x2 z = (f32x2){acc[ai][1][m][n][2 * jp], acc[ai][1][m][n][2 * jp + 1]} * (-1.44269504f);
;                         f32x2 e; e.x = __builtin_amdgcn_exp2f(z.x); e.y = __builtin_amdgcn_exp2f(z.y); e = e + 1.0f;
;                         f32x2 ig; ig.x = __builtin_amdgcn_rcpf(e.x); ig.y = __builtin_amdgcn_rcpf(e.y);
;                         const f32x2 x2 = (f32x2){acc[ai][0][m][n][2 * jp], acc[ai][0][m][n][2 * jp + 1]} * 2.0f;
;                         f32x2 ser = x2 * (1.0f / 120.0f) + (1.0f / 24.0f); ser = ser * x2 + (1.0f / 6.0f); ser = ser * x2 + 0.5f; ser = ser * x2 + 1.0f; ser = ser * (-x2);
;                         f32x2 em = ser;
;                         if (__builtin_expect(__builtin_amdgcn_ballot_w64(x2.x <= -0.25f || x2.y <= -0.25f) != 0ull, 0)) {
;                             em.x = (x2.x > -0.25f) ? ser.x : (1.0f - fexp(x2.x)); em.y = (x2.y > -0.25f) ? ser.y : (1.0f - fexp(x2.y)); }
;                         const unsigned wv = xw[2 * n + jp];
;                         f32x2 sq; sq.x = __builtin_amdgcn_sqrtf(em.x); sq.y = __builtin_amdgcn_sqrtf(em.y);
;                         const f32x2 b2 = sq * ig * (f32x2){bf_lo(wv), bf_hi(wv)};
;                         bt[4 * n + 2 * jp] = b2.x; bt[4 * n + 2 * jp + 1] = b2.y; }
;                 u32x4 w; w.x = cvt_pk_bf16(bt[0], bt[1]); w.y = cvt_pk_bf16(bt[2], bt[3]); w.z = cvt_pk_bf16(bt[4], bt[5]); w.w = cvt_pk_bf16(bt[6], bt[7]);
;                 *(u32x4*)(BT + off) = w; }
	v_lshlrev_b32_e32 v196, 16, v136
	v_and_b32_e32 v197, 0xffff0000, v136
	v_lshlrev_b32_e32 v198, 16, v137
	v_and_b32_e32 v199, 0xffff0000, v137
	v_lshlrev_b32_e32 v200, 16, v138
	v_and_b32_e32 v201, 0xffff0000, v138
	v_lshlrev_b32_e32 v202, 16, v139
	v_and_b32_e32 v203, 0xffff0000, v139
	v_pk_mul_f32 v[188:189], v[188:189], v[180:181]
	v_pk_mul_f32 v[190:191], v[190:191], v[182:183]
	v_pk_mul_f32 v[192:193], v[192:193], v[184:185]
	v_pk_mul_f32 v[194:195], v[194:195], v[186:187]
	v_pk_mul_f32 v[188:189], v[188:189], v[196:197]
	v_pk_mul_f32 v[190:191], v[190:191], v[198:199]
	v_pk_mul_f32 v[192:193], v[192:193], v[200:201]
	v_pk_mul_f32 v[194:195], v[194:195], v[202:203]
	v_cvt_pk_bf16_f32 v208, v188, v189
	v_cvt_pk_bf16_f32 v209, v190, v191
	v_cvt_pk_bf16_f32 v210, v192, v193
	v_cvt_pk_bf16_f32 v211, v194, v195
	global_store_dwordx4 v168, v[208:211], s[10:11]
	v_pk_mul_f32 v[180:181], v[50:51], s[74:75] op_sel_hi:[1,0]
	v_pk_mul_f32 v[182:183], v[52:53], s[74:75] op_sel_hi:[1,0]
	v_pk_mul_f32 v[184:185], v[54:55], s[74:75] op_sel_hi:[1,0]
	v_pk_mul_f32 v[186:187], v[56:57], s[74:75] op_sel_hi:[1,0]
	v_exp_f32_e32 v180, v180
	v_exp_f32_e32 v181, v181
	v_exp_f32_e32 v182, v182
	v_exp_f32_e32 v183, v183
	v_exp_f32_e32 v184, v184
	v_exp_f32_e32 v185, v185
	v_exp_f32_e32 v186, v186
	v_exp_f32_e32 v187, v187
	v_pk_fma_f32 v[188:189], v[224:225], s[26:27], v[236:237] op_sel_hi:[1,0,0]
	v_pk_fma_f32 v[190:191], v[226:227], s[26:27], v[236:237] op_sel_hi:[1,0,0]
	v_pk_fma_f32 v[192:193], v[126:127], s[26:27], v[236:237] op_sel_hi:[1,0,0]
	v_pk_fma_f32 v[194:195], v[128:129], s[26:27], v[236:237] op_sel_hi:[1,0,0]
	v_pk_add_f32 v[180:181], v[180:181], 1.0 op_sel_hi:[1,0]
	v_pk_add_f32 v[182:183], v[182:183], 1.0 op_sel_hi:[1,0]
	v_pk_add_f32 v[184:185], v[184:185], 1.0 op_sel_hi:[1,0]
	v_pk_add_f32 v[186:187], v[186:187], 1.0 op_sel_hi:[1,0]
	v_rcp_f32_e32 v180, v180
	v_rcp_f32_e32 v181, v181
	v_rcp_f32_e32 v182, v182
	v_rcp_f32_e32 v183, v183
	v_rcp_f32_e32 v184, v184
	v_rcp_f32_e32 v185, v185
	v_rcp_f32_e32 v186, v186
	v_rcp_f32_e32 v187, v187
	v_pk_fma_f32 v[188:189], v[224:225], v[188:189], s[22:23] op_sel_hi:[1,1,0]
	v_pk_fma_f32 v[190:191], v[226:227], v[190:191], s[22:23] op_sel_hi:[1,1,0]
	v_pk_fma_f32 v[192:193], v[126:127], v[192:193], s[22:23] op_sel_hi:[1,1,0]
	v_pk_fma_f32 v[194:195], v[128:129], v[194:195], s[22:23] op_sel_hi:[1,1,0]
	v_pk_fma_f32 v[188:189], v[224:225], v[188:189], -2.0 op_sel_hi:[1,1,0]
	v_pk_fma_f32 v[190:191], v[226:227], v[190:191], -2.0 op_sel_hi:[1,1,0]
	v_pk_fma_f32 v[192:193], v[126:127], v[192:193], -2.0 op_sel_hi:[1,1,0]
	v_pk_fma_f32 v[194:195], v[128:129], v[194:195], -2.0 op_sel_hi:[1,1,0]
	v_pk_fma_f32 v[188:189], v[224:225], v[188:189], -2.0 op_sel_hi:[1,1,0]
	v_pk_fma_f32 v[190:191], v[226:227], v[190:191], -2.0 op_sel_hi:[1,1,0]
	v_pk_fma_f32 v[192:193], v[126:127], v[192:193], -2.0 op_sel_hi:[1,1,0]
	v_pk_fma_f32 v[194:195], v[128:129], v[194:195], -2.0 op_sel_hi:[1,1,0]
	v_pk_mul_f32 v[188:189], v[224:225], v[188:189]
	v_pk_mul_f32 v[190:191], v[226:227], v[190:191]
	v_pk_mul_f32 v[192:193], v[126:127], v[192:193]
	v_pk_mul_f32 v[194:195], v[128:129], v[194:195]
	v_sqrt_f32_e32 v188, v188
	v_sqrt_f32_e32 v189, v189
	v_sqrt_f32_e32 v190, v190
	v_sqrt_f32_e32 v191, v191
	v_sqrt_f32_e32 v192, v192
	v_sqrt_f32_e32 v193, v193
	v_sqrt_f32_e32 v194, v194
	v_sqrt_f32_e32 v195, v195
	s_waitcnt vmcnt(15)
	v_lshlrev_b32_e32 v196, 16, v140
	v_and_b32_e32 v197, 0xffff0000, v140
	v_lshlrev_b32_e32 v198, 16, v141
	v_and_b32_e32 v199, 0xffff0000, v141
	v_lshlrev_b32_e32 v200, 16, v142
	v_and_b32_e32 v201, 0xffff0000, v142
	v_lshlrev_b32_e32 v202, 16, v143
	v_and_b32_e32 v203, 0xffff0000, v143
	v_pk_mul_f32 v[188:189], v[188:189], v[180:181]
	v_pk_mul_f32 v[190:191], v[190:191], v[182:183]
	v_pk_mul_f32 v[192:193], v[192:193], v[184:185]
	v_pk_mul_f32 v[194:195], v[194:195], v[186:187]
	v_pk_mul_f32 v[188:189], v[188:189], v[196:197]
	v_pk_mul_f32 v[190:191], v[190:191], v[198:199]
	v_pk_mul_f32 v[192:193], v[192:193], v[200:201]
	v_pk_mul_f32 v[194:195], v[194:195], v[202:203]
	v_cvt_pk_bf16_f32 v212, v188, v189
	v_cvt_pk_bf16_f32 v213, v190, v191
	v_cvt_pk_bf16_f32 v214, v192, v193
	v_cvt_pk_bf16_f32 v215, v194, v195
	global_store_dwordx4 v169, v[212:215], s[10:11]
	v_pk_mul_f32 v[180:181], v[42:43], s[74:75] op_sel_hi:[1,0]
	v_pk_mul_f32 v[182:183], v[44:45], s[74:75] op_sel_hi:[1,0]
	v_pk_mul_f32 v[184:185], v[46:47], s[74:75] op_sel_hi:[1,0]
	v_pk_mul_f32 v[186:187], v[48:49], s[74:75] op_sel_hi:[1,0]
	v_exp_f32_e32 v180, v180
	v_exp_f32_e32 v181, v181
	v_exp_f32_e32 v182, v182
	v_exp_f32_e32 v183, v183
	v_exp_f32_e32 v184, v184
	v_exp_f32_e32 v185, v185
	v_exp_f32_e32 v186, v186
	v_exp_f32_e32 v187, v187
	v_pk_fma_f32 v[188:189], v[122:123], s[26:27], v[236:237] op_sel_hi:[1,0,0]
	v_pk_fma_f32 v[190:191], v[124:125], s[26:27], v[236:237] op_sel_hi:[1,0,0]
	v_pk_fma_f32 v[192:193], v[118:119], s[26:27], v[236:237] op_sel_hi:[1,0,0]
	v_pk_fma_f32 v[194:195], v[120:121], s[26:27], v[236:237] op_sel_hi:[1,0,0]
	v_pk_add_f32 v[180:181], v[180:181], 1.0 op_sel_hi:[1,0]
	v_pk_add_f32 v[182:183], v[182:183], 1.0 op_sel_hi:[1,0]
	v_pk_add_f32 v[184:185], v[184:185], 1.0 op_sel_hi:[1,0]
	v_pk_add_f32 v[186:187], v[186:187], 1.0 op_sel_hi:[1,0]
	v_rcp_f32_e32 v180, v180
	v_rcp_f32_e32 v181, v181
	v_rcp_f32_e32 v182, v182
	v_rcp_f32_e32 v183, v183
	v_rcp_f32_e32 v184, v184
	v_rcp_f32_e32 v185, v185
	v_rcp_f32_e32 v186, v186
	v_rcp_f32_e32 v187, v187
	v_pk_fma_f32 v[188:189], v[122:123], v[188:189], s[22:23] op_sel_hi:[1,1,0]
	v_pk_fma_f32 v[190:191], v[124:125], v[190:191], s[22:23] op_sel_hi:[1,1,0]
	v_pk_fma_f32 v[192:193], v[118:119], v[192:193], s[22:23] op_sel_hi:[1,1,0]
	v_pk_fma_f32 v[194:195], v[120:121], v[194:195], s[22:23] op_sel_hi:[1,1,0]
	v_pk_fma_f32 v[188:189], v[122:123], v[188:189], -2.0 op_sel_hi:[1,1,0]
	v_pk_fma_f32 v[190:191], v[124:125], v[190:191], -2.0 op_sel_hi:[1,1,0]
	v_pk_fma_f32 v[192:193], v[118:119], v[192:193], -2.0 op_sel_hi:[1,1,0]
	v_pk_fma_f32 v[194:195], v[120:121], v[194:195], -2.0 op_sel_hi:[1,1,0]
	v_pk_fma_f32 v[188:189], v[122:123], v[188:189], -2.0 op_sel_hi:[1,1,0]
	v_pk_fma_f32 v[190:191], v[124:125], v[190:191], -2.0 op_sel_hi:[1,1,0]
	v_pk_fma_f32 v[192:193], v[118:119], v[192:193], -2.0 op_sel_hi:[1,1,0]
	v_pk_fma_f32 v[194:195], v[120:121], v[194:195], -2.0 op_sel_hi:[1,1,0]
	v_pk_mul_f32 v[188:189], v[122:123], v[188:189]
	v_pk_mul_f32 v[190:191], v[124:125], v[190:191]
	v_pk_mul_f32 v[192:193], v[118:119], v[192:193]
	v_pk_mul_f32 v[194:195], v[120:121], v[194:195]
	v_sqrt_f32_e32 v188, v188
	v_sqrt_f32_e32 v189, v189
	v_sqrt_f32_e32 v190, v190
	v_sqrt_f32_e32 v191, v191
	v_sqrt_f32_e32 v192, v192
	v_sqrt_f32_e32 v193, v193
	v_sqrt_f32_e32 v194, v194
	v_sqrt_f32_e32 v195, v195
	s_waitcnt vmcnt(15)
; __device__ __forceinline__ unsigned cvt_pk_bf16(float lo, float hi) { unsigned r; asm volatile("v_cvt_pk_bf16_f32 %0, %1, %2" : "=v"(r) : "v"(lo), "v"(hi)); return r; }
;     __device__ __forceinline__ void operator()(AccMut acc, const Unit& u, int sw) const {
;     ...
;         for (int ai = 0; ai < 2; ++ai)
; #pragma unroll
;             for (int m = 0; m < 4; ++m) { const size_t off = (size_t)(row0 + ai * HALF + m * 16) * E + c0;
;                 const u32x4 xw = xnext;
;                 if (ai * 4 + m < 7) { const int ai2 = (ai * 4 + m + 1) >> 2, m2 = (ai * 4 + m + 1) & 3; xnext = *(const u32x4*)(XC + (size_t)(row0 + ai2 * HALF + m2 * 16) * E + c0); }
;                 float bt[8];
; #pragma unroll
;                 for (int n = 0; n < 2; ++n)
; #pragma unroll
;                     for (int jp = 0; jp < 2; ++jp) {
;                         const f32x2 z = (f32x2){acc[ai][1][m][n][2 * jp], acc[ai][1][m][n][2 * jp + 1]} * (-1.44269504f);
;                         f32x2 e; e.x = __builtin_amdgcn_exp2f(z.x); e.y = __builtin_amdgcn_exp2f(z.y); e = e + 1.0f;
;                         f32x2 ig; ig.x = __builtin_amdgcn_rcpf(e.x); ig.y = __builtin_amdgcn_rcpf(e.y);
;                         const f32x2 x2 = (f32x2){acc[ai][0][m][n][2 * jp], acc[ai][0][m][n][2 * jp + 1]} * 2.0f;
;                         f32x2 ser = x2 * (1.0f / 120.0f) + (1.0f / 24.0f); ser = ser * x2 + (1.0f / 6.0f); ser = ser * x2 + 0.5f; ser = ser * x2 + 1.0f; ser = ser * (-x2);
;                         f32x2 em = ser;
;                         if (__builtin_expect(__builtin_amdgcn_ballot_w64(x2.x <= -0.25f || x2.y <= -0.25f) != 0ull, 0)) {
;                             em.x = (x2.x > -0.25f) ? ser.x : (1.0f - fexp(x2.x)); em.y = (x2.y > -0.25f) ? ser.y : (1.0f - fexp(x2.y)); }
;                         const unsigned wv = xw[2 * n + jp];
;                         f32x2 sq; sq.x = __builtin_amdgcn_sqrtf(em.x); sq.y = __builtin_amdgcn_sqrtf(em.y);
;                         const f32x2 b2 = sq * ig * (f32x2){bf_lo(wv), bf_hi(wv)};
;                         bt[4 * n + 2 * jp] = b2.x; bt[4 * n + 2 * jp + 1] = b2.y; }
;                 u32x4 w; w.x = cvt_pk_bf16(bt[0], bt[1]); w.y = cvt_pk_bf16(bt[2], bt[3]); w.z = cvt_pk_bf16(bt[4], bt[5]); w.w = cvt_pk_bf16(bt[6], bt[7]);
;                 *(u32x4*)(BT + off) = w; }
	v_lshlrev_b32_e32 v196, 16, v144
	v_and_b32_e32 v197, 0xffff0000, v144
	v_lshlrev_b32_e32 v198, 16, v145
	v_and_b32_e32 v199, 0xffff0000, v145
	v_lshlrev_b32_e32 v200, 16, v146
	v_and_b32_e32 v201, 0xffff0000, v146
	v_lshlrev_b32_e32 v202, 16, v147
	v_and_b32_e32 v203, 0xffff0000, v147
	v_pk_mul_f32 v[188:189], v[188:189], v[180:181]
	v_pk_mul_f32 v[190:191], v[190:191], v[182:183]
	v_pk_mul_f32 v[192:193], v[192:193], v[184:185]
	v_pk_mul_f32 v[194:195], v[194:195], v[186:187]
	v_pk_mul_f32 v[188:189], v[188:189], v[196:197]
	v_pk_mul_f32 v[190:191], v[190:191], v[198:199]
	v_pk_mul_f32 v[192:193], v[192:193], v[200:201]
	v_pk_mul_f32 v[194:195], v[194:195], v[202:203]
	v_cvt_pk_bf16_f32 v208, v188, v189
	v_cvt_pk_bf16_f32 v209, v190, v191
	v_cvt_pk_bf16_f32 v210, v192, v193
	v_cvt_pk_bf16_f32 v211, v194, v195
	global_store_dwordx4 v172, v[208:211], s[10:11]
	v_pk_mul_f32 v[180:181], v[34:35], s[74:75] op_sel_hi:[1,0]
	v_pk_mul_f32 v[182:183], v[36:37], s[74:75] op_sel_hi:[1,0]
	v_pk_mul_f32 v[184:185], v[38:39], s[74:75] op_sel_hi:[1,0]
	v_pk_mul_f32 v[186:187], v[40:41], s[74:75] op_sel_hi:[1,0]
	v_exp_f32_e32 v180, v180
	v_exp_f32_e32 v181, v181
	v_exp_f32_e32 v182, v182
	v_exp_f32_e32 v183, v183
	v_exp_f32_e32 v184, v184
	v_exp_f32_e32 v185, v185
	v_exp_f32_e32 v186, v186
	v_exp_f32_e32 v187, v187
	v_pk_fma_f32 v[188:189], v[114:115], s[26:27], v[236:237] op_sel_hi:[1,0,0]
	v_pk_fma_f32 v[190:191], v[116:117], s[26:27], v[236:237] op_sel_hi:[1,0,0]
	v_pk_fma_f32 v[192:193], v[106:107], s[26:27], v[236:237] op_sel_hi:[1,0,0]
	v_pk_fma_f32 v[194:195], v[108:109], s[26:27], v[236:237] op_sel_hi:[1,0,0]
	v_pk_add_f32 v[180:181], v[180:181], 1.0 op_sel_hi:[1,0]
	v_pk_add_f32 v[182:183], v[182:183], 1.0 op_sel_hi:[1,0]
	v_pk_add_f32 v[184:185], v[184:185], 1.0 op_sel_hi:[1,0]
	v_pk_add_f32 v[186:187], v[186:187], 1.0 op_sel_hi:[1,0]
	v_rcp_f32_e32 v180, v180
	v_rcp_f32_e32 v181, v181
	v_rcp_f32_e32 v182, v182
	v_rcp_f32_e32 v183, v183
	v_rcp_f32_e32 v184, v184
	v_rcp_f32_e32 v185, v185
	v_rcp_f32_e32 v186, v186
	v_rcp_f32_e32 v187, v187
	v_pk_fma_f32 v[188:189], v[114:115], v[188:189], s[22:23] op_sel_hi:[1,1,0]
	v_pk_fma_f32 v[190:191], v[116:117], v[190:191], s[22:23] op_sel_hi:[1,1,0]
	v_pk_fma_f32 v[192:193], v[106:107], v[192:193], s[22:23] op_sel_hi:[1,1,0]
	v_pk_fma_f32 v[194:195], v[108:109], v[194:195], s[22:23] op_sel_hi:[1,1,0]
	v_pk_fma_f32 v[188:189], v[114:115], v[188:189], -2.0 op_sel_hi:[1,1,0]
	v_pk_fma_f32 v[190:191], v[116:117], v[190:191], -2.0 op_sel_hi:[1,1,0]
	v_pk_fma_f32 v[192:193], v[106:107], v[192:193], -2.0 op_sel_hi:[1,1,0]
	v_pk_fma_f32 v[194:195], v[108:109], v[194:195], -2.0 op_sel_hi:[1,1,0]
	v_pk_fma_f32 v[188:189], v[114:115], v[188:189], -2.0 op_sel_hi:[1,1,0]
	v_pk_fma_f32 v[190:191], v[116:117], v[190:191], -2.0 op_sel_hi:[1,1,0]
	v_pk_fma_f32 v[192:193], v[106:107], v[192:193], -2.0 op_sel_hi:[1,1,0]
	v_pk_fma_f32 v[194:195], v[108:109], v[194:195], -2.0 op_sel_hi:[1,1,0]
	v_pk_mul_f32 v[188:189], v[114:115], v[188:189]
	v_pk_mul_f32 v[190:191], v[116:117], v[190:191]
	v_pk_mul_f32 v[192:193], v[106:107], v[192:193]
	v_pk_mul_f32 v[194:195], v[108:109], v[194:195]
	v_sqrt_f32_e32 v188, v188
	v_sqrt_f32_e32 v189, v189
	v_sqrt_f32_e32 v190, v190
	v_sqrt_f32_e32 v191, v191
	v_sqrt_f32_e32 v192, v192
	v_sqrt_f32_e32 v193, v193
	v_sqrt_f32_e32 v194, v194
	v_sqrt_f32_e32 v195, v195
	s_waitcnt vmcnt(15)
	v_lshlrev_b32_e32 v196, 16, v148
	v_and_b32_e32 v197, 0xffff0000, v148
	v_lshlrev_b32_e32 v198, 16, v149
	v_and_b32_e32 v199, 0xffff0000, v149
	v_lshlrev_b32_e32 v200, 16, v150
	v_and_b32_e32 v201, 0xffff0000, v150
	v_lshlrev_b32_e32 v202, 16, v151
	v_and_b32_e32 v203, 0xffff0000, v151
	v_pk_mul_f32 v[188:189], v[188:189], v[180:181]
	v_pk_mul_f32 v[190:191], v[190:191], v[182:183]
	v_pk_mul_f32 v[192:193], v[192:193], v[184:185]
	v_pk_mul_f32 v[194:195], v[194:195], v[186:187]
	v_pk_mul_f32 v[188:189], v[188:189], v[196:197]
	v_pk_mul_f32 v[190:191], v[190:191], v[198:199]
	v_pk_mul_f32 v[192:193], v[192:193], v[200:201]
	v_pk_mul_f32 v[194:195], v[194:195], v[202:203]
	v_cvt_pk_bf16_f32 v212, v188, v189
	v_cvt_pk_bf16_f32 v213, v190, v191
	v_cvt_pk_bf16_f32 v214, v192, v193
	v_cvt_pk_bf16_f32 v215, v194, v195
	global_store_dwordx4 v173, v[212:215], s[10:11]
	v_pk_mul_f32 v[180:181], v[26:27], s[74:75] op_sel_hi:[1,0]
	v_pk_mul_f32 v[182:183], v[28:29], s[74:75] op_sel_hi:[1,0]
	v_pk_mul_f32 v[184:185], v[30:31], s[74:75] op_sel_hi:[1,0]
	v_pk_mul_f32 v[186:187], v[32:33], s[74:75] op_sel_hi:[1,0]
	v_exp_f32_e32 v180, v180
	v_exp_f32_e32 v181, v181
	v_exp_f32_e32 v182, v182
	v_exp_f32_e32 v183, v183
	v_exp_f32_e32 v184, v184
	v_exp_f32_e32 v185, v185
	v_exp_f32_e32 v186, v186
	v_exp_f32_e32 v187, v187
	v_pk_fma_f32 v[188:189], v[110:111], s[26:27], v[236:237] op_sel_hi:[1,0,0]
	v_pk_fma_f32 v[190:191], v[112:113], s[26:27], v[236:237] op_sel_hi:[1,0,0]
	v_pk_fma_f32 v[192:193], v[102:103], s[26:27], v[236:237] op_sel_hi:[1,0,0]
	v_pk_fma_f32 v[194:195], v[104:105], s[26:27], v[236:237] op_sel_hi:[1,0,0]
	v_pk_add_f32 v[180:181], v[180:181], 1.0 op_sel_hi:[1,0]
	v_pk_add_f32 v[182:183], v[182:183], 1.0 op_sel_hi:[1,0]
	v_pk_add_f32 v[184:185], v[184:185], 1.0 op_sel_hi:[1,0]
	v_pk_add_f32 v[186:187], v[186:187], 1.0 op_sel_hi:[1,0]
	v_rcp_f32_e32 v180, v180
	v_rcp_f32_e32 v181, v181
	v_rcp_f32_e32 v182, v182
	v_rcp_f32_e32 v183, v183
	v_rcp_f32_e32 v184, v184
	v_rcp_f32_e32 v185, v185
	v_rcp_f32_e32 v186, v186
	v_rcp_f32_e32 v187, v187
	v_pk_fma_f32 v[188:189], v[110:111], v[188:189], s[22:23] op_sel_hi:[1,1,0]
	v_pk_fma_f32 v[190:191], v[112:113], v[190:191], s[22:23] op_sel_hi:[1,1,0]
	v_pk_fma_f32 v[192:193], v[102:103], v[192:193], s[22:23] op_sel_hi:[1,1,0]
	v_pk_fma_f32 v[194:195], v[104:105], v[194:195], s[22:23] op_sel_hi:[1,1,0]
	v_pk_fma_f32 v[188:189], v[110:111], v[188:189], -2.0 op_sel_hi:[1,1,0]
	v_pk_fma_f32 v[190:191], v[112:113], v[190:191], -2.0 op_sel_hi:[1,1,0]
	v_pk_fma_f32 v[192:193], v[102:103], v[192:193], -2.0 op_sel_hi:[1,1,0]
	v_pk_fma_f32 v[194:195], v[104:105], v[194:195], -2.0 op_sel_hi:[1,1,0]
	v_pk_fma_f32 v[188:189], v[110:111], v[188:189], -2.0 op_sel_hi:[1,1,0]
	v_pk_fma_f32 v[190:191], v[112:113], v[190:191], -2.0 op_sel_hi:[1,1,0]
	v_pk_fma_f32 v[192:193], v[102:103], v[192:193], -2.0 op_sel_hi:[1,1,0]
	v_pk_fma_f32 v[194:195], v[104:105], v[194:195], -2.0 op_sel_hi:[1,1,0]
	v_pk_mul_f32 v[188:189], v[110:111], v[188:189]
	v_pk_mul_f32 v[190:191], v[112:113], v[190:191]
	v_pk_mul_f32 v[192:193], v[102:103], v[192:193]
	v_pk_mul_f32 v[194:195], v[104:105], v[194:195]
	v_sqrt_f32_e32 v188, v188
	v_sqrt_f32_e32 v189, v189
	v_sqrt_f32_e32 v190, v190
	v_sqrt_f32_e32 v191, v191
	v_sqrt_f32_e32 v192, v192
	v_sqrt_f32_e32 v193, v193
	v_sqrt_f32_e32 v194, v194
	v_sqrt_f32_e32 v195, v195
	s_waitcnt vmcnt(15)
; __device__ __forceinline__ unsigned cvt_pk_bf16(float lo, float hi) { unsigned r; asm volatile("v_cvt_pk_bf16_f32 %0, %1, %2" : "=v"(r) : "v"(lo), "v"(hi)); return r; }
;     __device__ __forceinline__ void operator()(AccMut acc, const Unit& u, int sw) const {
;     ...
;         for (int ai = 0; ai < 2; ++ai)
; #pragma unroll
;             for (int m = 0; m < 4; ++m) { const size_t off = (size_t)(row0 + ai * HALF + m * 16) * E + c0;
;                 const u32x4 xw = xnext;
;                 if (ai * 4 + m < 7) { const int ai2 = (ai * 4 + m + 1) >> 2, m2 = (ai * 4 + m + 1) & 3; xnext = *(const u32x4*)(XC + (size_t)(row0 + ai2 * HALF + m2 * 16) * E + c0); }
;                 float bt[8];
; #pragma unroll
;                 for (int n = 0; n < 2; ++n)
; #pragma unroll
;                     for (int jp = 0; jp < 2; ++jp) {
;                         const f32x2 z = (f32x2){acc[ai][1][m][n][2 * jp], acc[ai][1][m][n][2 * jp + 1]} * (-1.44269504f);
;                         f32x2 e; e.x = __builtin_amdgcn_exp2f(z.x); e.y = __builtin_amdgcn_exp2f(z.y); e = e + 1.0f;
;                         f32x2 ig; ig.x = __builtin_amdgcn_rcpf(e.x); ig.y = __builtin_amdgcn_rcpf(e.y);
;                         const f32x2 x2 = (f32x2){acc[ai][0][m][n][2 * jp], acc[ai][0][m][n][2 * jp + 1]} * 2.0f;
;                         f32x2 ser = x2 * (1.0f / 120.0f) + (1.0f / 24.0f); ser = ser * x2 + (1.0f / 6.0f); ser = ser * x2 + 0.5f; ser = ser * x2 + 1.0f; ser = ser * (-x2);
;                         f32x2 em = ser;
;                         if (__builtin_expect(__builtin_amdgcn_ballot_w64(x2.x <= -0.25f || x2.y <= -0.25f) != 0ull, 0)) {
;                             em.x = (x2.x > -0.25f) ? ser.x : (1.0f - fexp(x2.x)); em.y = (x2.y > -0.25f) ? ser.y : (1.0f - fexp(x2.y)); }
;                         const unsigned wv = xw[2 * n + jp];
;                         f32x2 sq; sq.x = __builtin_amdgcn_sqrtf(em.x); sq.y = __builtin_amdgcn_sqrtf(em.y);
;                         const f32x2 b2 = sq * ig * (f32x2){bf_lo(wv), bf_hi(wv)};
;                         bt[4 * n + 2 * jp] = b2.x; bt[4 * n + 2 * jp + 1] = b2.y; }
;                 u32x4 w; w.x = cvt_pk_bf16(bt[0], bt[1]); w.y = cvt_pk_bf16(bt[2], bt[3]); w.z = cvt_pk_bf16(bt[4], bt[5]); w.w = cvt_pk_bf16(bt[6], bt[7]);
;                 *(u32x4*)(BT + off) = w; }
	v_lshlrev_b32_e32 v196, 16, v152
	v_and_b32_e32 v197, 0xffff0000, v152
	v_lshlrev_b32_e32 v198, 16, v153
	v_and_b32_e32 v199, 0xffff0000, v153
	v_lshlrev_b32_e32 v200, 16, v154
	v_and_b32_e32 v201, 0xffff0000, v154
	v_lshlrev_b32_e32 v202, 16, v155
	v_and_b32_e32 v203, 0xffff0000, v155
	v_pk_mul_f32 v[188:189], v[188:189], v[180:181]
	v_pk_mul_f32 v[190:191], v[190:191], v[182:183]
	v_pk_mul_f32 v[192:193], v[192:193], v[184:185]
	v_pk_mul_f32 v[194:195], v[194:195], v[186:187]
	v_pk_mul_f32 v[188:189], v[188:189], v[196:197]
	v_pk_mul_f32 v[190:191], v[190:191], v[198:199]
	v_pk_mul_f32 v[192:193], v[192:193], v[200:201]
	v_pk_mul_f32 v[194:195], v[194:195], v[202:203]
	v_cvt_pk_bf16_f32 v208, v188, v189
	v_cvt_pk_bf16_f32 v209, v190, v191
	v_cvt_pk_bf16_f32 v210, v192, v193
	v_cvt_pk_bf16_f32 v211, v194, v195
	global_store_dwordx4 v176, v[208:211], s[10:11]
	v_pk_mul_f32 v[180:181], v[18:19], s[74:75] op_sel_hi:[1,0]
	v_pk_mul_f32 v[182:183], v[20:21], s[74:75] op_sel_hi:[1,0]
	v_pk_mul_f32 v[184:185], v[22:23], s[74:75] op_sel_hi:[1,0]
	v_pk_mul_f32 v[186:187], v[24:25], s[74:75] op_sel_hi:[1,0]
	v_exp_f32_e32 v180, v180
	v_exp_f32_e32 v181, v181
	v_exp_f32_e32 v182, v182
	v_exp_f32_e32 v183, v183
	v_exp_f32_e32 v184, v184
	v_exp_f32_e32 v185, v185
	v_exp_f32_e32 v186, v186
	v_exp_f32_e32 v187, v187
	v_pk_fma_f32 v[188:189], v[98:99], s[26:27], v[236:237] op_sel_hi:[1,0,0]
	v_pk_fma_f32 v[190:191], v[100:101], s[26:27], v[236:237] op_sel_hi:[1,0,0]
	v_pk_fma_f32 v[192:193], v[94:95], s[26:27], v[236:237] op_sel_hi:[1,0,0]
	v_pk_fma_f32 v[194:195], v[96:97], s[26:27], v[236:237] op_sel_hi:[1,0,0]
	v_pk_add_f32 v[180:181], v[180:181], 1.0 op_sel_hi:[1,0]
	v_pk_add_f32 v[182:183], v[182:183], 1.0 op_sel_hi:[1,0]
	v_pk_add_f32 v[184:185], v[184:185], 1.0 op_sel_hi:[1,0]
	v_pk_add_f32 v[186:187], v[186:187], 1.0 op_sel_hi:[1,0]
	v_rcp_f32_e32 v180, v180
	v_rcp_f32_e32 v181, v181
	v_rcp_f32_e32 v182, v182
	v_rcp_f32_e32 v183, v183
	v_rcp_f32_e32 v184, v184
	v_rcp_f32_e32 v185, v185
	v_rcp_f32_e32 v186, v186
	v_rcp_f32_e32 v187, v187
	v_pk_fma_f32 v[188:189], v[98:99], v[188:189], s[22:23] op_sel_hi:[1,1,0]
	v_pk_fma_f32 v[190:191], v[100:101], v[190:191], s[22:23] op_sel_hi:[1,1,0]
	v_pk_fma_f32 v[192:193], v[94:95], v[192:193], s[22:23] op_sel_hi:[1,1,0]
	v_pk_fma_f32 v[194:195], v[96:97], v[194:195], s[22:23] op_sel_hi:[1,1,0]
	v_pk_fma_f32 v[188:189], v[98:99], v[188:189], -2.0 op_sel_hi:[1,1,0]
	v_pk_fma_f32 v[190:191], v[100:101], v[190:191], -2.0 op_sel_hi:[1,1,0]
	v_pk_fma_f32 v[192:193], v[94:95], v[192:193], -2.0 op_sel_hi:[1,1,0]
	v_pk_fma_f32 v[194:195], v[96:97], v[194:195], -2.0 op_sel_hi:[1,1,0]
	v_pk_fma_f32 v[188:189], v[98:99], v[188:189], -2.0 op_sel_hi:[1,1,0]
	v_pk_fma_f32 v[190:191], v[100:101], v[190:191], -2.0 op_sel_hi:[1,1,0]
	v_pk_fma_f32 v[192:193], v[94:95], v[192:193], -2.0 op_sel_hi:[1,1,0]
	v_pk_fma_f32 v[194:195], v[96:97], v[194:195], -2.0 op_sel_hi:[1,1,0]
	v_pk_mul_f32 v[188:189], v[98:99], v[188:189]
	v_pk_mul_f32 v[190:191], v[100:101], v[190:191]
	v_pk_mul_f32 v[192:193], v[94:95], v[192:193]
	v_pk_mul_f32 v[194:195], v[96:97], v[194:195]
	v_sqrt_f32_e32 v188, v188
	v_sqrt_f32_e32 v189, v189
	v_sqrt_f32_e32 v190, v190
	v_sqrt_f32_e32 v191, v191
	v_sqrt_f32_e32 v192, v192
	v_sqrt_f32_e32 v193, v193
	v_sqrt_f32_e32 v194, v194
	v_sqrt_f32_e32 v195, v195
	s_waitcnt vmcnt(15)
	v_lshlrev_b32_e32 v196, 16, v156
	v_and_b32_e32 v197, 0xffff0000, v156
	v_lshlrev_b32_e32 v198, 16, v157
	v_and_b32_e32 v199, 0xffff0000, v157
	v_lshlrev_b32_e32 v200, 16, v158
	v_and_b32_e32 v201, 0xffff0000, v158
	v_lshlrev_b32_e32 v202, 16, v159
	v_and_b32_e32 v203, 0xffff0000, v159
	v_pk_mul_f32 v[188:189], v[188:189], v[180:181]
	v_pk_mul_f32 v[190:191], v[190:191], v[182:183]
	v_pk_mul_f32 v[192:193], v[192:193], v[184:185]
	v_pk_mul_f32 v[194:195], v[194:195], v[186:187]
	v_pk_mul_f32 v[188:189], v[188:189], v[196:197]
	v_pk_mul_f32 v[190:191], v[190:191], v[198:199]
	v_pk_mul_f32 v[192:193], v[192:193], v[200:201]
	v_pk_mul_f32 v[194:195], v[194:195], v[202:203]
	v_cvt_pk_bf16_f32 v212, v188, v189
	v_cvt_pk_bf16_f32 v213, v190, v191
	v_cvt_pk_bf16_f32 v214, v192, v193
	v_cvt_pk_bf16_f32 v215, v194, v195
	global_store_dwordx4 v177, v[212:215], s[10:11]
	v_pk_mul_f32 v[180:181], v[10:11], s[74:75] op_sel_hi:[1,0]
	v_pk_mul_f32 v[182:183], v[12:13], s[74:75] op_sel_hi:[1,0]
	v_pk_mul_f32 v[184:185], v[14:15], s[74:75] op_sel_hi:[1,0]
	v_pk_mul_f32 v[186:187], v[16:17], s[74:75] op_sel_hi:[1,0]
	v_exp_f32_e32 v180, v180
	v_exp_f32_e32 v181, v181
	v_exp_f32_e32 v182, v182
	v_exp_f32_e32 v183, v183
	v_exp_f32_e32 v184, v184
	v_exp_f32_e32 v185, v185
	v_exp_f32_e32 v186, v186
	v_exp_f32_e32 v187, v187
	v_pk_fma_f32 v[188:189], v[90:91], s[26:27], v[236:237] op_sel_hi:[1,0,0]
	v_pk_fma_f32 v[190:191], v[92:93], s[26:27], v[236:237] op_sel_hi:[1,0,0]
	v_pk_fma_f32 v[192:193], v[86:87], s[26:27], v[236:237] op_sel_hi:[1,0,0]
	v_pk_fma_f32 v[194:195], v[88:89], s[26:27], v[236:237] op_sel_hi:[1,0,0]
	v_pk_add_f32 v[180:181], v[180:181], 1.0 op_sel_hi:[1,0]
	v_pk_add_f32 v[182:183], v[182:183], 1.0 op_sel_hi:[1,0]
	v_pk_add_f32 v[184:185], v[184:185], 1.0 op_sel_hi:[1,0]
	v_pk_add_f32 v[186:187], v[186:187], 1.0 op_sel_hi:[1,0]
	v_rcp_f32_e32 v180, v180
	v_rcp_f32_e32 v181, v181
	v_rcp_f32_e32 v182, v182
	v_rcp_f32_e32 v183, v183
	v_rcp_f32_e32 v184, v184
	v_rcp_f32_e32 v185, v185
	v_rcp_f32_e32 v186, v186
	v_rcp_f32_e32 v187, v187
	v_pk_fma_f32 v[188:189], v[90:91], v[188:189], s[22:23] op_sel_hi:[1,1,0]
	v_pk_fma_f32 v[190:191], v[92:93], v[190:191], s[22:23] op_sel_hi:[1,1,0]
	v_pk_fma_f32 v[192:193], v[86:87], v[192:193], s[22:23] op_sel_hi:[1,1,0]
	v_pk_fma_f32 v[194:195], v[88:89], v[194:195], s[22:23] op_sel_hi:[1,1,0]
	v_pk_fma_f32 v[188:189], v[90:91], v[188:189], -2.0 op_sel_hi:[1,1,0]
	v_pk_fma_f32 v[190:191], v[92:93], v[190:191], -2.0 op_sel_hi:[1,1,0]
	v_pk_fma_f32 v[192:193], v[86:87], v[192:193], -2.0 op_sel_hi:[1,1,0]
	v_pk_fma_f32 v[194:195], v[88:89], v[194:195], -2.0 op_sel_hi:[1,1,0]
	v_pk_fma_f32 v[188:189], v[90:91], v[188:189], -2.0 op_sel_hi:[1,1,0]
	v_pk_fma_f32 v[190:191], v[92:93], v[190:191], -2.0 op_sel_hi:[1,1,0]
	v_pk_fma_f32 v[192:193], v[86:87], v[192:193], -2.0 op_sel_hi:[1,1,0]
	v_pk_fma_f32 v[194:195], v[88:89], v[194:195], -2.0 op_sel_hi:[1,1,0]
	v_pk_mul_f32 v[188:189], v[90:91], v[188:189]
	v_pk_mul_f32 v[190:191], v[92:93], v[190:191]
	v_pk_mul_f32 v[192:193], v[86:87], v[192:193]
	v_pk_mul_f32 v[194:195], v[88:89], v[194:195]
	v_sqrt_f32_e32 v188, v188
	v_sqrt_f32_e32 v189, v189
	v_sqrt_f32_e32 v190, v190
	v_sqrt_f32_e32 v191, v191
	v_sqrt_f32_e32 v192, v192
	v_sqrt_f32_e32 v193, v193
	v_sqrt_f32_e32 v194, v194
	v_sqrt_f32_e32 v195, v195
	s_waitcnt vmcnt(15)
;     __device__ __forceinline__ void init(AccMut acc, const Unit& u, int sw) const {
;         const int tid_ = ltid(sw), lane_ = tid_ & 63, wc = sw & 3, fq = lane_ >> 4;
;         const int c0 = u.pn * 128 + wc * 32 + 8 * fq;
; #pragma unroll
;     __device__ __forceinline__ void operator()(AccMut acc, const Unit& u, int sw) const {
;     ...
;         for (int ai = 0; ai < 2; ++ai)
; #pragma unroll
;             for (int m = 0; m < 4; ++m) { const size_t off = (size_t)(row0 + ai * HALF + m * 16) * E + c0;
;                 const u32x4 xw = xnext;
;                 if (ai * 4 + m < 7) { const int ai2 = (ai * 4 + m + 1) >> 2, m2 = (ai * 4 + m + 1) & 3; xnext = *(const u32x4*)(XC + (size_t)(row0 + ai2 * HALF + m2 * 16) * E + c0); }
;                 float bt[8];
; #pragma unroll
;                 for (int n = 0; n < 2; ++n)
; #pragma unroll
;                     for (int jp = 0; jp < 2; ++jp) {
;                         const f32x2 z = (f32x2){acc[ai][1][m][n][2 * jp], acc[ai][1][m][n][2 * jp + 1]} * (-1.44269504f);
;                         f32x2 e; e.x = __builtin_amdgcn_exp2f(z.x); e.y = __builtin_amdgcn_exp2f(z.y); e = e + 1.0f;
;                         f32x2 ig; ig.x = __builtin_amdgcn_rcpf(e.x); ig.y = __builtin_amdgcn_rcpf(e.y);
;                         const f32x2 x2 = (f32x2){acc[ai][0][m][n][2 * jp], acc[ai][0][m][n][2 * jp + 1]} * 2.0f;
;                         f32x2 ser = x2 * (1.0f / 120.0f) + (1.0f / 24.0f); ser = ser * x2 + (1.0f / 6.0f); ser = ser * x2 + 0.5f; ser = ser * x2 + 1.0f; ser = ser * (-x2);
;                         f32x2 em = ser;
;                         if (__builtin_expect(__builtin_amdgcn_ballot_w64(x2.x <= -0.25f || x2.y <= -0.25f) != 0ull, 0)) {
;                             em.x = (x2.x > -0.25f) ? ser.x : (1.0f - fexp(x2.x)); em.y = (x2.y > -0.25f) ? ser.y : (1.0f - fexp(x2.y)); }
;                         const unsigned wv = xw[2 * n + jp];
;                         f32x2 sq; sq.x = __builtin_amdgcn_sqrtf(em.x); sq.y = __builtin_amdgcn_sqrtf(em.y);
;                         const f32x2 b2 = sq * ig * (f32x2){bf_lo(wv), bf_hi(wv)};
;                         bt[4 * n + 2 * jp] = b2.x; bt[4 * n + 2 * jp + 1] = b2.y; }
;                 u32x4 w; w.x = cvt_pk_bf16(bt[0], bt[1]); w.y = cvt_pk_bf16(bt[2], bt[3]); w.z = cvt_pk_bf16(bt[4], bt[5]); w.w = cvt_pk_bf16(bt[6], bt[7]);
;                 *(u32x4*)(BT + off) = w; }
	v_lshlrev_b32_e32 v196, 16, v160
	v_and_b32_e32 v197, 0xffff0000, v160
	v_lshlrev_b32_e32 v198, 16, v161
	v_and_b32_e32 v199, 0xffff0000, v161
	v_lshlrev_b32_e32 v200, 16, v162
	v_and_b32_e32 v201, 0xffff0000, v162
	v_lshlrev_b32_e32 v202, 16, v163
	v_and_b32_e32 v203, 0xffff0000, v163
	v_pk_mul_f32 v[188:189], v[188:189], v[180:181]
	v_pk_mul_f32 v[190:191], v[190:191], v[182:183]
	v_pk_mul_f32 v[192:193], v[192:193], v[184:185]
	v_pk_mul_f32 v[194:195], v[194:195], v[186:187]
	v_pk_mul_f32 v[188:189], v[188:189], v[196:197]
	v_pk_mul_f32 v[190:191], v[190:191], v[198:199]
	v_pk_mul_f32 v[192:193], v[192:193], v[200:201]
	v_pk_mul_f32 v[194:195], v[194:195], v[202:203]
	v_cvt_pk_bf16_f32 v208, v188, v189
	v_cvt_pk_bf16_f32 v209, v190, v191
	v_cvt_pk_bf16_f32 v210, v192, v193
	v_cvt_pk_bf16_f32 v211, v194, v195
	global_store_dwordx4 v178, v[208:211], s[10:11]
	v_pk_mul_f32 v[180:181], v[2:3], s[74:75] op_sel_hi:[1,0]
	v_pk_mul_f32 v[182:183], v[4:5], s[74:75] op_sel_hi:[1,0]
	v_pk_mul_f32 v[184:185], v[6:7], s[74:75] op_sel_hi:[1,0]
	v_pk_mul_f32 v[186:187], v[8:9], s[74:75] op_sel_hi:[1,0]
	v_exp_f32_e32 v180, v180
	v_exp_f32_e32 v181, v181
	v_exp_f32_e32 v182, v182
	v_exp_f32_e32 v183, v183
	v_exp_f32_e32 v184, v184
	v_exp_f32_e32 v185, v185
	v_exp_f32_e32 v186, v186
	v_exp_f32_e32 v187, v187
	v_pk_fma_f32 v[188:189], v[74:75], s[26:27], v[236:237] op_sel_hi:[1,0,0]
	v_pk_fma_f32 v[190:191], v[76:77], s[26:27], v[236:237] op_sel_hi:[1,0,0]
	v_pk_fma_f32 v[192:193], v[70:71], s[26:27], v[236:237] op_sel_hi:[1,0,0]
	v_pk_fma_f32 v[194:195], v[72:73], s[26:27], v[236:237] op_sel_hi:[1,0,0]
	v_pk_add_f32 v[180:181], v[180:181], 1.0 op_sel_hi:[1,0]
	v_pk_add_f32 v[182:183], v[182:183], 1.0 op_sel_hi:[1,0]
	v_pk_add_f32 v[184:185], v[184:185], 1.0 op_sel_hi:[1,0]
	v_pk_add_f32 v[186:187], v[186:187], 1.0 op_sel_hi:[1,0]
	v_rcp_f32_e32 v180, v180
	v_rcp_f32_e32 v181, v181
	v_rcp_f32_e32 v182, v182
	v_rcp_f32_e32 v183, v183
	v_rcp_f32_e32 v184, v184
	v_rcp_f32_e32 v185, v185
	v_rcp_f32_e32 v186, v186
	v_rcp_f32_e32 v187, v187
	v_pk_fma_f32 v[188:189], v[74:75], v[188:189], s[22:23] op_sel_hi:[1,1,0]
	v_pk_fma_f32 v[190:191], v[76:77], v[190:191], s[22:23] op_sel_hi:[1,1,0]
	v_pk_fma_f32 v[192:193], v[70:71], v[192:193], s[22:23] op_sel_hi:[1,1,0]
	v_pk_fma_f32 v[194:195], v[72:73], v[194:195], s[22:23] op_sel_hi:[1,1,0]
	v_pk_fma_f32 v[188:189], v[74:75], v[188:189], -2.0 op_sel_hi:[1,1,0]
	v_pk_fma_f32 v[190:191], v[76:77], v[190:191], -2.0 op_sel_hi:[1,1,0]
	v_pk_fma_f32 v[192:193], v[70:71], v[192:193], -2.0 op_sel_hi:[1,1,0]
	v_pk_fma_f32 v[194:195], v[72:73], v[194:195], -2.0 op_sel_hi:[1,1,0]
	v_pk_fma_f32 v[188:189], v[74:75], v[188:189], -2.0 op_sel_hi:[1,1,0]
	v_pk_fma_f32 v[190:191], v[76:77], v[190:191], -2.0 op_sel_hi:[1,1,0]
	v_pk_fma_f32 v[192:193], v[70:71], v[192:193], -2.0 op_sel_hi:[1,1,0]
	v_pk_fma_f32 v[194:195], v[72:73], v[194:195], -2.0 op_sel_hi:[1,1,0]
	v_pk_mul_f32 v[188:189], v[74:75], v[188:189]
	v_pk_mul_f32 v[190:191], v[76:77], v[190:191]
	v_pk_mul_f32 v[192:193], v[70:71], v[192:193]
	v_pk_mul_f32 v[194:195], v[72:73], v[194:195]
	v_sqrt_f32_e32 v188, v188
	v_sqrt_f32_e32 v189, v189
	v_sqrt_f32_e32 v190, v190
	v_sqrt_f32_e32 v191, v191
	v_sqrt_f32_e32 v192, v192
	v_sqrt_f32_e32 v193, v193
	v_sqrt_f32_e32 v194, v194
	v_sqrt_f32_e32 v195, v195
	s_waitcnt vmcnt(15)
	v_lshlrev_b32_e32 v196, 16, v164
	v_and_b32_e32 v197, 0xffff0000, v164
	v_lshlrev_b32_e32 v198, 16, v165
	v_and_b32_e32 v199, 0xffff0000, v165
	v_lshlrev_b32_e32 v200, 16, v166
	v_and_b32_e32 v201, 0xffff0000, v166
	v_lshlrev_b32_e32 v202, 16, v167
	v_and_b32_e32 v203, 0xffff0000, v167
	v_pk_mul_f32 v[188:189], v[188:189], v[180:181]
	v_pk_mul_f32 v[190:191], v[190:191], v[182:183]
	v_pk_mul_f32 v[192:193], v[192:193], v[184:185]
	v_pk_mul_f32 v[194:195], v[194:195], v[186:187]
	v_pk_mul_f32 v[188:189], v[188:189], v[196:197]
	v_pk_mul_f32 v[190:191], v[190:191], v[198:199]
	v_pk_mul_f32 v[192:193], v[192:193], v[200:201]
	v_pk_mul_f32 v[194:195], v[194:195], v[202:203]
	v_cvt_pk_bf16_f32 v212, v188, v189
	v_cvt_pk_bf16_f32 v213, v190, v191
	v_cvt_pk_bf16_f32 v214, v192, v193
	v_cvt_pk_bf16_f32 v215, v194, v195
	global_store_dwordx4 v179, v[212:215], s[10:11]
.Lgate_epi_done:
	s_andn2_b64 vcc, exec, s[4:5]
	s_mov_b64 s[4:5], -1
	s_cbranch_vccnz .LBB0_425
	s_mov_b32 s4, s75
	s_mov_b32 s5, s81
	s_nop 0
	v_mbcnt_lo_u32_b32 v2, -1, s5
	v_mbcnt_hi_u32_b32 v2, -1, v2
	v_lshl_add_u32 v2, s4, 6, v2
	s_lshl_b32 s4, s12, 7
	v_lshrrev_b32_e32 v2, 1, v2
	v_and_or_b32 v2, v2, 24, s4
	v_or_b32_e32 v2, s85, v2
	v_lshl_add_u32 v2, v2, 2, 0
	v_add_u32_e32 v3, 0x20400, v2
	v_add_u32_e32 v6, 0x22400, v2
	ds_read_b128 v[10:13], v3
	ds_read_b128 v[14:17], v3 offset:16
	ds_read_b128 v[2:5], v6
	ds_read_b128 v[6:9], v6 offset:16
	s_add_u32 s0, s0, s15
	s_addc_u32 s1, s1, s47
	s_mov_b64 s[4:5], 0
	s_branch .LBB0_425
; __device__ __forceinline__ unsigned cvt_pk_bf16(float lo, float hi) { unsigned r; asm volatile("v_cvt_pk_bf16_f32 %0, %1, %2" : "=v"(r) : "v"(lo), "v"(hi)); return r; }
;     __device__ __forceinline__ void operator()(AccMut acc, const Unit& u, int sw) const {
;     ...
;         for (int ai = 0; ai < 2; ++ai)
; #pragma unroll
;             for (int m = 0; m < 4; ++m) { const size_t off = (size_t)(row0 + ai * HALF + m * 16) * E + c0;
;                 const u32x4 xw = xnext;
;                 if (ai * 4 + m < 7) { const int ai2 = (ai * 4 + m + 1) >> 2, m2 = (ai * 4 + m + 1) & 3; xnext = *(const u32x4*)(XC + (size_t)(row0 + ai2 * HALF + m2 * 16) * E + c0); }
;                 float bt[8];
; #pragma unroll
;                 for (int n = 0; n < 2; ++n)
; #pragma unroll
;                     for (int jp = 0; jp < 2; ++jp) {
;                         const f32x2 z = (f32x2){acc[ai][1][m][n][2 * jp], acc[ai][1][m][n][2 * jp + 1]} * (-1.44269504f);
;                         f32x2 e; e.x = __builtin_amdgcn_exp2f(z.x); e.y = __builtin_amdgcn_exp2f(z.y); e = e + 1.0f;
;                         f32x2 ig; ig.x = __builtin_amdgcn_rcpf(e.x); ig.y = __builtin_amdgcn_rcpf(e.y);
;                         const f32x2 x2 = (f32x2){acc[ai][0][m][n][2 * jp], acc[ai][0][m][n][2 * jp + 1]} * 2.0f;
;                         f32x2 ser = x2 * (1.0f / 120.0f) + (1.0f / 24.0f); ser = ser * x2 + (1.0f / 6.0f); ser = ser * x2 + 0.5f; ser = ser * x2 + 1.0f; ser = ser * (-x2);
;                         f32x2 em = ser;
;                         if (__builtin_expect(__builtin_amdgcn_ballot_w64(x2.x <= -0.25f || x2.y <= -0.25f) != 0ull, 0)) {
;                             em.x = (x2.x > -0.25f) ? ser.x : (1.0f - fexp(x2.x)); em.y = (x2.y > -0.25f) ? ser.y : (1.0f - fexp(x2.y)); }
;                         const unsigned wv = xw[2 * n + jp];
;                         f32x2 sq; sq.x = __builtin_amdgcn_sqrtf(em.x); sq.y = __builtin_amdgcn_sqrtf(em.y);
;                         const f32x2 b2 = sq * ig * (f32x2){bf_lo(wv), bf_hi(wv)};
;                         bt[4 * n + 2 * jp] = b2.x; bt[4 * n + 2 * jp + 1] = b2.y; }
;                 u32x4 w; w.x = cvt_pk_bf16(bt[0], bt[1]); w.y = cvt_pk_bf16(bt[2], bt[3]); w.z = cvt_pk_bf16(bt[4], bt[5]); w.w = cvt_pk_bf16(bt[6], bt[7]);
;                 *(u32x4*)(BT + off) = w; }
.Lgate_epi_general:
	s_mov_b32 s17, 0x4038aa3b
	v_pk_mul_f32 v[180:181], v[58:59], s[74:75] op_sel_hi:[1,0]
	v_pk_mul_f32 v[182:183], v[60:61], s[74:75] op_sel_hi:[1,0]
	v_pk_mul_f32 v[184:185], v[66:67], s[74:75] op_sel_hi:[1,0]
	v_pk_mul_f32 v[186:187], v[68:69], s[74:75] op_sel_hi:[1,0]
	v_exp_f32_e32 v180, v180
	v_exp_f32_e32 v181, v181
	v_exp_f32_e32 v182, v182
	v_exp_f32_e32 v183, v183
	v_exp_f32_e32 v184, v184
	v_exp_f32_e32 v185, v185
	v_exp_f32_e32 v186, v186
	v_exp_f32_e32 v187, v187
	v_pk_fma_f32 v[188:189], v[204:205], s[26:27], v[236:237] op_sel_hi:[1,0,0]
	v_pk_fma_f32 v[190:191], v[206:207], s[26:27], v[236:237] op_sel_hi:[1,0,0]
	v_pk_fma_f32 v[192:193], v[220:221], s[26:27], v[236:237] op_sel_hi:[1,0,0]
	v_pk_fma_f32 v[194:195], v[222:223], s[26:27], v[236:237] op_sel_hi:[1,0,0]
	v_pk_add_f32 v[180:181], v[180:181], 1.0 op_sel_hi:[1,0]
	v_pk_add_f32 v[182:183], v[182:183], 1.0 op_sel_hi:[1,0]
	v_pk_add_f32 v[184:185], v[184:185], 1.0 op_sel_hi:[1,0]
	v_pk_add_f32 v[186:187], v[186:187], 1.0 op_sel_hi:[1,0]
	v_rcp_f32_e32 v180, v180
	v_rcp_f32_e32 v181, v181
	v_rcp_f32_e32 v182, v182
	v_rcp_f32_e32 v183, v183
	v_rcp_f32_e32 v184, v184
	v_rcp_f32_e32 v185, v185
	v_rcp_f32_e32 v186, v186
	v_rcp_f32_e32 v187, v187
	v_pk_fma_f32 v[188:189], v[204:205], v[188:189], s[22:23] op_sel_hi:[1,1,0]
	v_pk_fma_f32 v[190:191], v[206:207], v[190:191], s[22:23] op_sel_hi:[1,1,0]
	v_pk_fma_f32 v[192:193], v[220:221], v[192:193], s[22:23] op_sel_hi:[1,1,0]
	v_pk_fma_f32 v[194:195], v[222:223], v[194:195], s[22:23] op_sel_hi:[1,1,0]
	v_pk_fma_f32 v[188:189], v[204:205], v[188:189], -2.0 op_sel_hi:[1,1,0]
	v_pk_fma_f32 v[190:191], v[206:207], v[190:191], -2.0 op_sel_hi:[1,1,0]
	v_pk_fma_f32 v[192:193], v[220:221], v[192:193], -2.0 op_sel_hi:[1,1,0]
	v_pk_fma_f32 v[194:195], v[222:223], v[194:195], -2.0 op_sel_hi:[1,1,0]
	v_pk_fma_f32 v[188:189], v[204:205], v[188:189], -2.0 op_sel_hi:[1,1,0]
	v_pk_fma_f32 v[190:191], v[206:207], v[190:191], -2.0 op_sel_hi:[1,1,0]
	v_pk_fma_f32 v[192:193], v[220:221], v[192:193], -2.0 op_sel_hi:[1,1,0]
	v_pk_fma_f32 v[194:195], v[222:223], v[194:195], -2.0 op_sel_hi:[1,1,0]
	v_pk_mul_f32 v[188:189], v[204:205], v[188:189]
	v_pk_mul_f32 v[190:191], v[206:207], v[190:191]
	v_pk_mul_f32 v[192:193], v[220:221], v[192:193]
	v_pk_mul_f32 v[194:195], v[222:223], v[194:195]
	v_mul_f32_e32 v228, s17, v204
	v_mul_f32_e32 v229, s17, v205
	v_mul_f32_e32 v230, s17, v206
	v_mul_f32_e32 v231, s17, v207
	v_mul_f32_e32 v232, s17, v220
	v_mul_f32_e32 v233, s17, v221
	v_mul_f32_e32 v234, s17, v222
	v_mul_f32_e32 v235, s17, v223
	v_exp_f32_e32 v228, v228
	v_exp_f32_e32 v229, v229
	v_exp_f32_e32 v230, v230
	v_exp_f32_e32 v231, v231
	v_exp_f32_e32 v232, v232
	v_exp_f32_e32 v233, v233
	v_exp_f32_e32 v234, v234
	v_exp_f32_e32 v235, v235
	v_pk_add_f32 v[228:229], v[228:229], 1.0 op_sel_hi:[1,0] neg_lo:[1,0] neg_hi:[1,0]
	v_pk_add_f32 v[230:231], v[230:231], 1.0 op_sel_hi:[1,0] neg_lo:[1,0] neg_hi:[1,0]
	v_pk_add_f32 v[232:233], v[232:233], 1.0 op_sel_hi:[1,0] neg_lo:[1,0] neg_hi:[1,0]
	v_pk_add_f32 v[234:235], v[234:235], 1.0 op_sel_hi:[1,0] neg_lo:[1,0] neg_hi:[1,0]
	v_cmp_lt_f32_e32 vcc, s13, v204
	s_nop 1
	v_cndmask_b32_e32 v188, v228, v188, vcc
	v_cmp_lt_f32_e32 vcc, s13, v205
	s_nop 1
	v_cndmask_b32_e32 v189, v229, v189, vcc
	v_cmp_lt_f32_e32 vcc, s13, v206
	s_nop 1
	v_cndmask_b32_e32 v190, v230, v190, vcc
	v_cmp_lt_f32_e32 vcc, s13, v207
	s_nop 1
	v_cndmask_b32_e32 v191, v231, v191, vcc
	v_cmp_lt_f32_e32 vcc, s13, v220
	s_nop 1
	v_cndmask_b32_e32 v192, v232, v192, vcc
	v_cmp_lt_f32_e32 vcc, s13, v221
	s_nop 1
	v_cndmask_b32_e32 v193, v233, v193, vcc
	v_cmp_lt_f32_e32 vcc, s13, v222
	s_nop 1
	v_cndmask_b32_e32 v194, v234, v194, vcc
	v_cmp_lt_f32_e32 vcc, s13, v223
	s_nop 1
	v_cndmask_b32_e32 v195, v235, v195, vcc
	v_sqrt_f32_e32 v188, v188
	v_sqrt_f32_e32 v189, v189
	v_sqrt_f32_e32 v190, v190
	v_sqrt_f32_e32 v191, v191
	v_sqrt_f32_e32 v192, v192
	v_sqrt_f32_e32 v193, v193
	v_sqrt_f32_e32 v194, v194
	v_sqrt_f32_e32 v195, v195
	s_waitcnt vmcnt(15)
	v_lshlrev_b32_e32 v196, 16, v136
	v_and_b32_e32 v197, 0xffff0000, v136
	v_lshlrev_b32_e32 v198, 16, v137
	v_and_b32_e32 v199, 0xffff0000, v137
	v_lshlrev_b32_e32 v200, 16, v138
	v_and_b32_e32 v201, 0xffff0000, v138
	v_lshlrev_b32_e32 v202, 16, v139
	v_and_b32_e32 v203, 0xffff0000, v139
	v_pk_mul_f32 v[188:189], v[188:189], v[180:181]
	v_pk_mul_f32 v[190:191], v[190:191], v[182:183]
	v_pk_mul_f32 v[192:193], v[192:193], v[184:185]
	v_pk_mul_f32 v[194:195], v[194:195], v[186:187]
	v_pk_mul_f32 v[188:189], v[188:189], v[196:197]
	v_pk_mul_f32 v[190:191], v[190:191], v[198:199]
	v_pk_mul_f32 v[192:193], v[192:193], v[200:201]
	v_pk_mul_f32 v[194:195], v[194:195], v[202:203]
	v_cvt_pk_bf16_f32 v208, v188, v189
	v_cvt_pk_bf16_f32 v209, v190, v191
	v_cvt_pk_bf16_f32 v210, v192, v193
	v_cvt_pk_bf16_f32 v211, v194, v195
	global_store_dwordx4 v168, v[208:211], s[10:11]
	v_pk_mul_f32 v[180:181], v[50:51], s[74:75] op_sel_hi:[1,0]
	v_pk_mul_f32 v[182:183], v[52:53], s[74:75] op_sel_hi:[1,0]
	v_pk_mul_f32 v[184:185], v[54:55], s[74:75] op_sel_hi:[1,0]
	v_pk_mul_f32 v[186:187], v[56:57], s[74:75] op_sel_hi:[1,0]
	v_exp_f32_e32 v180, v180
	v_exp_f32_e32 v181, v181
	v_exp_f32_e32 v182, v182
	v_exp_f32_e32 v183, v183
	v_exp_f32_e32 v184, v184
	v_exp_f32_e32 v185, v185
	v_exp_f32_e32 v186, v186
	v_exp_f32_e32 v187, v187
	v_pk_fma_f32 v[188:189], v[224:225], s[26:27], v[236:237] op_sel_hi:[1,0,0]
	v_pk_fma_f32 v[190:191], v[226:227], s[26:27], v[236:237] op_sel_hi:[1,0,0]
	v_pk_fma_f32 v[192:193], v[126:127], s[26:27], v[236:237] op_sel_hi:[1,0,0]
	v_pk_fma_f32 v[194:195], v[128:129], s[26:27], v[236:237] op_sel_hi:[1,0,0]
; __device__ __forceinline__ unsigned cvt_pk_bf16(float lo, float hi) { unsigned r; asm volatile("v_cvt_pk_bf16_f32 %0, %1, %2" : "=v"(r) : "v"(lo), "v"(hi)); return r; }
;     __device__ __forceinline__ void operator()(AccMut acc, const Unit& u, int sw) const {
;     ...
;         for (int ai = 0; ai < 2; ++ai)
; #pragma unroll
;             for (int m = 0; m < 4; ++m) { const size_t off = (size_t)(row0 + ai * HALF + m * 16) * E + c0;
;                 const u32x4 xw = xnext;
;                 if (ai * 4 + m < 7) { const int ai2 = (ai * 4 + m + 1) >> 2, m2 = (ai * 4 + m + 1) & 3; xnext = *(const u32x4*)(XC + (size_t)(row0 + ai2 * HALF + m2 * 16) * E + c0); }
;                 float bt[8];
; #pragma unroll
;                 for (int n = 0; n < 2; ++n)
; #pragma unroll
;                     for (int jp = 0; jp < 2; ++jp) {
;                         const f32x2 z = (f32x2){acc[ai][1][m][n][2 * jp], acc[ai][1][m][n][2 * jp + 1]} * (-1.44269504f);
;                         f32x2 e; e.x = __builtin_amdgcn_exp2f(z.x); e.y = __builtin_amdgcn_exp2f(z.y); e = e + 1.0f;
;                         f32x2 ig; ig.x = __builtin_amdgcn_rcpf(e.x); ig.y = __builtin_amdgcn_rcpf(e.y);
;                         const f32x2 x2 = (f32x2){acc[ai][0][m][n][2 * jp], acc[ai][0][m][n][2 * jp + 1]} * 2.0f;
;                         f32x2 ser = x2 * (1.0f / 120.0f) + (1.0f / 24.0f); ser = ser * x2 + (1.0f / 6.0f); ser = ser * x2 + 0.5f; ser = ser * x2 + 1.0f; ser = ser * (-x2);
;                         f32x2 em = ser;
;                         if (__builtin_expect(__builtin_amdgcn_ballot_w64(x2.x <= -0.25f || x2.y <= -0.25f) != 0ull, 0)) {
;                             em.x = (x2.x > -0.25f) ? ser.x : (1.0f - fexp(x2.x)); em.y = (x2.y > -0.25f) ? ser.y : (1.0f - fexp(x2.y)); }
;                         const unsigned wv = xw[2 * n + jp];
;                         f32x2 sq; sq.x = __builtin_amdgcn_sqrtf(em.x); sq.y = __builtin_amdgcn_sqrtf(em.y);
;                         const f32x2 b2 = sq * ig * (f32x2){bf_lo(wv), bf_hi(wv)};
;                         bt[4 * n + 2 * jp] = b2.x; bt[4 * n + 2 * jp + 1] = b2.y; }
;                 u32x4 w; w.x = cvt_pk_bf16(bt[0], bt[1]); w.y = cvt_pk_bf16(bt[2], bt[3]); w.z = cvt_pk_bf16(bt[4], bt[5]); w.w = cvt_pk_bf16(bt[6], bt[7]);
;                 *(u32x4*)(BT + off) = w; }
	v_pk_add_f32 v[180:181], v[180:181], 1.0 op_sel_hi:[1,0]
	v_pk_add_f32 v[182:183], v[182:183], 1.0 op_sel_hi:[1,0]
	v_pk_add_f32 v[184:185], v[184:185], 1.0 op_sel_hi:[1,0]
	v_pk_add_f32 v[186:187], v[186:187], 1.0 op_sel_hi:[1,0]
	v_rcp_f32_e32 v180, v180
	v_rcp_f32_e32 v181, v181
	v_rcp_f32_e32 v182, v182
	v_rcp_f32_e32 v183, v183
	v_rcp_f32_e32 v184, v184
	v_rcp_f32_e32 v185, v185
	v_rcp_f32_e32 v186, v186
	v_rcp_f32_e32 v187, v187
	v_pk_fma_f32 v[188:189], v[224:225], v[188:189], s[22:23] op_sel_hi:[1,1,0]
	v_pk_fma_f32 v[190:191], v[226:227], v[190:191], s[22:23] op_sel_hi:[1,1,0]
	v_pk_fma_f32 v[192:193], v[126:127], v[192:193], s[22:23] op_sel_hi:[1,1,0]
	v_pk_fma_f32 v[194:195], v[128:129], v[194:195], s[22:23] op_sel_hi:[1,1,0]
	v_pk_fma_f32 v[188:189], v[224:225], v[188:189], -2.0 op_sel_hi:[1,1,0]
	v_pk_fma_f32 v[190:191], v[226:227], v[190:191], -2.0 op_sel_hi:[1,1,0]
	v_pk_fma_f32 v[192:193], v[126:127], v[192:193], -2.0 op_sel_hi:[1,1,0]
	v_pk_fma_f32 v[194:195], v[128:129], v[194:195], -2.0 op_sel_hi:[1,1,0]
	v_pk_fma_f32 v[188:189], v[224:225], v[188:189], -2.0 op_sel_hi:[1,1,0]
	v_pk_fma_f32 v[190:191], v[226:227], v[190:191], -2.0 op_sel_hi:[1,1,0]
	v_pk_fma_f32 v[192:193], v[126:127], v[192:193], -2.0 op_sel_hi:[1,1,0]
	v_pk_fma_f32 v[194:195], v[128:129], v[194:195], -2.0 op_sel_hi:[1,1,0]
	v_pk_mul_f32 v[188:189], v[224:225], v[188:189]
	v_pk_mul_f32 v[190:191], v[226:227], v[190:191]
	v_pk_mul_f32 v[192:193], v[126:127], v[192:193]
	v_pk_mul_f32 v[194:195], v[128:129], v[194:195]
	v_mul_f32_e32 v228, s17, v224
	v_mul_f32_e32 v229, s17, v225
	v_mul_f32_e32 v230, s17, v226
	v_mul_f32_e32 v231, s17, v227
	v_mul_f32_e32 v232, s17, v126
	v_mul_f32_e32 v233, s17, v127
	v_mul_f32_e32 v234, s17, v128
	v_mul_f32_e32 v235, s17, v129
	v_exp_f32_e32 v228, v228
	v_exp_f32_e32 v229, v229
	v_exp_f32_e32 v230, v230
	v_exp_f32_e32 v231, v231
	v_exp_f32_e32 v232, v232
	v_exp_f32_e32 v233, v233
	v_exp_f32_e32 v234, v234
	v_exp_f32_e32 v235, v235
	v_pk_add_f32 v[228:229], v[228:229], 1.0 op_sel_hi:[1,0] neg_lo:[1,0] neg_hi:[1,0]
	v_pk_add_f32 v[230:231], v[230:231], 1.0 op_sel_hi:[1,0] neg_lo:[1,0] neg_hi:[1,0]
	v_pk_add_f32 v[232:233], v[232:233], 1.0 op_sel_hi:[1,0] neg_lo:[1,0] neg_hi:[1,0]
	v_pk_add_f32 v[234:235], v[234:235], 1.0 op_sel_hi:[1,0] neg_lo:[1,0] neg_hi:[1,0]
	v_cmp_lt_f32_e32 vcc, s13, v224
	s_nop 1
	v_cndmask_b32_e32 v188, v228, v188, vcc
	v_cmp_lt_f32_e32 vcc, s13, v225
	s_nop 1
	v_cndmask_b32_e32 v189, v229, v189, vcc
	v_cmp_lt_f32_e32 vcc, s13, v226
	s_nop 1
	v_cndmask_b32_e32 v190, v230, v190, vcc
	v_cmp_lt_f32_e32 vcc, s13, v227
	s_nop 1
	v_cndmask_b32_e32 v191, v231, v191, vcc
	v_cmp_lt_f32_e32 vcc, s13, v126
	s_nop 1
	v_cndmask_b32_e32 v192, v232, v192, vcc
	v_cmp_lt_f32_e32 vcc, s13, v127
	s_nop 1
	v_cndmask_b32_e32 v193, v233, v193, vcc
	v_cmp_lt_f32_e32 vcc, s13, v128
	s_nop 1
	v_cndmask_b32_e32 v194, v234, v194, vcc
	v_cmp_lt_f32_e32 vcc, s13, v129
	s_nop 1
	v_cndmask_b32_e32 v195, v235, v195, vcc
	v_sqrt_f32_e32 v188, v188
	v_sqrt_f32_e32 v189, v189
	v_sqrt_f32_e32 v190, v190
	v_sqrt_f32_e32 v191, v191
	v_sqrt_f32_e32 v192, v192
	v_sqrt_f32_e32 v193, v193
	v_sqrt_f32_e32 v194, v194
	v_sqrt_f32_e32 v195, v195
	s_waitcnt vmcnt(15)
	v_lshlrev_b32_e32 v196, 16, v140
	v_and_b32_e32 v197, 0xffff0000, v140
	v_lshlrev_b32_e32 v198, 16, v141
	v_and_b32_e32 v199, 0xffff0000, v141
	v_lshlrev_b32_e32 v200, 16, v142
	v_and_b32_e32 v201, 0xffff0000, v142
	v_lshlrev_b32_e32 v202, 16, v143
	v_and_b32_e32 v203, 0xffff0000, v143
	v_pk_mul_f32 v[188:189], v[188:189], v[180:181]
	v_pk_mul_f32 v[190:191], v[190:191], v[182:183]
	v_pk_mul_f32 v[192:193], v[192:193], v[184:185]
	v_pk_mul_f32 v[194:195], v[194:195], v[186:187]
	v_pk_mul_f32 v[188:189], v[188:189], v[196:197]
	v_pk_mul_f32 v[190:191], v[190:191], v[198:199]
	v_pk_mul_f32 v[192:193], v[192:193], v[200:201]
	v_pk_mul_f32 v[194:195], v[194:195], v[202:203]
	v_cvt_pk_bf16_f32 v212, v188, v189
	v_cvt_pk_bf16_f32 v213, v190, v191
	v_cvt_pk_bf16_f32 v214, v192, v193
	v_cvt_pk_bf16_f32 v215, v194, v195
	global_store_dwordx4 v169, v[212:215], s[10:11]
	v_pk_mul_f32 v[180:181], v[42:43], s[74:75] op_sel_hi:[1,0]
	v_pk_mul_f32 v[182:183], v[44:45], s[74:75] op_sel_hi:[1,0]
	v_pk_mul_f32 v[184:185], v[46:47], s[74:75] op_sel_hi:[1,0]
	v_pk_mul_f32 v[186:187], v[48:49], s[74:75] op_sel_hi:[1,0]
	v_exp_f32_e32 v180, v180
	v_exp_f32_e32 v181, v181
	v_exp_f32_e32 v182, v182
	v_exp_f32_e32 v183, v183
	v_exp_f32_e32 v184, v184
	v_exp_f32_e32 v185, v185
	v_exp_f32_e32 v186, v186
	v_exp_f32_e32 v187, v187
	v_pk_fma_f32 v[188:189], v[122:123], s[26:27], v[236:237] op_sel_hi:[1,0,0]
	v_pk_fma_f32 v[190:191], v[124:125], s[26:27], v[236:237] op_sel_hi:[1,0,0]
	v_pk_fma_f32 v[192:193], v[118:119], s[26:27], v[236:237] op_sel_hi:[1,0,0]
	v_pk_fma_f32 v[194:195], v[120:121], s[26:27], v[236:237] op_sel_hi:[1,0,0]
	v_pk_add_f32 v[180:181], v[180:181], 1.0 op_sel_hi:[1,0]
	v_pk_add_f32 v[182:183], v[182:183], 1.0 op_sel_hi:[1,0]
	v_pk_add_f32 v[184:185], v[184:185], 1.0 op_sel_hi:[1,0]
	v_pk_add_f32 v[186:187], v[186:187], 1.0 op_sel_hi:[1,0]
	v_rcp_f32_e32 v180, v180
	v_rcp_f32_e32 v181, v181
	v_rcp_f32_e32 v182, v182
	v_rcp_f32_e32 v183, v183
	v_rcp_f32_e32 v184, v184
	v_rcp_f32_e32 v185, v185
	v_rcp_f32_e32 v186, v186
	v_rcp_f32_e32 v187, v187
	v_pk_fma_f32 v[188:189], v[122:123], v[188:189], s[22:23] op_sel_hi:[1,1,0]
	v_pk_fma_f32 v[190:191], v[124:125], v[190:191], s[22:23] op_sel_hi:[1,1,0]
	v_pk_fma_f32 v[192:193], v[118:119], v[192:193], s[22:23] op_sel_hi:[1,1,0]
	v_pk_fma_f32 v[194:195], v[120:121], v[194:195], s[22:23] op_sel_hi:[1,1,0]
	v_pk_fma_f32 v[188:189], v[122:123], v[188:189], -2.0 op_sel_hi:[1,1,0]
; __device__ __forceinline__ unsigned cvt_pk_bf16(float lo, float hi) { unsigned r; asm volatile("v_cvt_pk_bf16_f32 %0, %1, %2" : "=v"(r) : "v"(lo), "v"(hi)); return r; }
;     __device__ __forceinline__ void operator()(AccMut acc, const Unit& u, int sw) const {
;     ...
;         for (int ai = 0; ai < 2; ++ai)
; #pragma unroll
;             for (int m = 0; m < 4; ++m) { const size_t off = (size_t)(row0 + ai * HALF + m * 16) * E + c0;
;                 const u32x4 xw = xnext;
;                 if (ai * 4 + m < 7) { const int ai2 = (ai * 4 + m + 1) >> 2, m2 = (ai * 4 + m + 1) & 3; xnext = *(const u32x4*)(XC + (size_t)(row0 + ai2 * HALF + m2 * 16) * E + c0); }
;                 float bt[8];
; #pragma unroll
;                 for (int n = 0; n < 2; ++n)
; #pragma unroll
;                     for (int jp = 0; jp < 2; ++jp) {
;                         const f32x2 z = (f32x2){acc[ai][1][m][n][2 * jp], acc[ai][1][m][n][2 * jp + 1]} * (-1.44269504f);
;                         f32x2 e; e.x = __builtin_amdgcn_exp2f(z.x); e.y = __builtin_amdgcn_exp2f(z.y); e = e + 1.0f;
;                         f32x2 ig; ig.x = __builtin_amdgcn_rcpf(e.x); ig.y = __builtin_amdgcn_rcpf(e.y);
;                         const f32x2 x2 = (f32x2){acc[ai][0][m][n][2 * jp], acc[ai][0][m][n][2 * jp + 1]} * 2.0f;
;                         f32x2 ser = x2 * (1.0f / 120.0f) + (1.0f / 24.0f); ser = ser * x2 + (1.0f / 6.0f); ser = ser * x2 + 0.5f; ser = ser * x2 + 1.0f; ser = ser * (-x2);
;                         f32x2 em = ser;
;                         if (__builtin_expect(__builtin_amdgcn_ballot_w64(x2.x <= -0.25f || x2.y <= -0.25f) != 0ull, 0)) {
;                             em.x = (x2.x > -0.25f) ? ser.x : (1.0f - fexp(x2.x)); em.y = (x2.y > -0.25f) ? ser.y : (1.0f - fexp(x2.y)); }
;                         const unsigned wv = xw[2 * n + jp];
;                         f32x2 sq; sq.x = __builtin_amdgcn_sqrtf(em.x); sq.y = __builtin_amdgcn_sqrtf(em.y);
;                         const f32x2 b2 = sq * ig * (f32x2){bf_lo(wv), bf_hi(wv)};
;                         bt[4 * n + 2 * jp] = b2.x; bt[4 * n + 2 * jp + 1] = b2.y; }
;                 u32x4 w; w.x = cvt_pk_bf16(bt[0], bt[1]); w.y = cvt_pk_bf16(bt[2], bt[3]); w.z = cvt_pk_bf16(bt[4], bt[5]); w.w = cvt_pk_bf16(bt[6], bt[7]);
;                 *(u32x4*)(BT + off) = w; }
	v_pk_fma_f32 v[190:191], v[124:125], v[190:191], -2.0 op_sel_hi:[1,1,0]
	v_pk_fma_f32 v[192:193], v[118:119], v[192:193], -2.0 op_sel_hi:[1,1,0]
	v_pk_fma_f32 v[194:195], v[120:121], v[194:195], -2.0 op_sel_hi:[1,1,0]
	v_pk_fma_f32 v[188:189], v[122:123], v[188:189], -2.0 op_sel_hi:[1,1,0]
	v_pk_fma_f32 v[190:191], v[124:125], v[190:191], -2.0 op_sel_hi:[1,1,0]
	v_pk_fma_f32 v[192:193], v[118:119], v[192:193], -2.0 op_sel_hi:[1,1,0]
	v_pk_fma_f32 v[194:195], v[120:121], v[194:195], -2.0 op_sel_hi:[1,1,0]
	v_pk_mul_f32 v[188:189], v[122:123], v[188:189]
	v_pk_mul_f32 v[190:191], v[124:125], v[190:191]
	v_pk_mul_f32 v[192:193], v[118:119], v[192:193]
	v_pk_mul_f32 v[194:195], v[120:121], v[194:195]
	v_mul_f32_e32 v228, s17, v122
	v_mul_f32_e32 v229, s17, v123
	v_mul_f32_e32 v230, s17, v124
	v_mul_f32_e32 v231, s17, v125
	v_mul_f32_e32 v232, s17, v118
	v_mul_f32_e32 v233, s17, v119
	v_mul_f32_e32 v234, s17, v120
	v_mul_f32_e32 v235, s17, v121
	v_exp_f32_e32 v228, v228
	v_exp_f32_e32 v229, v229
	v_exp_f32_e32 v230, v230
	v_exp_f32_e32 v231, v231
	v_exp_f32_e32 v232, v232
	v_exp_f32_e32 v233, v233
	v_exp_f32_e32 v234, v234
	v_exp_f32_e32 v235, v235
	v_pk_add_f32 v[228:229], v[228:229], 1.0 op_sel_hi:[1,0] neg_lo:[1,0] neg_hi:[1,0]
	v_pk_add_f32 v[230:231], v[230:231], 1.0 op_sel_hi:[1,0] neg_lo:[1,0] neg_hi:[1,0]
	v_pk_add_f32 v[232:233], v[232:233], 1.0 op_sel_hi:[1,0] neg_lo:[1,0] neg_hi:[1,0]
	v_pk_add_f32 v[234:235], v[234:235], 1.0 op_sel_hi:[1,0] neg_lo:[1,0] neg_hi:[1,0]
	v_cmp_lt_f32_e32 vcc, s13, v122
	s_nop 1
	v_cndmask_b32_e32 v188, v228, v188, vcc
	v_cmp_lt_f32_e32 vcc, s13, v123
	s_nop 1
	v_cndmask_b32_e32 v189, v229, v189, vcc
	v_cmp_lt_f32_e32 vcc, s13, v124
	s_nop 1
	v_cndmask_b32_e32 v190, v230, v190, vcc
	v_cmp_lt_f32_e32 vcc, s13, v125
	s_nop 1
	v_cndmask_b32_e32 v191, v231, v191, vcc
	v_cmp_lt_f32_e32 vcc, s13, v118
	s_nop 1
	v_cndmask_b32_e32 v192, v232, v192, vcc
	v_cmp_lt_f32_e32 vcc, s13, v119
	s_nop 1
	v_cndmask_b32_e32 v193, v233, v193, vcc
	v_cmp_lt_f32_e32 vcc, s13, v120
	s_nop 1
	v_cndmask_b32_e32 v194, v234, v194, vcc
	v_cmp_lt_f32_e32 vcc, s13, v121
	s_nop 1
	v_cndmask_b32_e32 v195, v235, v195, vcc
	v_sqrt_f32_e32 v188, v188
	v_sqrt_f32_e32 v189, v189
	v_sqrt_f32_e32 v190, v190
	v_sqrt_f32_e32 v191, v191
	v_sqrt_f32_e32 v192, v192
	v_sqrt_f32_e32 v193, v193
	v_sqrt_f32_e32 v194, v194
	v_sqrt_f32_e32 v195, v195
	s_waitcnt vmcnt(15)
	v_lshlrev_b32_e32 v196, 16, v144
	v_and_b32_e32 v197, 0xffff0000, v144
	v_lshlrev_b32_e32 v198, 16, v145
	v_and_b32_e32 v199, 0xffff0000, v145
	v_lshlrev_b32_e32 v200, 16, v146
	v_and_b32_e32 v201, 0xffff0000, v146
	v_lshlrev_b32_e32 v202, 16, v147
	v_and_b32_e32 v203, 0xffff0000, v147
	v_pk_mul_f32 v[188:189], v[188:189], v[180:181]
	v_pk_mul_f32 v[190:191], v[190:191], v[182:183]
	v_pk_mul_f32 v[192:193], v[192:193], v[184:185]
	v_pk_mul_f32 v[194:195], v[194:195], v[186:187]
	v_pk_mul_f32 v[188:189], v[188:189], v[196:197]
	v_pk_mul_f32 v[190:191], v[190:191], v[198:199]
	v_pk_mul_f32 v[192:193], v[192:193], v[200:201]
	v_pk_mul_f32 v[194:195], v[194:195], v[202:203]
	v_cvt_pk_bf16_f32 v208, v188, v189
	v_cvt_pk_bf16_f32 v209, v190, v191
	v_cvt_pk_bf16_f32 v210, v192, v193
	v_cvt_pk_bf16_f32 v211, v194, v195
	global_store_dwordx4 v172, v[208:211], s[10:11]
	v_pk_mul_f32 v[180:181], v[34:35], s[74:75] op_sel_hi:[1,0]
	v_pk_mul_f32 v[182:183], v[36:37], s[74:75] op_sel_hi:[1,0]
	v_pk_mul_f32 v[184:185], v[38:39], s[74:75] op_sel_hi:[1,0]
	v_pk_mul_f32 v[186:187], v[40:41], s[74:75] op_sel_hi:[1,0]
	v_exp_f32_e32 v180, v180
	v_exp_f32_e32 v181, v181
	v_exp_f32_e32 v182, v182
	v_exp_f32_e32 v183, v183
	v_exp_f32_e32 v184, v184
	v_exp_f32_e32 v185, v185
	v_exp_f32_e32 v186, v186
	v_exp_f32_e32 v187, v187
	v_pk_fma_f32 v[188:189], v[114:115], s[26:27], v[236:237] op_sel_hi:[1,0,0]
	v_pk_fma_f32 v[190:191], v[116:117], s[26:27], v[236:237] op_sel_hi:[1,0,0]
	v_pk_fma_f32 v[192:193], v[106:107], s[26:27], v[236:237] op_sel_hi:[1,0,0]
	v_pk_fma_f32 v[194:195], v[108:109], s[26:27], v[236:237] op_sel_hi:[1,0,0]
	v_pk_add_f32 v[180:181], v[180:181], 1.0 op_sel_hi:[1,0]
	v_pk_add_f32 v[182:183], v[182:183], 1.0 op_sel_hi:[1,0]
	v_pk_add_f32 v[184:185], v[184:185], 1.0 op_sel_hi:[1,0]
	v_pk_add_f32 v[186:187], v[186:187], 1.0 op_sel_hi:[1,0]
	v_rcp_f32_e32 v180, v180
	v_rcp_f32_e32 v181, v181
	v_rcp_f32_e32 v182, v182
	v_rcp_f32_e32 v183, v183
	v_rcp_f32_e32 v184, v184
	v_rcp_f32_e32 v185, v185
	v_rcp_f32_e32 v186, v186
	v_rcp_f32_e32 v187, v187
	v_pk_fma_f32 v[188:189], v[114:115], v[188:189], s[22:23] op_sel_hi:[1,1,0]
	v_pk_fma_f32 v[190:191], v[116:117], v[190:191], s[22:23] op_sel_hi:[1,1,0]
	v_pk_fma_f32 v[192:193], v[106:107], v[192:193], s[22:23] op_sel_hi:[1,1,0]
	v_pk_fma_f32 v[194:195], v[108:109], v[194:195], s[22:23] op_sel_hi:[1,1,0]
	v_pk_fma_f32 v[188:189], v[114:115], v[188:189], -2.0 op_sel_hi:[1,1,0]
	v_pk_fma_f32 v[190:191], v[116:117], v[190:191], -2.0 op_sel_hi:[1,1,0]
	v_pk_fma_f32 v[192:193], v[106:107], v[192:193], -2.0 op_sel_hi:[1,1,0]
	v_pk_fma_f32 v[194:195], v[108:109], v[194:195], -2.0 op_sel_hi:[1,1,0]
	v_pk_fma_f32 v[188:189], v[114:115], v[188:189], -2.0 op_sel_hi:[1,1,0]
	v_pk_fma_f32 v[190:191], v[116:117], v[190:191], -2.0 op_sel_hi:[1,1,0]
	v_pk_fma_f32 v[192:193], v[106:107], v[192:193], -2.0 op_sel_hi:[1,1,0]
	v_pk_fma_f32 v[194:195], v[108:109], v[194:195], -2.0 op_sel_hi:[1,1,0]
	v_pk_mul_f32 v[188:189], v[114:115], v[188:189]
	v_pk_mul_f32 v[190:191], v[116:117], v[190:191]
	v_pk_mul_f32 v[192:193], v[106:107], v[192:193]
	v_pk_mul_f32 v[194:195], v[108:109], v[194:195]
	v_mul_f32_e32 v228, s17, v114
	v_mul_f32_e32 v229, s17, v115
	v_mul_f32_e32 v230, s17, v116
; __device__ __forceinline__ unsigned cvt_pk_bf16(float lo, float hi) { unsigned r; asm volatile("v_cvt_pk_bf16_f32 %0, %1, %2" : "=v"(r) : "v"(lo), "v"(hi)); return r; }
;     __device__ __forceinline__ void operator()(AccMut acc, const Unit& u, int sw) const {
;     ...
;         for (int ai = 0; ai < 2; ++ai)
; #pragma unroll
;             for (int m = 0; m < 4; ++m) { const size_t off = (size_t)(row0 + ai * HALF + m * 16) * E + c0;
;                 const u32x4 xw = xnext;
;                 if (ai * 4 + m < 7) { const int ai2 = (ai * 4 + m + 1) >> 2, m2 = (ai * 4 + m + 1) & 3; xnext = *(const u32x4*)(XC + (size_t)(row0 + ai2 * HALF + m2 * 16) * E + c0); }
;                 float bt[8];
; #pragma unroll
;                 for (int n = 0; n < 2; ++n)
; #pragma unroll
;                     for (int jp = 0; jp < 2; ++jp) {
;                         const f32x2 z = (f32x2){acc[ai][1][m][n][2 * jp], acc[ai][1][m][n][2 * jp + 1]} * (-1.44269504f);
;                         f32x2 e; e.x = __builtin_amdgcn_exp2f(z.x); e.y = __builtin_amdgcn_exp2f(z.y); e = e + 1.0f;
;                         f32x2 ig; ig.x = __builtin_amdgcn_rcpf(e.x); ig.y = __builtin_amdgcn_rcpf(e.y);
;                         const f32x2 x2 = (f32x2){acc[ai][0][m][n][2 * jp], acc[ai][0][m][n][2 * jp + 1]} * 2.0f;
;                         f32x2 ser = x2 * (1.0f / 120.0f) + (1.0f / 24.0f); ser = ser * x2 + (1.0f / 6.0f); ser = ser * x2 + 0.5f; ser = ser * x2 + 1.0f; ser = ser * (-x2);
;                         f32x2 em = ser;
;                         if (__builtin_expect(__builtin_amdgcn_ballot_w64(x2.x <= -0.25f || x2.y <= -0.25f) != 0ull, 0)) {
;                             em.x = (x2.x > -0.25f) ? ser.x : (1.0f - fexp(x2.x)); em.y = (x2.y > -0.25f) ? ser.y : (1.0f - fexp(x2.y)); }
;                         const unsigned wv = xw[2 * n + jp];
;                         f32x2 sq; sq.x = __builtin_amdgcn_sqrtf(em.x); sq.y = __builtin_amdgcn_sqrtf(em.y);
;                         const f32x2 b2 = sq * ig * (f32x2){bf_lo(wv), bf_hi(wv)};
;                         bt[4 * n + 2 * jp] = b2.x; bt[4 * n + 2 * jp + 1] = b2.y; }
;                 u32x4 w; w.x = cvt_pk_bf16(bt[0], bt[1]); w.y = cvt_pk_bf16(bt[2], bt[3]); w.z = cvt_pk_bf16(bt[4], bt[5]); w.w = cvt_pk_bf16(bt[6], bt[7]);
;                 *(u32x4*)(BT + off) = w; }
	v_mul_f32_e32 v231, s17, v117
	v_mul_f32_e32 v232, s17, v106
	v_mul_f32_e32 v233, s17, v107
	v_mul_f32_e32 v234, s17, v108
	v_mul_f32_e32 v235, s17, v109
	v_exp_f32_e32 v228, v228
	v_exp_f32_e32 v229, v229
	v_exp_f32_e32 v230, v230
	v_exp_f32_e32 v231, v231
	v_exp_f32_e32 v232, v232
	v_exp_f32_e32 v233, v233
	v_exp_f32_e32 v234, v234
	v_exp_f32_e32 v235, v235
	v_pk_add_f32 v[228:229], v[228:229], 1.0 op_sel_hi:[1,0] neg_lo:[1,0] neg_hi:[1,0]
	v_pk_add_f32 v[230:231], v[230:231], 1.0 op_sel_hi:[1,0] neg_lo:[1,0] neg_hi:[1,0]
	v_pk_add_f32 v[232:233], v[232:233], 1.0 op_sel_hi:[1,0] neg_lo:[1,0] neg_hi:[1,0]
	v_pk_add_f32 v[234:235], v[234:235], 1.0 op_sel_hi:[1,0] neg_lo:[1,0] neg_hi:[1,0]
	v_cmp_lt_f32_e32 vcc, s13, v114
	s_nop 1
	v_cndmask_b32_e32 v188, v228, v188, vcc
	v_cmp_lt_f32_e32 vcc, s13, v115
	s_nop 1
	v_cndmask_b32_e32 v189, v229, v189, vcc
	v_cmp_lt_f32_e32 vcc, s13, v116
	s_nop 1
	v_cndmask_b32_e32 v190, v230, v190, vcc
	v_cmp_lt_f32_e32 vcc, s13, v117
	s_nop 1
	v_cndmask_b32_e32 v191, v231, v191, vcc
	v_cmp_lt_f32_e32 vcc, s13, v106
	s_nop 1
	v_cndmask_b32_e32 v192, v232, v192, vcc
	v_cmp_lt_f32_e32 vcc, s13, v107
	s_nop 1
	v_cndmask_b32_e32 v193, v233, v193, vcc
	v_cmp_lt_f32_e32 vcc, s13, v108
	s_nop 1
	v_cndmask_b32_e32 v194, v234, v194, vcc
	v_cmp_lt_f32_e32 vcc, s13, v109
	s_nop 1
	v_cndmask_b32_e32 v195, v235, v195, vcc
	v_sqrt_f32_e32 v188, v188
	v_sqrt_f32_e32 v189, v189
	v_sqrt_f32_e32 v190, v190
	v_sqrt_f32_e32 v191, v191
	v_sqrt_f32_e32 v192, v192
	v_sqrt_f32_e32 v193, v193
	v_sqrt_f32_e32 v194, v194
	v_sqrt_f32_e32 v195, v195
	s_waitcnt vmcnt(15)
	v_lshlrev_b32_e32 v196, 16, v148
	v_and_b32_e32 v197, 0xffff0000, v148
	v_lshlrev_b32_e32 v198, 16, v149
	v_and_b32_e32 v199, 0xffff0000, v149
	v_lshlrev_b32_e32 v200, 16, v150
	v_and_b32_e32 v201, 0xffff0000, v150
	v_lshlrev_b32_e32 v202, 16, v151
	v_and_b32_e32 v203, 0xffff0000, v151
	v_pk_mul_f32 v[188:189], v[188:189], v[180:181]
	v_pk_mul_f32 v[190:191], v[190:191], v[182:183]
	v_pk_mul_f32 v[192:193], v[192:193], v[184:185]
	v_pk_mul_f32 v[194:195], v[194:195], v[186:187]
	v_pk_mul_f32 v[188:189], v[188:189], v[196:197]
	v_pk_mul_f32 v[190:191], v[190:191], v[198:199]
	v_pk_mul_f32 v[192:193], v[192:193], v[200:201]
	v_pk_mul_f32 v[194:195], v[194:195], v[202:203]
	v_cvt_pk_bf16_f32 v212, v188, v189
	v_cvt_pk_bf16_f32 v213, v190, v191
	v_cvt_pk_bf16_f32 v214, v192, v193
	v_cvt_pk_bf16_f32 v215, v194, v195
	global_store_dwordx4 v173, v[212:215], s[10:11]
	v_pk_mul_f32 v[180:181], v[26:27], s[74:75] op_sel_hi:[1,0]
	v_pk_mul_f32 v[182:183], v[28:29], s[74:75] op_sel_hi:[1,0]
	v_pk_mul_f32 v[184:185], v[30:31], s[74:75] op_sel_hi:[1,0]
	v_pk_mul_f32 v[186:187], v[32:33], s[74:75] op_sel_hi:[1,0]
	v_exp_f32_e32 v180, v180
	v_exp_f32_e32 v181, v181
	v_exp_f32_e32 v182, v182
	v_exp_f32_e32 v183, v183
	v_exp_f32_e32 v184, v184
	v_exp_f32_e32 v185, v185
	v_exp_f32_e32 v186, v186
	v_exp_f32_e32 v187, v187
	v_pk_fma_f32 v[188:189], v[110:111], s[26:27], v[236:237] op_sel_hi:[1,0,0]
	v_pk_fma_f32 v[190:191], v[112:113], s[26:27], v[236:237] op_sel_hi:[1,0,0]
	v_pk_fma_f32 v[192:193], v[102:103], s[26:27], v[236:237] op_sel_hi:[1,0,0]
	v_pk_fma_f32 v[194:195], v[104:105], s[26:27], v[236:237] op_sel_hi:[1,0,0]
	v_pk_add_f32 v[180:181], v[180:181], 1.0 op_sel_hi:[1,0]
	v_pk_add_f32 v[182:183], v[182:183], 1.0 op_sel_hi:[1,0]
	v_pk_add_f32 v[184:185], v[184:185], 1.0 op_sel_hi:[1,0]
	v_pk_add_f32 v[186:187], v[186:187], 1.0 op_sel_hi:[1,0]
	v_rcp_f32_e32 v180, v180
	v_rcp_f32_e32 v181, v181
	v_rcp_f32_e32 v182, v182
	v_rcp_f32_e32 v183, v183
	v_rcp_f32_e32 v184, v184
	v_rcp_f32_e32 v185, v185
	v_rcp_f32_e32 v186, v186
	v_rcp_f32_e32 v187, v187
	v_pk_fma_f32 v[188:189], v[110:111], v[188:189], s[22:23] op_sel_hi:[1,1,0]
	v_pk_fma_f32 v[190:191], v[112:113], v[190:191], s[22:23] op_sel_hi:[1,1,0]
	v_pk_fma_f32 v[192:193], v[102:103], v[192:193], s[22:23] op_sel_hi:[1,1,0]
	v_pk_fma_f32 v[194:195], v[104:105], v[194:195], s[22:23] op_sel_hi:[1,1,0]
	v_pk_fma_f32 v[188:189], v[110:111], v[188:189], -2.0 op_sel_hi:[1,1,0]
	v_pk_fma_f32 v[190:191], v[112:113], v[190:191], -2.0 op_sel_hi:[1,1,0]
	v_pk_fma_f32 v[192:193], v[102:103], v[192:193], -2.0 op_sel_hi:[1,1,0]
	v_pk_fma_f32 v[194:195], v[104:105], v[194:195], -2.0 op_sel_hi:[1,1,0]
	v_pk_fma_f32 v[188:189], v[110:111], v[188:189], -2.0 op_sel_hi:[1,1,0]
	v_pk_fma_f32 v[190:191], v[112:113], v[190:191], -2.0 op_sel_hi:[1,1,0]
	v_pk_fma_f32 v[192:193], v[102:103], v[192:193], -2.0 op_sel_hi:[1,1,0]
	v_pk_fma_f32 v[194:195], v[104:105], v[194:195], -2.0 op_sel_hi:[1,1,0]
	v_pk_mul_f32 v[188:189], v[110:111], v[188:189]
	v_pk_mul_f32 v[190:191], v[112:113], v[190:191]
	v_pk_mul_f32 v[192:193], v[102:103], v[192:193]
	v_pk_mul_f32 v[194:195], v[104:105], v[194:195]
	v_mul_f32_e32 v228, s17, v110
	v_mul_f32_e32 v229, s17, v111
	v_mul_f32_e32 v230, s17, v112
	v_mul_f32_e32 v231, s17, v113
	v_mul_f32_e32 v232, s17, v102
	v_mul_f32_e32 v233, s17, v103
	v_mul_f32_e32 v234, s17, v104
	v_mul_f32_e32 v235, s17, v105
	v_exp_f32_e32 v228, v228
	v_exp_f32_e32 v229, v229
	v_exp_f32_e32 v230, v230
	v_exp_f32_e32 v231, v231
	v_exp_f32_e32 v232, v232
	v_exp_f32_e32 v233, v233
	v_exp_f32_e32 v234, v234
	v_exp_f32_e32 v235, v235
	v_pk_add_f32 v[228:229], v[228:229], 1.0 op_sel_hi:[1,0] neg_lo:[1,0] neg_hi:[1,0]
	v_pk_add_f32 v[230:231], v[230:231], 1.0 op_sel_hi:[1,0] neg_lo:[1,0] neg_hi:[1,0]
	v_pk_add_f32 v[232:233], v[232:233], 1.0 op_sel_hi:[1,0] neg_lo:[1,0] neg_hi:[1,0]
	v_pk_add_f32 v[234:235], v[234:235], 1.0 op_sel_hi:[1,0] neg_lo:[1,0] neg_hi:[1,0]
	v_cmp_lt_f32_e32 vcc, s13, v110
	s_nop 1
	v_cndmask_b32_e32 v188, v228, v188, vcc
	v_cmp_lt_f32_e32 vcc, s13, v111
	s_nop 1
	v_cndmask_b32_e32 v189, v229, v189, vcc
	v_cmp_lt_f32_e32 vcc, s13, v112
	s_nop 1
	v_cndmask_b32_e32 v190, v230, v190, vcc
	v_cmp_lt_f32_e32 vcc, s13, v113
	s_nop 1
	v_cndmask_b32_e32 v191, v231, v191, vcc
	v_cmp_lt_f32_e32 vcc, s13, v102
	s_nop 1
	v_cndmask_b32_e32 v192, v232, v192, vcc
	v_cmp_lt_f32_e32 vcc, s13, v103
	s_nop 1
	v_cndmask_b32_e32 v193, v233, v193, vcc
	v_cmp_lt_f32_e32 vcc, s13, v104
	s_nop 1
	v_cndmask_b32_e32 v194, v234, v194, vcc
	v_cmp_lt_f32_e32 vcc, s13, v105
	s_nop 1
	v_cndmask_b32_e32 v195, v235, v195, vcc
	v_sqrt_f32_e32 v188, v188
	v_sqrt_f32_e32 v189, v189
	v_sqrt_f32_e32 v190, v190
	v_sqrt_f32_e32 v191, v191
	v_sqrt_f32_e32 v192, v192
	v_sqrt_f32_e32 v193, v193
	v_sqrt_f32_e32 v194, v194
	v_sqrt_f32_e32 v195, v195
	s_waitcnt vmcnt(15)
; __device__ __forceinline__ unsigned cvt_pk_bf16(float lo, float hi) { unsigned r; asm volatile("v_cvt_pk_bf16_f32 %0, %1, %2" : "=v"(r) : "v"(lo), "v"(hi)); return r; }
;     __device__ __forceinline__ void operator()(AccMut acc, const Unit& u, int sw) const {
;     ...
;         for (int ai = 0; ai < 2; ++ai)
; #pragma unroll
;             for (int m = 0; m < 4; ++m) { const size_t off = (size_t)(row0 + ai * HALF + m * 16) * E + c0;
;                 const u32x4 xw = xnext;
;                 if (ai * 4 + m < 7) { const int ai2 = (ai * 4 + m + 1) >> 2, m2 = (ai * 4 + m + 1) & 3; xnext = *(const u32x4*)(XC + (size_t)(row0 + ai2 * HALF + m2 * 16) * E + c0); }
;                 float bt[8];
; #pragma unroll
;                 for (int n = 0; n < 2; ++n)
; #pragma unroll
;                     for (int jp = 0; jp < 2; ++jp) {
;                         const f32x2 z = (f32x2){acc[ai][1][m][n][2 * jp], acc[ai][1][m][n][2 * jp + 1]} * (-1.44269504f);
;                         f32x2 e; e.x = __builtin_amdgcn_exp2f(z.x); e.y = __builtin_amdgcn_exp2f(z.y); e = e + 1.0f;
;                         f32x2 ig; ig.x = __builtin_amdgcn_rcpf(e.x); ig.y = __builtin_amdgcn_rcpf(e.y);
;                         const f32x2 x2 = (f32x2){acc[ai][0][m][n][2 * jp], acc[ai][0][m][n][2 * jp + 1]} * 2.0f;
;                         f32x2 ser = x2 * (1.0f / 120.0f) + (1.0f / 24.0f); ser = ser * x2 + (1.0f / 6.0f); ser = ser * x2 + 0.5f; ser = ser * x2 + 1.0f; ser = ser * (-x2);
;                         f32x2 em = ser;
;                         if (__builtin_expect(__builtin_amdgcn_ballot_w64(x2.x <= -0.25f || x2.y <= -0.25f) != 0ull, 0)) {
;                             em.x = (x2.x > -0.25f) ? ser.x : (1.0f - fexp(x2.x)); em.y = (x2.y > -0.25f) ? ser.y : (1.0f - fexp(x2.y)); }
;                         const unsigned wv = xw[2 * n + jp];
;                         f32x2 sq; sq.x = __builtin_amdgcn_sqrtf(em.x); sq.y = __builtin_amdgcn_sqrtf(em.y);
;                         const f32x2 b2 = sq * ig * (f32x2){bf_lo(wv), bf_hi(wv)};
;                         bt[4 * n + 2 * jp] = b2.x; bt[4 * n + 2 * jp + 1] = b2.y; }
;                 u32x4 w; w.x = cvt_pk_bf16(bt[0], bt[1]); w.y = cvt_pk_bf16(bt[2], bt[3]); w.z = cvt_pk_bf16(bt[4], bt[5]); w.w = cvt_pk_bf16(bt[6], bt[7]);
;                 *(u32x4*)(BT + off) = w; }
	v_lshlrev_b32_e32 v196, 16, v152
	v_and_b32_e32 v197, 0xffff0000, v152
	v_lshlrev_b32_e32 v198, 16, v153
	v_and_b32_e32 v199, 0xffff0000, v153
	v_lshlrev_b32_e32 v200, 16, v154
	v_and_b32_e32 v201, 0xffff0000, v154
	v_lshlrev_b32_e32 v202, 16, v155
	v_and_b32_e32 v203, 0xffff0000, v155
	v_pk_mul_f32 v[188:189], v[188:189], v[180:181]
	v_pk_mul_f32 v[190:191], v[190:191], v[182:183]
	v_pk_mul_f32 v[192:193], v[192:193], v[184:185]
	v_pk_mul_f32 v[194:195], v[194:195], v[186:187]
	v_pk_mul_f32 v[188:189], v[188:189], v[196:197]
	v_pk_mul_f32 v[190:191], v[190:191], v[198:199]
	v_pk_mul_f32 v[192:193], v[192:193], v[200:201]
	v_pk_mul_f32 v[194:195], v[194:195], v[202:203]
	v_cvt_pk_bf16_f32 v208, v188, v189
	v_cvt_pk_bf16_f32 v209, v190, v191
	v_cvt_pk_bf16_f32 v210, v192, v193
	v_cvt_pk_bf16_f32 v211, v194, v195
	global_store_dwordx4 v176, v[208:211], s[10:11]
	v_pk_mul_f32 v[180:181], v[18:19], s[74:75] op_sel_hi:[1,0]
	v_pk_mul_f32 v[182:183], v[20:21], s[74:75] op_sel_hi:[1,0]
	v_pk_mul_f32 v[184:185], v[22:23], s[74:75] op_sel_hi:[1,0]
	v_pk_mul_f32 v[186:187], v[24:25], s[74:75] op_sel_hi:[1,0]
	v_exp_f32_e32 v180, v180
	v_exp_f32_e32 v181, v181
	v_exp_f32_e32 v182, v182
	v_exp_f32_e32 v183, v183
	v_exp_f32_e32 v184, v184
	v_exp_f32_e32 v185, v185
	v_exp_f32_e32 v186, v186
	v_exp_f32_e32 v187, v187
	v_pk_fma_f32 v[188:189], v[98:99], s[26:27], v[236:237] op_sel_hi:[1,0,0]
	v_pk_fma_f32 v[190:191], v[100:101], s[26:27], v[236:237] op_sel_hi:[1,0,0]
	v_pk_fma_f32 v[192:193], v[94:95], s[26:27], v[236:237] op_sel_hi:[1,0,0]
	v_pk_fma_f32 v[194:195], v[96:97], s[26:27], v[236:237] op_sel_hi:[1,0,0]
	v_pk_add_f32 v[180:181], v[180:181], 1.0 op_sel_hi:[1,0]
	v_pk_add_f32 v[182:183], v[182:183], 1.0 op_sel_hi:[1,0]
	v_pk_add_f32 v[184:185], v[184:185], 1.0 op_sel_hi:[1,0]
	v_pk_add_f32 v[186:187], v[186:187], 1.0 op_sel_hi:[1,0]
	v_rcp_f32_e32 v180, v180
	v_rcp_f32_e32 v181, v181
	v_rcp_f32_e32 v182, v182
	v_rcp_f32_e32 v183, v183
	v_rcp_f32_e32 v184, v184
	v_rcp_f32_e32 v185, v185
	v_rcp_f32_e32 v186, v186
	v_rcp_f32_e32 v187, v187
	v_pk_fma_f32 v[188:189], v[98:99], v[188:189], s[22:23] op_sel_hi:[1,1,0]
	v_pk_fma_f32 v[190:191], v[100:101], v[190:191], s[22:23] op_sel_hi:[1,1,0]
	v_pk_fma_f32 v[192:193], v[94:95], v[192:193], s[22:23] op_sel_hi:[1,1,0]
	v_pk_fma_f32 v[194:195], v[96:97], v[194:195], s[22:23] op_sel_hi:[1,1,0]
	v_pk_fma_f32 v[188:189], v[98:99], v[188:189], -2.0 op_sel_hi:[1,1,0]
	v_pk_fma_f32 v[190:191], v[100:101], v[190:191], -2.0 op_sel_hi:[1,1,0]
	v_pk_fma_f32 v[192:193], v[94:95], v[192:193], -2.0 op_sel_hi:[1,1,0]
	v_pk_fma_f32 v[194:195], v[96:97], v[194:195], -2.0 op_sel_hi:[1,1,0]
	v_pk_fma_f32 v[188:189], v[98:99], v[188:189], -2.0 op_sel_hi:[1,1,0]
	v_pk_fma_f32 v[190:191], v[100:101], v[190:191], -2.0 op_sel_hi:[1,1,0]
	v_pk_fma_f32 v[192:193], v[94:95], v[192:193], -2.0 op_sel_hi:[1,1,0]
	v_pk_fma_f32 v[194:195], v[96:97], v[194:195], -2.0 op_sel_hi:[1,1,0]
	v_pk_mul_f32 v[188:189], v[98:99], v[188:189]
	v_pk_mul_f32 v[190:191], v[100:101], v[190:191]
	v_pk_mul_f32 v[192:193], v[94:95], v[192:193]
	v_pk_mul_f32 v[194:195], v[96:97], v[194:195]
	v_mul_f32_e32 v228, s17, v98
	v_mul_f32_e32 v229, s17, v99
	v_mul_f32_e32 v230, s17, v100
	v_mul_f32_e32 v231, s17, v101
	v_mul_f32_e32 v232, s17, v94
	v_mul_f32_e32 v233, s17, v95
	v_mul_f32_e32 v234, s17, v96
	v_mul_f32_e32 v235, s17, v97
	v_exp_f32_e32 v228, v228
	v_exp_f32_e32 v229, v229
	v_exp_f32_e32 v230, v230
	v_exp_f32_e32 v231, v231
	v_exp_f32_e32 v232, v232
	v_exp_f32_e32 v233, v233
	v_exp_f32_e32 v234, v234
	v_exp_f32_e32 v235, v235
	v_pk_add_f32 v[228:229], v[228:229], 1.0 op_sel_hi:[1,0] neg_lo:[1,0] neg_hi:[1,0]
	v_pk_add_f32 v[230:231], v[230:231], 1.0 op_sel_hi:[1,0] neg_lo:[1,0] neg_hi:[1,0]
	v_pk_add_f32 v[232:233], v[232:233], 1.0 op_sel_hi:[1,0] neg_lo:[1,0] neg_hi:[1,0]
	v_pk_add_f32 v[234:235], v[234:235], 1.0 op_sel_hi:[1,0] neg_lo:[1,0] neg_hi:[1,0]
	v_cmp_lt_f32_e32 vcc, s13, v98
	s_nop 1
	v_cndmask_b32_e32 v188, v228, v188, vcc
	v_cmp_lt_f32_e32 vcc, s13, v99
	s_nop 1
	v_cndmask_b32_e32 v189, v229, v189, vcc
	v_cmp_lt_f32_e32 vcc, s13, v100
	s_nop 1
	v_cndmask_b32_e32 v190, v230, v190, vcc
	v_cmp_lt_f32_e32 vcc, s13, v101
	s_nop 1
	v_cndmask_b32_e32 v191, v231, v191, vcc
	v_cmp_lt_f32_e32 vcc, s13, v94
	s_nop 1
	v_cndmask_b32_e32 v192, v232, v192, vcc
	v_cmp_lt_f32_e32 vcc, s13, v95
	s_nop 1
	v_cndmask_b32_e32 v193, v233, v193, vcc
	v_cmp_lt_f32_e32 vcc, s13, v96
	s_nop 1
	v_cndmask_b32_e32 v194, v234, v194, vcc
	v_cmp_lt_f32_e32 vcc, s13, v97
	s_nop 1
	v_cndmask_b32_e32 v195, v235, v195, vcc
	v_sqrt_f32_e32 v188, v188
	v_sqrt_f32_e32 v189, v189
	v_sqrt_f32_e32 v190, v190
	v_sqrt_f32_e32 v191, v191
	v_sqrt_f32_e32 v192, v192
	v_sqrt_f32_e32 v193, v193
	v_sqrt_f32_e32 v194, v194
	v_sqrt_f32_e32 v195, v195
	s_waitcnt vmcnt(15)
; __device__ __forceinline__ unsigned cvt_pk_bf16(float lo, float hi) { unsigned r; asm volatile("v_cvt_pk_bf16_f32 %0, %1, %2" : "=v"(r) : "v"(lo), "v"(hi)); return r; }
;     __device__ __forceinline__ void operator()(AccMut acc, const Unit& u, int sw) const {
;     ...
;         for (int ai = 0; ai < 2; ++ai)
; #pragma unroll
;             for (int m = 0; m < 4; ++m) { const size_t off = (size_t)(row0 + ai * HALF + m * 16) * E + c0;
;                 const u32x4 xw = xnext;
;                 if (ai * 4 + m < 7) { const int ai2 = (ai * 4 + m + 1) >> 2, m2 = (ai * 4 + m + 1) & 3; xnext = *(const u32x4*)(XC + (size_t)(row0 + ai2 * HALF + m2 * 16) * E + c0); }
;                 float bt[8];
; #pragma unroll
;                 for (int n = 0; n < 2; ++n)
; #pragma unroll
;                     for (int jp = 0; jp < 2; ++jp) {
;                         const f32x2 z = (f32x2){acc[ai][1][m][n][2 * jp], acc[ai][1][m][n][2 * jp + 1]} * (-1.44269504f);
;                         f32x2 e; e.x = __builtin_amdgcn_exp2f(z.x); e.y = __builtin_amdgcn_exp2f(z.y); e = e + 1.0f;
;                         f32x2 ig; ig.x = __builtin_amdgcn_rcpf(e.x); ig.y = __builtin_amdgcn_rcpf(e.y);
;                         const f32x2 x2 = (f32x2){acc[ai][0][m][n][2 * jp], acc[ai][0][m][n][2 * jp + 1]} * 2.0f;
;                         f32x2 ser = x2 * (1.0f / 120.0f) + (1.0f / 24.0f); ser = ser * x2 + (1.0f / 6.0f); ser = ser * x2 + 0.5f; ser = ser * x2 + 1.0f; ser = ser * (-x2);
;                         f32x2 em = ser;
;                         if (__builtin_expect(__builtin_amdgcn_ballot_w64(x2.x <= -0.25f || x2.y <= -0.25f) != 0ull, 0)) {
;                             em.x = (x2.x > -0.25f) ? ser.x : (1.0f - fexp(x2.x)); em.y = (x2.y > -0.25f) ? ser.y : (1.0f - fexp(x2.y)); }
;                         const unsigned wv = xw[2 * n + jp];
;                         f32x2 sq; sq.x = __builtin_amdgcn_sqrtf(em.x); sq.y = __builtin_amdgcn_sqrtf(em.y);
;                         const f32x2 b2 = sq * ig * (f32x2){bf_lo(wv), bf_hi(wv)};
;                         bt[4 * n + 2 * jp] = b2.x; bt[4 * n + 2 * jp + 1] = b2.y; }
;                 u32x4 w; w.x = cvt_pk_bf16(bt[0], bt[1]); w.y = cvt_pk_bf16(bt[2], bt[3]); w.z = cvt_pk_bf16(bt[4], bt[5]); w.w = cvt_pk_bf16(bt[6], bt[7]);
;                 *(u32x4*)(BT + off) = w; }
	v_lshlrev_b32_e32 v196, 16, v156
	v_and_b32_e32 v197, 0xffff0000, v156
	v_lshlrev_b32_e32 v198, 16, v157
	v_and_b32_e32 v199, 0xffff0000, v157
	v_lshlrev_b32_e32 v200, 16, v158
	v_and_b32_e32 v201, 0xffff0000, v158
	v_lshlrev_b32_e32 v202, 16, v159
	v_and_b32_e32 v203, 0xffff0000, v159
	v_pk_mul_f32 v[188:189], v[188:189], v[180:181]
	v_pk_mul_f32 v[190:191], v[190:191], v[182:183]
	v_pk_mul_f32 v[192:193], v[192:193], v[184:185]
	v_pk_mul_f32 v[194:195], v[194:195], v[186:187]
	v_pk_mul_f32 v[188:189], v[188:189], v[196:197]
	v_pk_mul_f32 v[190:191], v[190:191], v[198:199]
	v_pk_mul_f32 v[192:193], v[192:193], v[200:201]
	v_pk_mul_f32 v[194:195], v[194:195], v[202:203]
	v_cvt_pk_bf16_f32 v212, v188, v189
	v_cvt_pk_bf16_f32 v213, v190, v191
	v_cvt_pk_bf16_f32 v214, v192, v193
	v_cvt_pk_bf16_f32 v215, v194, v195
	global_store_dwordx4 v177, v[212:215], s[10:11]
	v_pk_mul_f32 v[180:181], v[10:11], s[74:75] op_sel_hi:[1,0]
	v_pk_mul_f32 v[182:183], v[12:13], s[74:75] op_sel_hi:[1,0]
	v_pk_mul_f32 v[184:185], v[14:15], s[74:75] op_sel_hi:[1,0]
	v_pk_mul_f32 v[186:187], v[16:17], s[74:75] op_sel_hi:[1,0]
	v_exp_f32_e32 v180, v180
	v_exp_f32_e32 v181, v181
	v_exp_f32_e32 v182, v182
	v_exp_f32_e32 v183, v183
	v_exp_f32_e32 v184, v184
	v_exp_f32_e32 v185, v185
	v_exp_f32_e32 v186, v186
	v_exp_f32_e32 v187, v187
	v_pk_fma_f32 v[188:189], v[90:91], s[26:27], v[236:237] op_sel_hi:[1,0,0]
	v_pk_fma_f32 v[190:191], v[92:93], s[26:27], v[236:237] op_sel_hi:[1,0,0]
	v_pk_fma_f32 v[192:193], v[86:87], s[26:27], v[236:237] op_sel_hi:[1,0,0]
	v_pk_fma_f32 v[194:195], v[88:89], s[26:27], v[236:237] op_sel_hi:[1,0,0]
	v_pk_add_f32 v[180:181], v[180:181], 1.0 op_sel_hi:[1,0]
	v_pk_add_f32 v[182:183], v[182:183], 1.0 op_sel_hi:[1,0]
	v_pk_add_f32 v[184:185], v[184:185], 1.0 op_sel_hi:[1,0]
	v_pk_add_f32 v[186:187], v[186:187], 1.0 op_sel_hi:[1,0]
	v_rcp_f32_e32 v180, v180
	v_rcp_f32_e32 v181, v181
	v_rcp_f32_e32 v182, v182
	v_rcp_f32_e32 v183, v183
	v_rcp_f32_e32 v184, v184
	v_rcp_f32_e32 v185, v185
	v_rcp_f32_e32 v186, v186
	v_rcp_f32_e32 v187, v187
	v_pk_fma_f32 v[188:189], v[90:91], v[188:189], s[22:23] op_sel_hi:[1,1,0]
	v_pk_fma_f32 v[190:191], v[92:93], v[190:191], s[22:23] op_sel_hi:[1,1,0]
	v_pk_fma_f32 v[192:193], v[86:87], v[192:193], s[22:23] op_sel_hi:[1,1,0]
	v_pk_fma_f32 v[194:195], v[88:89], v[194:195], s[22:23] op_sel_hi:[1,1,0]
	v_pk_fma_f32 v[188:189], v[90:91], v[188:189], -2.0 op_sel_hi:[1,1,0]
	v_pk_fma_f32 v[190:191], v[92:93], v[190:191], -2.0 op_sel_hi:[1,1,0]
	v_pk_fma_f32 v[192:193], v[86:87], v[192:193], -2.0 op_sel_hi:[1,1,0]
	v_pk_fma_f32 v[194:195], v[88:89], v[194:195], -2.0 op_sel_hi:[1,1,0]
	v_pk_fma_f32 v[188:189], v[90:91], v[188:189], -2.0 op_sel_hi:[1,1,0]
	v_pk_fma_f32 v[190:191], v[92:93], v[190:191], -2.0 op_sel_hi:[1,1,0]
	v_pk_fma_f32 v[192:193], v[86:87], v[192:193], -2.0 op_sel_hi:[1,1,0]
	v_pk_fma_f32 v[194:195], v[88:89], v[194:195], -2.0 op_sel_hi:[1,1,0]
	v_pk_mul_f32 v[188:189], v[90:91], v[188:189]
	v_pk_mul_f32 v[190:191], v[92:93], v[190:191]
	v_pk_mul_f32 v[192:193], v[86:87], v[192:193]
	v_pk_mul_f32 v[194:195], v[88:89], v[194:195]
	v_mul_f32_e32 v228, s17, v90
	v_mul_f32_e32 v229, s17, v91
	v_mul_f32_e32 v230, s17, v92
	v_mul_f32_e32 v231, s17, v93
	v_mul_f32_e32 v232, s17, v86
	v_mul_f32_e32 v233, s17, v87
	v_mul_f32_e32 v234, s17, v88
	v_mul_f32_e32 v235, s17, v89
	v_exp_f32_e32 v228, v228
	v_exp_f32_e32 v229, v229
	v_exp_f32_e32 v230, v230
	v_exp_f32_e32 v231, v231
	v_exp_f32_e32 v232, v232
	v_exp_f32_e32 v233, v233
	v_exp_f32_e32 v234, v234
	v_exp_f32_e32 v235, v235
	v_pk_add_f32 v[228:229], v[228:229], 1.0 op_sel_hi:[1,0] neg_lo:[1,0] neg_hi:[1,0]
	v_pk_add_f32 v[230:231], v[230:231], 1.0 op_sel_hi:[1,0] neg_lo:[1,0] neg_hi:[1,0]
	v_pk_add_f32 v[232:233], v[232:233], 1.0 op_sel_hi:[1,0] neg_lo:[1,0] neg_hi:[1,0]
	v_pk_add_f32 v[234:235], v[234:235], 1.0 op_sel_hi:[1,0] neg_lo:[1,0] neg_hi:[1,0]
	v_cmp_lt_f32_e32 vcc, s13, v90
	s_nop 1
	v_cndmask_b32_e32 v188, v228, v188, vcc
	v_cmp_lt_f32_e32 vcc, s13, v91
	s_nop 1
	v_cndmask_b32_e32 v189, v229, v189, vcc
	v_cmp_lt_f32_e32 vcc, s13, v92
	s_nop 1
	v_cndmask_b32_e32 v190, v230, v190, vcc
	v_cmp_lt_f32_e32 vcc, s13, v93
	s_nop 1
	v_cndmask_b32_e32 v191, v231, v191, vcc
	v_cmp_lt_f32_e32 vcc, s13, v86
	s_nop 1
	v_cndmask_b32_e32 v192, v232, v192, vcc
	v_cmp_lt_f32_e32 vcc, s13, v87
	s_nop 1
	v_cndmask_b32_e32 v193, v233, v193, vcc
	v_cmp_lt_f32_e32 vcc, s13, v88
	s_nop 1
	v_cndmask_b32_e32 v194, v234, v194, vcc
	v_cmp_lt_f32_e32 vcc, s13, v89
	s_nop 1
	v_cndmask_b32_e32 v195, v235, v195, vcc
	v_sqrt_f32_e32 v188, v188
	v_sqrt_f32_e32 v189, v189
	v_sqrt_f32_e32 v190, v190
	v_sqrt_f32_e32 v191, v191
	v_sqrt_f32_e32 v192, v192
	v_sqrt_f32_e32 v193, v193
	v_sqrt_f32_e32 v194, v194
	v_sqrt_f32_e32 v195, v195
	s_waitcnt vmcnt(15)
; __device__ __forceinline__ unsigned cvt_pk_bf16(float lo, float hi) { unsigned r; asm volatile("v_cvt_pk_bf16_f32 %0, %1, %2" : "=v"(r) : "v"(lo), "v"(hi)); return r; }
;     __device__ __forceinline__ void operator()(AccMut acc, const Unit& u, int sw) const {
;     ...
;         for (int ai = 0; ai < 2; ++ai)
; #pragma unroll
;             for (int m = 0; m < 4; ++m) { const size_t off = (size_t)(row0 + ai * HALF + m * 16) * E + c0;
;                 const u32x4 xw = xnext;
;                 if (ai * 4 + m < 7) { const int ai2 = (ai * 4 + m + 1) >> 2, m2 = (ai * 4 + m + 1) & 3; xnext = *(const u32x4*)(XC + (size_t)(row0 + ai2 * HALF + m2 * 16) * E + c0); }
;                 float bt[8];
; #pragma unroll
;                 for (int n = 0; n < 2; ++n)
; #pragma unroll
;                     for (int jp = 0; jp < 2; ++jp) {
;                         const f32x2 z = (f32x2){acc[ai][1][m][n][2 * jp], acc[ai][1][m][n][2 * jp + 1]} * (-1.44269504f);
;                         f32x2 e; e.x = __builtin_amdgcn_exp2f(z.x); e.y = __builtin_amdgcn_exp2f(z.y); e = e + 1.0f;
;                         f32x2 ig; ig.x = __builtin_amdgcn_rcpf(e.x); ig.y = __builtin_amdgcn_rcpf(e.y);
;                         const f32x2 x2 = (f32x2){acc[ai][0][m][n][2 * jp], acc[ai][0][m][n][2 * jp + 1]} * 2.0f;
;                         f32x2 ser = x2 * (1.0f / 120.0f) + (1.0f / 24.0f); ser = ser * x2 + (1.0f / 6.0f); ser = ser * x2 + 0.5f; ser = ser * x2 + 1.0f; ser = ser * (-x2);
;                         f32x2 em = ser;
;                         if (__builtin_expect(__builtin_amdgcn_ballot_w64(x2.x <= -0.25f || x2.y <= -0.25f) != 0ull, 0)) {
;                             em.x = (x2.x > -0.25f) ? ser.x : (1.0f - fexp(x2.x)); em.y = (x2.y > -0.25f) ? ser.y : (1.0f - fexp(x2.y)); }
;                         const unsigned wv = xw[2 * n + jp];
;                         f32x2 sq; sq.x = __builtin_amdgcn_sqrtf(em.x); sq.y = __builtin_amdgcn_sqrtf(em.y);
;                         const f32x2 b2 = sq * ig * (f32x2){bf_lo(wv), bf_hi(wv)};
;                         bt[4 * n + 2 * jp] = b2.x; bt[4 * n + 2 * jp + 1] = b2.y; }
;                 u32x4 w; w.x = cvt_pk_bf16(bt[0], bt[1]); w.y = cvt_pk_bf16(bt[2], bt[3]); w.z = cvt_pk_bf16(bt[4], bt[5]); w.w = cvt_pk_bf16(bt[6], bt[7]);
;                 *(u32x4*)(BT + off) = w; }
	v_lshlrev_b32_e32 v196, 16, v160
	v_and_b32_e32 v197, 0xffff0000, v160
	v_lshlrev_b32_e32 v198, 16, v161
	v_and_b32_e32 v199, 0xffff0000, v161
	v_lshlrev_b32_e32 v200, 16, v162
	v_and_b32_e32 v201, 0xffff0000, v162
	v_lshlrev_b32_e32 v202, 16, v163
	v_and_b32_e32 v203, 0xffff0000, v163
	v_pk_mul_f32 v[188:189], v[188:189], v[180:181]
	v_pk_mul_f32 v[190:191], v[190:191], v[182:183]
	v_pk_mul_f32 v[192:193], v[192:193], v[184:185]
	v_pk_mul_f32 v[194:195], v[194:195], v[186:187]
	v_pk_mul_f32 v[188:189], v[188:189], v[196:197]
	v_pk_mul_f32 v[190:191], v[190:191], v[198:199]
	v_pk_mul_f32 v[192:193], v[192:193], v[200:201]
	v_pk_mul_f32 v[194:195], v[194:195], v[202:203]
	v_cvt_pk_bf16_f32 v208, v188, v189
	v_cvt_pk_bf16_f32 v209, v190, v191
	v_cvt_pk_bf16_f32 v210, v192, v193
	v_cvt_pk_bf16_f32 v211, v194, v195
	global_store_dwordx4 v178, v[208:211], s[10:11]
	v_pk_mul_f32 v[180:181], v[2:3], s[74:75] op_sel_hi:[1,0]
	v_pk_mul_f32 v[182:183], v[4:5], s[74:75] op_sel_hi:[1,0]
	v_pk_mul_f32 v[184:185], v[6:7], s[74:75] op_sel_hi:[1,0]
	v_pk_mul_f32 v[186:187], v[8:9], s[74:75] op_sel_hi:[1,0]
	v_exp_f32_e32 v180, v180
	v_exp_f32_e32 v181, v181
	v_exp_f32_e32 v182, v182
	v_exp_f32_e32 v183, v183
	v_exp_f32_e32 v184, v184
	v_exp_f32_e32 v185, v185
	v_exp_f32_e32 v186, v186
	v_exp_f32_e32 v187, v187
	v_pk_fma_f32 v[188:189], v[74:75], s[26:27], v[236:237] op_sel_hi:[1,0,0]
	v_pk_fma_f32 v[190:191], v[76:77], s[26:27], v[236:237] op_sel_hi:[1,0,0]
	v_pk_fma_f32 v[192:193], v[70:71], s[26:27], v[236:237] op_sel_hi:[1,0,0]
	v_pk_fma_f32 v[194:195], v[72:73], s[26:27], v[236:237] op_sel_hi:[1,0,0]
	v_pk_add_f32 v[180:181], v[180:181], 1.0 op_sel_hi:[1,0]
	v_pk_add_f32 v[182:183], v[182:183], 1.0 op_sel_hi:[1,0]
	v_pk_add_f32 v[184:185], v[184:185], 1.0 op_sel_hi:[1,0]
	v_pk_add_f32 v[186:187], v[186:187], 1.0 op_sel_hi:[1,0]
	v_rcp_f32_e32 v180, v180
	v_rcp_f32_e32 v181, v181
	v_rcp_f32_e32 v182, v182
	v_rcp_f32_e32 v183, v183
	v_rcp_f32_e32 v184, v184
	v_rcp_f32_e32 v185, v185
	v_rcp_f32_e32 v186, v186
	v_rcp_f32_e32 v187, v187
	v_pk_fma_f32 v[188:189], v[74:75], v[188:189], s[22:23] op_sel_hi:[1,1,0]
	v_pk_fma_f32 v[190:191], v[76:77], v[190:191], s[22:23] op_sel_hi:[1,1,0]
	v_pk_fma_f32 v[192:193], v[70:71], v[192:193], s[22:23] op_sel_hi:[1,1,0]
	v_pk_fma_f32 v[194:195], v[72:73], v[194:195], s[22:23] op_sel_hi:[1,1,0]
	v_pk_fma_f32 v[188:189], v[74:75], v[188:189], -2.0 op_sel_hi:[1,1,0]
	v_pk_fma_f32 v[190:191], v[76:77], v[190:191], -2.0 op_sel_hi:[1,1,0]
	v_pk_fma_f32 v[192:193], v[70:71], v[192:193], -2.0 op_sel_hi:[1,1,0]
	v_pk_fma_f32 v[194:195], v[72:73], v[194:195], -2.0 op_sel_hi:[1,1,0]
	v_pk_fma_f32 v[188:189], v[74:75], v[188:189], -2.0 op_sel_hi:[1,1,0]
	v_pk_fma_f32 v[190:191], v[76:77], v[190:191], -2.0 op_sel_hi:[1,1,0]
	v_pk_fma_f32 v[192:193], v[70:71], v[192:193], -2.0 op_sel_hi:[1,1,0]
	v_pk_fma_f32 v[194:195], v[72:73], v[194:195], -2.0 op_sel_hi:[1,1,0]
	v_pk_mul_f32 v[188:189], v[74:75], v[188:189]
	v_pk_mul_f32 v[190:191], v[76:77], v[190:191]
	v_pk_mul_f32 v[192:193], v[70:71], v[192:193]
	v_pk_mul_f32 v[194:195], v[72:73], v[194:195]
	v_mul_f32_e32 v228, s17, v74
	v_mul_f32_e32 v229, s17, v75
	v_mul_f32_e32 v230, s17, v76
	v_mul_f32_e32 v231, s17, v77
	v_mul_f32_e32 v232, s17, v70
	v_mul_f32_e32 v233, s17, v71
	v_mul_f32_e32 v234, s17, v72
	v_mul_f32_e32 v235, s17, v73
	v_exp_f32_e32 v228, v228
	v_exp_f32_e32 v229, v229
	v_exp_f32_e32 v230, v230
	v_exp_f32_e32 v231, v231
	v_exp_f32_e32 v232, v232
	v_exp_f32_e32 v233, v233
	v_exp_f32_e32 v234, v234
	v_exp_f32_e32 v235, v235
	v_pk_add_f32 v[228:229], v[228:229], 1.0 op_sel_hi:[1,0] neg_lo:[1,0] neg_hi:[1,0]
	v_pk_add_f32 v[230:231], v[230:231], 1.0 op_sel_hi:[1,0] neg_lo:[1,0] neg_hi:[1,0]
	v_pk_add_f32 v[232:233], v[232:233], 1.0 op_sel_hi:[1,0] neg_lo:[1,0] neg_hi:[1,0]
	v_pk_add_f32 v[234:235], v[234:235], 1.0 op_sel_hi:[1,0] neg_lo:[1,0] neg_hi:[1,0]
	v_cmp_lt_f32_e32 vcc, s13, v74
	s_nop 1
	v_cndmask_b32_e32 v188, v228, v188, vcc
	v_cmp_lt_f32_e32 vcc, s13, v75
	s_nop 1
	v_cndmask_b32_e32 v189, v229, v189, vcc
	v_cmp_lt_f32_e32 vcc, s13, v76
	s_nop 1
	v_cndmask_b32_e32 v190, v230, v190, vcc
	v_cmp_lt_f32_e32 vcc, s13, v77
	s_nop 1
	v_cndmask_b32_e32 v191, v231, v191, vcc
	v_cmp_lt_f32_e32 vcc, s13, v70
	s_nop 1
	v_cndmask_b32_e32 v192, v232, v192, vcc
	v_cmp_lt_f32_e32 vcc, s13, v71
	s_nop 1
	v_cndmask_b32_e32 v193, v233, v193, vcc
	v_cmp_lt_f32_e32 vcc, s13, v72
	s_nop 1
	v_cndmask_b32_e32 v194, v234, v194, vcc
	v_cmp_lt_f32_e32 vcc, s13, v73
	s_nop 1
	v_cndmask_b32_e32 v195, v235, v195, vcc
	v_sqrt_f32_e32 v188, v188
	v_sqrt_f32_e32 v189, v189
	v_sqrt_f32_e32 v190, v190
	v_sqrt_f32_e32 v191, v191
	v_sqrt_f32_e32 v192, v192
	v_sqrt_f32_e32 v193, v193
	v_sqrt_f32_e32 v194, v194
	v_sqrt_f32_e32 v195, v195
	s_waitcnt vmcnt(15)
	v_lshlrev_b32_e32 v196, 16, v164
	v_and_b32_e32 v197, 0xffff0000, v164
	v_lshlrev_b32_e32 v198, 16, v165
	v_and_b32_e32 v199, 0xffff0000, v165
	v_lshlrev_b32_e32 v200, 16, v166
	v_and_b32_e32 v201, 0xffff0000, v166
	v_lshlrev_b32_e32 v202, 16, v167
	v_and_b32_e32 v203, 0xffff0000, v167
	v_pk_mul_f32 v[188:189], v[188:189], v[180:181]
	v_pk_mul_f32 v[190:191], v[190:191], v[182:183]
	v_pk_mul_f32 v[192:193], v[192:193], v[184:185]
	v_pk_mul_f32 v[194:195], v[194:195], v[186:187]
	v_pk_mul_f32 v[188:189], v[188:189], v[196:197]
	v_pk_mul_f32 v[190:191], v[190:191], v[198:199]
	v_pk_mul_f32 v[192:193], v[192:193], v[200:201]
	v_pk_mul_f32 v[194:195], v[194:195], v[202:203]
	v_cvt_pk_bf16_f32 v212, v188, v189
	v_cvt_pk_bf16_f32 v213, v190, v191
	v_cvt_pk_bf16_f32 v214, v192, v193
	v_cvt_pk_bf16_f32 v215, v194, v195
	global_store_dwordx4 v179, v[212:215], s[10:11]
	s_branch .Lgate_epi_done
